# stack on v8: ssq row-stat prefetch one unit ahead (Q-up, KV-up), attention z-block DMA deferred into first tile iteration, relaxed first two vmcnt waits after epilogues (flag-guarded)
# speedup vs baseline: 1.0206x; 1.0016x over previous
; #define PG8_STAGE(bufoff, gbase, voff) do { _Pragma("unroll") for (int _i = 0; _i < 2; ++_i) \
;         __builtin_amdgcn_global_load_lds((const unsigned*)((const char*)(gbase) + (voff)[_i]), (PG8_LAS unsigned*)(lds + (bufoff) + ldsw + _i * 8192), 16, 0, 0); } while (0)
; #define PG8_WAIT_V(n) asm volatile("s_waitcnt vmcnt(" #n ")" ::: "memory")
; #define PG8_BAR __builtin_amdgcn_s_barrier()
; template <class Epi, class Sched, bool ALIGN_EPI = false, bool SP2 = false>
; __device__ __forceinline__ void gemm_phase(PG8_LAS unsigned char* lds, const Gemm g, const Sched& S, const Epi& E) {
;     ...
;         PG8_STAGE(PG8_SB(1, 0), cB + kstep, voffB); PG8_STAGE(PG8_SA(1, 0), cA + kstep, voffA); PG8_STAGE(PG8_SB(1, 1), cB + hstep + kstep, voffB);
;         PG8_WAIT_V(6); PG8_BAR;
.LBB0_345:
	s_mov_b64 s[20:21], 0x80
	s_add_i32 m0, s59, 0x18000
	v_lshl_add_u64 v[8:9], v[8:9], 0, s[20:21]
	s_waitcnt vmcnt(2)
	s_barrier
	global_load_lds_dwordx4 v[8:9], off
	v_lshl_add_u64 v[4:5], v[4:5], 0, s[20:21]
	s_add_i32 m0, s59, 0x1a000
	s_add_i32 s63, s59, 0x8000
	global_load_lds_dwordx4 v[4:5], off
	v_lshl_add_u64 v[4:5], v[6:7], 0, s[20:21]
	s_mov_b32 m0, s63
	s_add_i32 s64, s59, 0xa000
	global_load_lds_dwordx4 v[4:5], off
	v_lshl_add_u64 v[4:5], v[10:11], 0, s[20:21]
	s_mov_b32 m0, s64
	v_lshl_add_u64 v[2:3], v[2:3], 0, s[20:21]
	global_load_lds_dwordx4 v[4:5], off
	s_add_i32 m0, s59, 0x1c000
	v_lshl_add_u64 v[0:1], v[0:1], 0, s[20:21]
	global_load_lds_dwordx4 v[2:3], off
	s_add_i32 m0, s59, 0x1e000
	s_lshr_b32 s1, s1, 26
	global_load_lds_dwordx4 v[0:1], off
	s_and_b32 s2, s2, 3
	s_add_i32 s1, s0, s1
	s_ashr_i32 s65, s1, 6
	s_lshl_b32 s66, s3, 6
	s_lshl_b32 s1, s3, 13
	s_lshl_b32 s67, s2, 5
	s_cmp_gt_i32 s0, 63
	s_cselect_b64 s[22:23], -1, 0
	s_add_i32 s68, s65, -2
	s_cmpk_lt_u32 s11, 0x100
	s_cselect_b64 s[24:25], -1, 0
	s_add_u32 s69, s90, 0x9000000
	s_addc_u32 s70, s91, 0
	s_add_u32 s26, s90, 0x2600000
	s_addc_u32 s27, s91, 0
	s_add_u32 s28, s90, 0x3e00000
	s_addc_u32 s29, s91, 0
	s_add_u32 s30, s90, 0x2200000
	s_addc_u32 s31, s91, 0
	v_lshlrev_b32_e32 v1, 2, v201
	s_add_u32 s71, s88, 0x4000000
	v_lshl_or_b32 v0, v201, 6, v238
	v_and_b32_e32 v1, 32, v1
	s_addc_u32 s72, s89, 0
	v_bitop3_b32 v0, v0, s1, v1 bitop3:0xde
	s_add_u32 s34, s90, 0x20000
	v_add_u32_e32 v1, v237, v235
	s_addc_u32 s35, s91, 0
	v_mul_lo_u32 v1, s0, v1
	s_add_u32 s36, s90, 0x100000
	v_lshlrev_b32_e32 v1, 1, v1
	s_addc_u32 s37, s91, 0
	v_add3_u32 v136, v233, v1, v234
	v_add_u32_e32 v1, v236, v235
	s_cmp_gt_u32 s2, 1
	v_mul_lo_u32 v1, s0, v1
	s_waitcnt vmcnt(6)
	s_cselect_b64 s[38:39], -1, 0
	s_cmp_eq_u32 s2, 2
	v_lshlrev_b32_e32 v1, 1, v1
	v_lshl_or_b32 v170, s2, 12, v239
	s_cselect_b64 s[40:41], -1, 0
	v_lshl_add_u64 v[138:139], s[12:13], 0, v[136:137]
	v_add3_u32 v136, v233, v1, v234
	s_add_i32 s75, 0, 0x10000
	s_add_i32 s76, 0, 0x14000
	v_add_u32_e32 v173, 0, v0
	v_mbcnt_lo_u32_b32 v0, -1, 0
	s_ashr_i32 s73, s83, 31
	s_mov_b32 s86, s80
	s_ashr_i32 s74, s80, 31
	v_lshl_add_u64 v[140:141], s[12:13], 0, v[136:137]
	v_mov_b64_e32 v[142:143], 0xb80
	v_mov_b64_e32 v[144:145], 0xb7f
	v_add_u32_e32 v171, s75, v170
	v_add_u32_e32 v172, s76, v170
	s_movk_i32 s77, 0x300
	s_mov_b64 s[42:43], 0xcffe200
	s_mov_b32 s78, 0xcffe000
	v_mbcnt_hi_u32_b32 v174, -1, v0
	s_mov_b32 s79, 0
	s_barrier
	s_mov_b32 s99, 0
	s_branch .LBB0_348

; #define PG8_STAGE(bufoff, gbase, voff) do { _Pragma("unroll") for (int _i = 0; _i < 2; ++_i) \
;         __builtin_amdgcn_global_load_lds((const unsigned*)((const char*)(gbase) + (voff)[_i]), (PG8_LAS unsigned*)(lds + (bufoff) + ldsw + _i * 8192), 16, 0, 0); } while (0)
; #define PG8_LDA(dst, b, h) do { _Pragma("unroll") for (int m = 0; m < 4; ++m) _Pragma("unroll") for (int k = 0; k < 2; ++k) dst[m][k] = *(const PG8_LAS bf16x8*)(lds + PG8_SA(b, h) + aoff + m * 2048 + k * 1024); } while (0)
; #define PG8_LDB(dst, b, h) do { _Pragma("unroll") for (int n = 0; n < 2; ++n) _Pragma("unroll") for (int k = 0; k < 2; ++k) dst[n][k] = *(const PG8_LAS bf16x8*)(lds + PG8_SB(b, h) + boff + n * 2048 + k * 1024); } while (0)
; #define PG8_MMA(ai, bj, At, Bt) do { __builtin_amdgcn_s_setprio(1); _Pragma("unroll") for (int m = 0; m < 4; ++m) _Pragma("unroll") for (int n = 0; n < 2; ++n) _Pragma("unroll") for (int k = 0; k < 2; ++k) \
;         acc[ai][bj][m][n] = __builtin_amdgcn_mfma_f32_16x16x32_bf16(Bt[n][k], At[m][k], acc[ai][bj][m][n], 0, 0, 0); __builtin_amdgcn_s_setprio(0); } while (0)
; #define PG8_WAIT_V(n) asm volatile("s_waitcnt vmcnt(" #n ")" ::: "memory")
; #define PG8_WAIT_L(n) asm volatile("s_waitcnt lgkmcnt(" #n ")" ::: "memory")
; #define PG8_BAR __builtin_amdgcn_s_barrier()
; #define PG8_SCHED __builtin_amdgcn_sched_barrier(0)
; template <class Epi, class Sched, bool ALIGN_EPI = false, bool SP2 = false>
; __device__ __forceinline__ void gemm_phase(PG8_LAS unsigned char* lds, const Gemm g, const Sched& S, const Epi& E) {
;     ...
;             PG8_LDB(B0, 0, 0); PG8_LDB(B1, 0, 1); PG8_SCHED; PG8_LDA(At, 0, 0); PG8_STAGE(PG8_SA(1, 1), a1 + hstep, voffA);
;             PG8_WAIT_V(8); PG8_WAIT_L(0); PG8_BAR; PG8_MMA(0, 0, At, B0); PG8_MMA(0, 1, At, B1); PG8_BAR; PG8_SCHED;
.LBB0_354:
	s_andn2_b64 vcc, exec, s[22:23]
	s_waitcnt lgkmcnt(0)
	s_cbranch_vccnz .LBB0_357
	s_add_u32 s4, s4, 0x80
	s_addc_u32 s5, s5, 0
	s_add_u32 s11, s6, 0x100
	s_addc_u32 s16, s7, 0
	s_mov_b32 s6, 0
	ds_read_b128 v[146:149], v171
	ds_read_b128 v[150:153], v171 offset:1024
	ds_read_b128 v[154:157], v171 offset:2048
	ds_read_b128 v[158:161], v171 offset:3072
	ds_read_b128 v[162:165], v172
	ds_read_b128 v[166:169], v172 offset:1024
	ds_read_b128 v[176:179], v172 offset:2048
	ds_read_b128 v[180:183], v172 offset:3072
	s_add_i32 s46, s6, 2
	s_add_u32 s47, s4, 0x80
	s_addc_u32 s7, s5, 0
	s_cmp_eq_u32 s68, s6
	s_cselect_b32 s6, s0, s47
	s_cselect_b32 s7, s1, s7
	s_cselect_b32 s49, s45, s16
	s_cselect_b32 s48, s44, s11
	v_lshl_add_u64 v[218:219], s[4:5], 0, v[138:139]
	s_add_i32 m0, s59, 0xc000
	ds_read_b128 v[184:187], v173
	ds_read_b128 v[188:191], v173 offset:1024
	ds_read_b128 v[192:195], v173 offset:2048
	ds_read_b128 v[196:199], v173 offset:3072
	ds_read_b128 v[202:205], v173 offset:4096
	ds_read_b128 v[206:209], v173 offset:5120
	ds_read_b128 v[210:213], v173 offset:6144
	ds_read_b128 v[214:217], v173 offset:7168
	global_load_lds_dwordx4 v[218:219], off
	v_lshl_add_u64 v[218:219], s[4:5], 0, v[140:141]
	s_add_i32 m0, s59, 0xe000
	s_nop 0
	global_load_lds_dwordx4 v[218:219], off
	s_cmp_eq_u32 s99, 0
	s_cbranch_scc1 .Lw8_0_0
	s_waitcnt vmcnt(16)
	s_branch .Lwj_0_0

; #define PG8_STAGE(bufoff, gbase, voff) do { _Pragma("unroll") for (int _i = 0; _i < 2; ++_i) \
;         __builtin_amdgcn_global_load_lds((const unsigned*)((const char*)(gbase) + (voff)[_i]), (PG8_LAS unsigned*)(lds + (bufoff) + ldsw + _i * 8192), 16, 0, 0); } while (0)
; #define PG8_LDA(dst, b, h) do { _Pragma("unroll") for (int m = 0; m < 4; ++m) _Pragma("unroll") for (int k = 0; k < 2; ++k) dst[m][k] = *(const PG8_LAS bf16x8*)(lds + PG8_SA(b, h) + aoff + m * 2048 + k * 1024); } while (0)
; #define PG8_MMA(ai, bj, At, Bt) do { __builtin_amdgcn_s_setprio(1); _Pragma("unroll") for (int m = 0; m < 4; ++m) _Pragma("unroll") for (int n = 0; n < 2; ++n) _Pragma("unroll") for (int k = 0; k < 2; ++k) \
;         acc[ai][bj][m][n] = __builtin_amdgcn_mfma_f32_16x16x32_bf16(Bt[n][k], At[m][k], acc[ai][bj][m][n], 0, 0, 0); __builtin_amdgcn_s_setprio(0); } while (0)
; #define PG8_WAIT_V(n) asm volatile("s_waitcnt vmcnt(" #n ")" ::: "memory")
; #define PG8_WAIT_L(n) asm volatile("s_waitcnt lgkmcnt(" #n ")" ::: "memory")
; #define PG8_BAR __builtin_amdgcn_s_barrier()
; #define PG8_SCHED __builtin_amdgcn_sched_barrier(0)
; template <class Epi, class Sched, bool ALIGN_EPI = false, bool SP2 = false>
; __device__ __forceinline__ void gemm_phase(PG8_LAS unsigned char* lds, const Gemm g, const Sched& S, const Epi& E) {
;     ...
;             PG8_WAIT_V(8); PG8_WAIT_L(0); PG8_BAR; PG8_MMA(0, 0, At, B0); PG8_MMA(0, 1, At, B1); PG8_BAR; PG8_SCHED;
;             PG8_LDA(At, 0, 1); PG8_STAGE(PG8_SB(0, 0), b2, voffB); PG8_STAGE(PG8_SB(0, 1), b2 + hstep, voffB); PG8_STAGE(PG8_SA(0, 0), a2, voffA);
;             PG8_WAIT_V(8); PG8_WAIT_L(0); PG8_BAR; PG8_MMA(1, 0, At, B0); PG8_MMA(1, 1, At, B1); PG8_BAR; PG8_SCHED;
.Lwj_0_0:
	s_waitcnt lgkmcnt(0)
	s_barrier
	s_setprio 1
	s_waitcnt lgkmcnt(0)
	v_mfma_f32_16x16x32_bf16 v[120:123], v[146:149], v[184:187], 0
	v_mfma_f32_16x16x32_bf16 v[116:119], v[154:157], v[184:187], 0
	v_mfma_f32_16x16x32_bf16 v[108:111], v[146:149], v[192:195], 0
	v_mfma_f32_16x16x32_bf16 v[100:103], v[154:157], v[192:195], 0
	v_mfma_f32_16x16x32_bf16 v[92:95], v[146:149], v[202:205], 0
	v_mfma_f32_16x16x32_bf16 v[84:87], v[154:157], v[202:205], 0
	v_mfma_f32_16x16x32_bf16 v[76:79], v[146:149], v[210:213], 0
	v_mfma_f32_16x16x32_bf16 v[68:71], v[154:157], v[210:213], 0
	v_mfma_f32_16x16x32_bf16 v[120:123], v[150:153], v[188:191], v[120:123]
	v_mfma_f32_16x16x32_bf16 v[116:119], v[158:161], v[188:191], v[116:119]
	v_mfma_f32_16x16x32_bf16 v[108:111], v[150:153], v[196:199], v[108:111]
	v_mfma_f32_16x16x32_bf16 v[100:103], v[158:161], v[196:199], v[100:103]
	v_mfma_f32_16x16x32_bf16 v[92:95], v[150:153], v[206:209], v[92:95]
	v_mfma_f32_16x16x32_bf16 v[84:87], v[158:161], v[206:209], v[84:87]
	v_mfma_f32_16x16x32_bf16 v[76:79], v[150:153], v[214:217], v[76:79]
	v_mfma_f32_16x16x32_bf16 v[68:71], v[158:161], v[214:217], v[68:71]
	s_setprio 0
	s_setprio 1
	v_mfma_f32_16x16x32_bf16 v[124:127], v[162:165], v[184:187], 0
	v_mfma_f32_16x16x32_bf16 v[112:115], v[176:179], v[184:187], 0
	v_mfma_f32_16x16x32_bf16 v[104:107], v[162:165], v[192:195], 0
	v_mfma_f32_16x16x32_bf16 v[96:99], v[176:179], v[192:195], 0
	v_mfma_f32_16x16x32_bf16 v[88:91], v[162:165], v[202:205], 0
	v_mfma_f32_16x16x32_bf16 v[80:83], v[176:179], v[202:205], 0
	v_mfma_f32_16x16x32_bf16 v[72:75], v[162:165], v[210:213], 0
	v_mfma_f32_16x16x32_bf16 v[64:67], v[176:179], v[210:213], 0
	v_mfma_f32_16x16x32_bf16 v[124:127], v[166:169], v[188:191], v[124:127]
	v_mfma_f32_16x16x32_bf16 v[112:115], v[180:183], v[188:191], v[112:115]
	v_mfma_f32_16x16x32_bf16 v[104:107], v[166:169], v[196:199], v[104:107]
	v_mfma_f32_16x16x32_bf16 v[96:99], v[180:183], v[196:199], v[96:99]
	v_mfma_f32_16x16x32_bf16 v[88:91], v[166:169], v[206:209], v[88:91]
	v_mfma_f32_16x16x32_bf16 v[80:83], v[180:183], v[206:209], v[80:83]
	v_mfma_f32_16x16x32_bf16 v[72:75], v[166:169], v[214:217], v[72:75]
	v_mfma_f32_16x16x32_bf16 v[64:67], v[180:183], v[214:217], v[64:67]
	s_setprio 0
	s_barrier
	s_add_i32 s47, s75, s58
	v_lshl_add_u64 v[218:219], s[48:49], 0, v[130:131]
	s_mov_b32 m0, s47
	ds_read_b128 v[184:187], v173 offset:16384
	ds_read_b128 v[188:191], v173 offset:17408
	ds_read_b128 v[192:195], v173 offset:18432
	ds_read_b128 v[196:199], v173 offset:19456
	ds_read_b128 v[202:205], v173 offset:20480
	ds_read_b128 v[206:209], v173 offset:21504
	ds_read_b128 v[210:213], v173 offset:22528
	ds_read_b128 v[214:217], v173 offset:23552
	global_load_lds_dwordx4 v[218:219], off
	s_add_i32 m0, s47, 0x2000
	v_lshl_add_u64 v[220:221], s[48:49], 0, v[134:135]
	s_add_u32 s48, s48, s12
	s_addc_u32 s49, s49, s13
	s_add_i32 s47, s76, s58
	global_load_lds_dwordx4 v[220:221], off
	v_lshl_add_u64 v[222:223], s[48:49], 0, v[130:131]
	s_mov_b32 m0, s47
	v_lshl_add_u64 v[224:225], s[48:49], 0, v[134:135]
	global_load_lds_dwordx4 v[222:223], off
	s_add_i32 m0, s47, 0x2000
	v_lshl_add_u64 v[226:227], s[6:7], 0, v[128:129]
	global_load_lds_dwordx4 v[224:225], off
	s_mov_b32 m0, s59
	v_lshl_add_u64 v[228:229], s[6:7], 0, v[132:133]
	global_load_lds_dwordx4 v[226:227], off
	s_mov_b32 m0, s60
	s_nop 0
	global_load_lds_dwordx4 v[228:229], off
	s_cmp_eq_u32 s99, 0
	s_cbranch_scc1 .Lw8_0_1
	s_waitcnt vmcnt(16)
	s_branch .Lwj_0_1

; #define PG8_STAGE(bufoff, gbase, voff) do { _Pragma("unroll") for (int _i = 0; _i < 2; ++_i) \
;         __builtin_amdgcn_global_load_lds((const unsigned*)((const char*)(gbase) + (voff)[_i]), (PG8_LAS unsigned*)(lds + (bufoff) + ldsw + _i * 8192), 16, 0, 0); } while (0)
; #define PG8_LDA(dst, b, h) do { _Pragma("unroll") for (int m = 0; m < 4; ++m) _Pragma("unroll") for (int k = 0; k < 2; ++k) dst[m][k] = *(const PG8_LAS bf16x8*)(lds + PG8_SA(b, h) + aoff + m * 2048 + k * 1024); } while (0)
; #define PG8_LDB(dst, b, h) do { _Pragma("unroll") for (int n = 0; n < 2; ++n) _Pragma("unroll") for (int k = 0; k < 2; ++k) dst[n][k] = *(const PG8_LAS bf16x8*)(lds + PG8_SB(b, h) + boff + n * 2048 + k * 1024); } while (0)
; #define PG8_MMA(ai, bj, At, Bt) do { __builtin_amdgcn_s_setprio(1); _Pragma("unroll") for (int m = 0; m < 4; ++m) _Pragma("unroll") for (int n = 0; n < 2; ++n) _Pragma("unroll") for (int k = 0; k < 2; ++k) \
;         acc[ai][bj][m][n] = __builtin_amdgcn_mfma_f32_16x16x32_bf16(Bt[n][k], At[m][k], acc[ai][bj][m][n], 0, 0, 0); __builtin_amdgcn_s_setprio(0); } while (0)
; #define PG8_WAIT_V(n) asm volatile("s_waitcnt vmcnt(" #n ")" ::: "memory")
; #define PG8_WAIT_L(n) asm volatile("s_waitcnt lgkmcnt(" #n ")" ::: "memory")
; #define PG8_BAR __builtin_amdgcn_s_barrier()
; #define PG8_SCHED __builtin_amdgcn_sched_barrier(0)
; template <class Epi, class Sched, bool ALIGN_EPI = false, bool SP2 = false>
; __device__ __forceinline__ void gemm_phase(PG8_LAS unsigned char* lds, const Gemm g, const Sched& S, const Epi& E) {
;     ...
;             PG8_WAIT_V(8); PG8_WAIT_L(0); PG8_BAR; PG8_MMA(1, 0, At, B0); PG8_MMA(1, 1, At, B1); PG8_BAR; PG8_SCHED;
;             PG8_LDB(B0, 1, 0); PG8_LDB(B1, 1, 1); PG8_SCHED; PG8_LDA(At, 1, 0); PG8_STAGE(PG8_SA(0, 1), a2 + hstep, voffA);
;             PG8_WAIT_V(8); PG8_WAIT_L(0); PG8_BAR; PG8_MMA(0, 0, At, B0); PG8_MMA(0, 1, At, B1); PG8_BAR; PG8_SCHED;
.Lwj_0_1:
	s_waitcnt lgkmcnt(0)
	s_barrier
	s_setprio 1
	s_waitcnt lgkmcnt(0)
	v_mfma_f32_16x16x32_bf16 v[60:63], v[146:149], v[184:187], 0
	v_mfma_f32_16x16x32_bf16 v[52:55], v[154:157], v[184:187], 0
	v_mfma_f32_16x16x32_bf16 v[44:47], v[146:149], v[192:195], 0
	v_mfma_f32_16x16x32_bf16 v[36:39], v[154:157], v[192:195], 0
	v_mfma_f32_16x16x32_bf16 v[28:31], v[146:149], v[202:205], 0
	v_mfma_f32_16x16x32_bf16 v[20:23], v[154:157], v[202:205], 0
	v_mfma_f32_16x16x32_bf16 v[12:15], v[146:149], v[210:213], 0
	v_mfma_f32_16x16x32_bf16 v[4:7], v[154:157], v[210:213], 0
	v_mfma_f32_16x16x32_bf16 v[60:63], v[150:153], v[188:191], v[60:63]
	v_mfma_f32_16x16x32_bf16 v[52:55], v[158:161], v[188:191], v[52:55]
	v_mfma_f32_16x16x32_bf16 v[44:47], v[150:153], v[196:199], v[44:47]
	v_mfma_f32_16x16x32_bf16 v[36:39], v[158:161], v[196:199], v[36:39]
	v_mfma_f32_16x16x32_bf16 v[28:31], v[150:153], v[206:209], v[28:31]
	v_mfma_f32_16x16x32_bf16 v[20:23], v[158:161], v[206:209], v[20:23]
	v_mfma_f32_16x16x32_bf16 v[12:15], v[150:153], v[214:217], v[12:15]
	v_mfma_f32_16x16x32_bf16 v[4:7], v[158:161], v[214:217], v[4:7]
	s_setprio 0
	s_setprio 1
	v_mfma_f32_16x16x32_bf16 v[56:59], v[162:165], v[184:187], 0
	v_mfma_f32_16x16x32_bf16 v[48:51], v[176:179], v[184:187], 0
	v_mfma_f32_16x16x32_bf16 v[40:43], v[162:165], v[192:195], 0
	v_mfma_f32_16x16x32_bf16 v[32:35], v[176:179], v[192:195], 0
	v_mfma_f32_16x16x32_bf16 v[24:27], v[162:165], v[202:205], 0
	v_mfma_f32_16x16x32_bf16 v[16:19], v[176:179], v[202:205], 0
	v_mfma_f32_16x16x32_bf16 v[8:11], v[162:165], v[210:213], 0
	v_mfma_f32_16x16x32_bf16 v[0:3], v[176:179], v[210:213], 0
	v_mfma_f32_16x16x32_bf16 v[56:59], v[166:169], v[188:191], v[56:59]
	v_mfma_f32_16x16x32_bf16 v[48:51], v[180:183], v[188:191], v[48:51]
	v_mfma_f32_16x16x32_bf16 v[40:43], v[166:169], v[196:199], v[40:43]
	v_mfma_f32_16x16x32_bf16 v[32:35], v[180:183], v[196:199], v[32:35]
	v_mfma_f32_16x16x32_bf16 v[24:27], v[166:169], v[206:209], v[24:27]
	v_mfma_f32_16x16x32_bf16 v[16:19], v[180:183], v[206:209], v[16:19]
	v_mfma_f32_16x16x32_bf16 v[8:11], v[166:169], v[214:217], v[8:11]
	v_mfma_f32_16x16x32_bf16 v[0:3], v[180:183], v[214:217], v[0:3]
	s_setprio 0
	s_barrier
	s_add_i32 s47, 0, 0x18000
	v_add_u32_e32 v136, s47, v170
	s_add_i32 s48, 0, 0x1c000
	ds_read_b128 v[146:149], v136
	ds_read_b128 v[150:153], v136 offset:1024
	ds_read_b128 v[154:157], v136 offset:2048
	ds_read_b128 v[158:161], v136 offset:3072
	v_add_u32_e32 v136, s48, v170
	ds_read_b128 v[162:165], v136
	ds_read_b128 v[166:169], v136 offset:1024
	ds_read_b128 v[176:179], v136 offset:2048
	ds_read_b128 v[180:183], v136 offset:3072
	s_add_u32 s6, s6, s12
	s_addc_u32 s7, s7, s13
	s_mov_b32 m0, s61
	v_lshl_add_u64 v[230:231], s[6:7], 0, v[128:129]
	ds_read_b128 v[184:187], v173 offset:32768
	ds_read_b128 v[188:191], v173 offset:33792
	ds_read_b128 v[192:195], v173 offset:34816
	ds_read_b128 v[196:199], v173 offset:35840
	ds_read_b128 v[202:205], v173 offset:36864
	ds_read_b128 v[206:209], v173 offset:37888
	ds_read_b128 v[210:213], v173 offset:38912
	ds_read_b128 v[214:217], v173 offset:39936
	global_load_lds_dwordx4 v[230:231], off
	v_lshl_add_u64 v[230:231], s[6:7], 0, v[132:133]
	s_mov_b32 m0, s62
	s_nop 0
	global_load_lds_dwordx4 v[230:231], off
	s_waitcnt vmcnt(8)
	s_waitcnt lgkmcnt(0)
	s_barrier
	s_setprio 1
	s_waitcnt lgkmcnt(0)
	v_mfma_f32_16x16x32_bf16 v[120:123], v[146:149], v[184:187], v[120:123]
	v_mfma_f32_16x16x32_bf16 v[116:119], v[154:157], v[184:187], v[116:119]
	v_mfma_f32_16x16x32_bf16 v[108:111], v[146:149], v[192:195], v[108:111]
	v_mfma_f32_16x16x32_bf16 v[100:103], v[154:157], v[192:195], v[100:103]
	v_mfma_f32_16x16x32_bf16 v[92:95], v[146:149], v[202:205], v[92:95]
	v_mfma_f32_16x16x32_bf16 v[84:87], v[154:157], v[202:205], v[84:87]
	v_mfma_f32_16x16x32_bf16 v[76:79], v[146:149], v[210:213], v[76:79]
	v_mfma_f32_16x16x32_bf16 v[68:71], v[154:157], v[210:213], v[68:71]
	v_mfma_f32_16x16x32_bf16 v[120:123], v[150:153], v[188:191], v[120:123]
	v_mfma_f32_16x16x32_bf16 v[116:119], v[158:161], v[188:191], v[116:119]
	v_mfma_f32_16x16x32_bf16 v[108:111], v[150:153], v[196:199], v[108:111]
	v_mfma_f32_16x16x32_bf16 v[100:103], v[158:161], v[196:199], v[100:103]
	v_mfma_f32_16x16x32_bf16 v[92:95], v[150:153], v[206:209], v[92:95]
	v_mfma_f32_16x16x32_bf16 v[84:87], v[158:161], v[206:209], v[84:87]
	v_mfma_f32_16x16x32_bf16 v[76:79], v[150:153], v[214:217], v[76:79]
	v_mfma_f32_16x16x32_bf16 v[68:71], v[158:161], v[214:217], v[68:71]
	s_setprio 0
	s_setprio 1
	v_mfma_f32_16x16x32_bf16 v[124:127], v[162:165], v[184:187], v[124:127]
	v_mfma_f32_16x16x32_bf16 v[112:115], v[176:179], v[184:187], v[112:115]
	v_mfma_f32_16x16x32_bf16 v[104:107], v[162:165], v[192:195], v[104:107]
	v_mfma_f32_16x16x32_bf16 v[96:99], v[176:179], v[192:195], v[96:99]
	v_mfma_f32_16x16x32_bf16 v[88:91], v[162:165], v[202:205], v[88:91]
	v_mfma_f32_16x16x32_bf16 v[80:83], v[176:179], v[202:205], v[80:83]
	v_mfma_f32_16x16x32_bf16 v[72:75], v[162:165], v[210:213], v[72:75]
	v_mfma_f32_16x16x32_bf16 v[64:67], v[176:179], v[210:213], v[64:67]
	v_mfma_f32_16x16x32_bf16 v[124:127], v[166:169], v[188:191], v[124:127]
	v_mfma_f32_16x16x32_bf16 v[112:115], v[180:183], v[188:191], v[112:115]
	v_mfma_f32_16x16x32_bf16 v[104:107], v[166:169], v[196:199], v[104:107]
	v_mfma_f32_16x16x32_bf16 v[96:99], v[180:183], v[196:199], v[96:99]
	v_mfma_f32_16x16x32_bf16 v[88:91], v[166:169], v[206:209], v[88:91]
	v_mfma_f32_16x16x32_bf16 v[80:83], v[180:183], v[206:209], v[80:83]
	v_mfma_f32_16x16x32_bf16 v[72:75], v[166:169], v[214:217], v[72:75]
	v_mfma_f32_16x16x32_bf16 v[64:67], v[180:183], v[214:217], v[64:67]
	s_setprio 0
	s_barrier
; #define PG8_STAGE(bufoff, gbase, voff) do { _Pragma("unroll") for (int _i = 0; _i < 2; ++_i) \
;         __builtin_amdgcn_global_load_lds((const unsigned*)((const char*)(gbase) + (voff)[_i]), (PG8_LAS unsigned*)(lds + (bufoff) + ldsw + _i * 8192), 16, 0, 0); } while (0)
; #define PG8_LDA(dst, b, h) do { _Pragma("unroll") for (int m = 0; m < 4; ++m) _Pragma("unroll") for (int k = 0; k < 2; ++k) dst[m][k] = *(const PG8_LAS bf16x8*)(lds + PG8_SA(b, h) + aoff + m * 2048 + k * 1024); } while (0)
; #define PG8_MMA(ai, bj, At, Bt) do { __builtin_amdgcn_s_setprio(1); _Pragma("unroll") for (int m = 0; m < 4; ++m) _Pragma("unroll") for (int n = 0; n < 2; ++n) _Pragma("unroll") for (int k = 0; k < 2; ++k) \
;         acc[ai][bj][m][n] = __builtin_amdgcn_mfma_f32_16x16x32_bf16(Bt[n][k], At[m][k], acc[ai][bj][m][n], 0, 0, 0); __builtin_amdgcn_s_setprio(0); } while (0)
; #define PG8_WAIT_V(n) asm volatile("s_waitcnt vmcnt(" #n ")" ::: "memory")
; #define PG8_WAIT_L(n) asm volatile("s_waitcnt lgkmcnt(" #n ")" ::: "memory")
; #define PG8_BAR __builtin_amdgcn_s_barrier()
; #define PG8_SCHED __builtin_amdgcn_sched_barrier(0)
; template <class Epi, class Sched, bool ALIGN_EPI = false, bool SP2 = false>
; __device__ __forceinline__ void gemm_phase(PG8_LAS unsigned char* lds, const Gemm g, const Sched& S, const Epi& E) {
;     ...
;             PG8_LDA(At, 1, 1); PG8_STAGE(PG8_SB(1, 0), b3, voffB); PG8_STAGE(PG8_SB(1, 1), b3 + hstep, voffB); PG8_STAGE(PG8_SA(1, 0), a3, voffA);
;             PG8_WAIT_V(8); PG8_WAIT_L(0); PG8_BAR; PG8_MMA(1, 0, At, B0); PG8_MMA(1, 1, At, B1); PG8_BAR; PG8_SCHED;
	s_add_i32 s6, s47, s58
	v_lshl_add_u64 v[218:219], v[218:219], 0, s[20:21]
	s_mov_b32 m0, s6
	ds_read_b128 v[184:187], v173 offset:49152
	ds_read_b128 v[188:191], v173 offset:50176
	ds_read_b128 v[192:195], v173 offset:51200
	ds_read_b128 v[196:199], v173 offset:52224
	ds_read_b128 v[202:205], v173 offset:53248
	ds_read_b128 v[206:209], v173 offset:54272
	ds_read_b128 v[210:213], v173 offset:55296
	ds_read_b128 v[214:217], v173 offset:56320
	global_load_lds_dwordx4 v[218:219], off
	v_lshl_add_u64 v[218:219], v[220:221], 0, s[20:21]
	s_add_i32 m0, s6, 0x2000
	s_add_i32 s6, s48, s58
	global_load_lds_dwordx4 v[218:219], off
	v_lshl_add_u64 v[218:219], v[222:223], 0, s[20:21]
	s_mov_b32 m0, s6
	s_nop 0
	global_load_lds_dwordx4 v[218:219], off
	v_lshl_add_u64 v[218:219], v[224:225], 0, s[20:21]
	s_add_i32 m0, s6, 0x2000
	s_nop 0
	global_load_lds_dwordx4 v[218:219], off
	v_lshl_add_u64 v[218:219], v[226:227], 0, s[20:21]
	s_mov_b32 m0, s63
	s_nop 0
	global_load_lds_dwordx4 v[218:219], off
	v_lshl_add_u64 v[218:219], v[228:229], 0, s[20:21]
	s_mov_b32 m0, s64
	s_nop 0
	global_load_lds_dwordx4 v[218:219], off
	s_waitcnt vmcnt(8)
	s_waitcnt lgkmcnt(0)
	s_barrier
	s_setprio 1
	s_waitcnt lgkmcnt(0)
	v_mfma_f32_16x16x32_bf16 v[60:63], v[146:149], v[184:187], v[60:63]
	v_mfma_f32_16x16x32_bf16 v[52:55], v[154:157], v[184:187], v[52:55]
	v_mfma_f32_16x16x32_bf16 v[44:47], v[146:149], v[192:195], v[44:47]
	v_mfma_f32_16x16x32_bf16 v[36:39], v[154:157], v[192:195], v[36:39]
	v_mfma_f32_16x16x32_bf16 v[28:31], v[146:149], v[202:205], v[28:31]
	v_mfma_f32_16x16x32_bf16 v[20:23], v[154:157], v[202:205], v[20:23]
	v_mfma_f32_16x16x32_bf16 v[12:15], v[146:149], v[210:213], v[12:15]
	v_mfma_f32_16x16x32_bf16 v[4:7], v[154:157], v[210:213], v[4:7]
	v_mfma_f32_16x16x32_bf16 v[60:63], v[150:153], v[188:191], v[60:63]
	v_mfma_f32_16x16x32_bf16 v[52:55], v[158:161], v[188:191], v[52:55]
	v_mfma_f32_16x16x32_bf16 v[44:47], v[150:153], v[196:199], v[44:47]
	v_mfma_f32_16x16x32_bf16 v[36:39], v[158:161], v[196:199], v[36:39]
	v_mfma_f32_16x16x32_bf16 v[28:31], v[150:153], v[206:209], v[28:31]
	v_mfma_f32_16x16x32_bf16 v[20:23], v[158:161], v[206:209], v[20:23]
	v_mfma_f32_16x16x32_bf16 v[12:15], v[150:153], v[214:217], v[12:15]
	v_mfma_f32_16x16x32_bf16 v[4:7], v[158:161], v[214:217], v[4:7]
	s_setprio 0
	s_setprio 1
	v_mfma_f32_16x16x32_bf16 v[56:59], v[162:165], v[184:187], v[56:59]
	v_mfma_f32_16x16x32_bf16 v[48:51], v[176:179], v[184:187], v[48:51]
	v_mfma_f32_16x16x32_bf16 v[40:43], v[162:165], v[192:195], v[40:43]
	v_mfma_f32_16x16x32_bf16 v[32:35], v[176:179], v[192:195], v[32:35]
	v_mfma_f32_16x16x32_bf16 v[24:27], v[162:165], v[202:205], v[24:27]
	v_mfma_f32_16x16x32_bf16 v[16:19], v[176:179], v[202:205], v[16:19]
	v_mfma_f32_16x16x32_bf16 v[8:11], v[162:165], v[210:213], v[8:11]
	v_mfma_f32_16x16x32_bf16 v[0:3], v[176:179], v[210:213], v[0:3]
	v_mfma_f32_16x16x32_bf16 v[56:59], v[166:169], v[188:191], v[56:59]
	v_mfma_f32_16x16x32_bf16 v[48:51], v[180:183], v[188:191], v[48:51]
	v_mfma_f32_16x16x32_bf16 v[40:43], v[166:169], v[196:199], v[40:43]
	v_mfma_f32_16x16x32_bf16 v[32:35], v[180:183], v[196:199], v[32:35]
	v_mfma_f32_16x16x32_bf16 v[24:27], v[166:169], v[206:209], v[24:27]
	v_mfma_f32_16x16x32_bf16 v[16:19], v[180:183], v[206:209], v[16:19]
	v_mfma_f32_16x16x32_bf16 v[8:11], v[166:169], v[214:217], v[8:11]
	v_mfma_f32_16x16x32_bf16 v[0:3], v[180:183], v[214:217], v[0:3]
	s_setprio 0
	s_barrier
	s_add_u32 s4, s4, 0x100
	s_addc_u32 s5, s5, 0
	s_add_u32 s11, s11, 0x100
	s_addc_u32 s16, s16, 0
	s_cmp_ge_i32 s46, s65
	s_mov_b32 s6, s46
	s_cbranch_scc1 .LBB0_357

;     __device__ __forceinline__ void operator()(const AccT& acc, const Unit& u, int wr, int wc, int fr_, int fq_) const {
;         int fr = fr_, fq = fq_; asm volatile("" : "+v"(fr), "+v"(fq));
;         const int pn = u.pn < 8 ? u.pn : u.pn + 8, cb = wc * 32 + 8 * fq;
;         bf16_t* const U = (bf16_t*)(ws + WS_RB); bf16_t* const A2 = (bf16_t*)(ws + WS_A2); bf16_t* const QL = (bf16_t*)(ws + WS_QL); bf16_t* const KVL = (bf16_t*)(ws + WS_KVL); bf16_t* const KPE = (bf16_t*)(ws + WS_KPE);
;         bf16_t* const R = (bf16_t*)out; bf16_t* const SB = (bf16_t*)out + (size_t)T * 1024; float* const ssq_q = (float*)(ws + WS_SSQ); float* const ssq_kv = ssq_q + T; const float* const rope = (const float*)(ws + WS_ROPE);
; #pragma unroll
;         for (int ai = 0; ai < 2; ++ai)
; #pragma unroll
;             for (int m = 0; m < 4; ++m) {
;                 const size_t row = (size_t)ROW_OF(ai, m);
;                 const f32x4 a0 = acc[ai][0][m][0], a1 = acc[ai][0][m][1], b0 = acc[ai][1][m][0], b1 = acc[ai][1][m][1];
;                 if (pn < 8) {
.LBB0_359:
	s_add_i32 s4, s10, 8
	s_cmp_lt_i32 s10, 8
	s_cselect_b32 s82, s10, s4
	s_cmp_lg_u32 s82, 18
	s_cselect_b32 s99, 1, 0
	s_cmp_gt_i32 s82, 7
	s_cselect_b64 s[10:11], -1, 0
	s_cmp_gt_u32 s82, 22
	s_cselect_b64 s[48:49], -1, 0
	s_lshl_b32 s6, s82, 7
	s_add_i32 s16, s6, 0xfffff480
	s_lshl_b64 s[46:47], s[16:17], 1
	v_mov_b32_e32 v136, v201
	v_mov_b32_e32 v150, v232
	s_add_u32 s50, s88, s46
	s_addc_u32 s51, s89, s47
	v_lshl_add_u32 v148, v150, 3, s67
	v_lshlrev_b32_e32 v146, 4, v150
	v_ashrrev_i32_e32 v149, 31, v148
	s_add_u32 s46, s71, s46
	v_ashrrev_i32_e32 v147, 31, v146
	v_lshlrev_b64 v[160:161], 1, v[148:149]
	s_addc_u32 s47, s72, s47
	s_lshl_b32 s7, s82, 9
	v_lshl_add_u64 v[158:159], v[146:147], 2, s[36:37]
	v_lshlrev_b32_e32 v146, 8, v150
	v_cmp_eq_u32_e64 s[4:5], 0, v150
	v_lshl_add_u64 v[150:151], s[46:47], 0, v[160:161]
	s_add_u32 s46, s90, s7
	s_addc_u32 s47, s91, 0
	s_ashr_i32 s7, s6, 31
	s_lshl_b64 s[6:7], s[6:7], 1
	s_add_u32 s6, s69, s6
	s_addc_u32 s7, s70, s7
	s_lshl_b32 s16, s33, 8
	s_add_i32 s16, s16, s66
	v_and_b32_e32 v175, 0x100, v146
	v_and_b32_e32 v156, 0xfffffe00, v146
	v_add_u32_e32 v146, s16, v136
	v_ashrrev_i32_e32 v157, 31, v156
	v_lshl_add_u64 v[154:155], s[28:29], 0, v[160:161]
	v_lshl_add_u64 v[152:153], s[50:51], 0, v[160:161]
	v_ashrrev_i32_e32 v147, 31, v146
	s_mov_b64 s[50:51], -1
	s_and_b64 vcc, exec, s[10:11]
	s_cbranch_vccz .LBB0_391
	s_mov_b64 s[54:55], -1
	s_mov_b64 s[50:51], 0
	s_cmp_lt_i32 s82, 17
	s_mov_b64 s[52:53], 0
	s_cbranch_scc0 .LBB0_364
	s_and_b64 vcc, exec, s[54:55]
	s_cbranch_vccnz .LBB0_381

;     __device__ __forceinline__ void operator()(const AccT& acc, const Unit& u, int wr, int wc, int fr_, int fq_) const {
;     ...
;         float ssv[2][4];
; #pragma unroll
;         for (int ai = 0; ai < 2; ++ai)
; #pragma unroll
;             for (int m = 0; m < 4; ++m) ssv[ai][m] = ssq_kv[(size_t)ROW_OF(ai, m)];
.LBB0_697:
	s_mov_b64 s[16:17], 0x80
	s_add_i32 m0, s40, 0x18000
	v_lshl_add_u64 v[8:9], v[8:9], 0, s[16:17]
	s_waitcnt vmcnt(2)
	s_barrier
	global_load_lds_dwordx4 v[8:9], off
	v_lshl_add_u64 v[4:5], v[4:5], 0, s[16:17]
	s_add_i32 m0, s40, 0x1a000
	s_add_i32 s45, s40, 0x8000
	global_load_lds_dwordx4 v[4:5], off
	v_lshl_add_u64 v[4:5], v[6:7], 0, s[16:17]
	s_mov_b32 m0, s45
	s_add_i32 s46, s40, 0xa000
	global_load_lds_dwordx4 v[4:5], off
	v_lshl_add_u64 v[4:5], v[10:11], 0, s[16:17]
	s_mov_b32 m0, s46
	v_lshl_add_u64 v[2:3], v[2:3], 0, s[16:17]
	global_load_lds_dwordx4 v[4:5], off
	s_add_i32 m0, s40, 0x1c000
	v_lshl_add_u64 v[0:1], v[0:1], 0, s[16:17]
	global_load_lds_dwordx4 v[2:3], off
	s_add_i32 m0, s40, 0x1e000
	s_lshr_b32 s1, s1, 26
	global_load_lds_dwordx4 v[0:1], off
	s_add_i32 s1, s0, s1
	s_and_b32 s4, s4, 3
	s_ashr_i32 s47, s1, 6
	s_lshl_b32 s48, s5, 6
	s_lshl_b32 s1, s5, 13
	s_cmp_gt_i32 s0, 63
	s_cselect_b64 s[18:19], -1, 0
	s_add_i32 s49, s47, -2
	v_lshlrev_b32_e32 v1, 2, v201
	s_cmpk_lt_u32 s20, 0x100
	v_lshl_or_b32 v0, v201, 6, v238
	v_and_b32_e32 v1, 32, v1
	s_cselect_b64 s[20:21], -1, 0
	s_add_u32 s22, s90, 0x5000000
	v_bitop3_b32 v0, v0, s1, v1 bitop3:0xde
	s_addc_u32 s23, s91, 0
	v_add_u32_e32 v1, v237, v235
	s_add_u32 s24, s90, 0x20000
	v_mul_lo_u32 v1, s0, v1
	s_addc_u32 s25, s91, 0
	s_lshl_b32 s1, s4, 9
	v_lshlrev_b32_e32 v1, 1, v1
	s_add_u32 s1, s90, s1
	v_add3_u32 v136, v233, v1, v234
	v_add_u32_e32 v1, v236, v235
	s_addc_u32 s5, s91, 0
	v_mul_lo_u32 v1, s0, v1
	s_waitcnt vmcnt(6)
	s_add_u32 s26, s1, 0x1b000000
	v_lshlrev_b32_e32 v1, 1, v1
	v_lshl_or_b32 v168, s4, 12, v239
	s_addc_u32 s27, s5, 0
	v_lshl_add_u64 v[138:139], s[10:11], 0, v[136:137]
	v_add3_u32 v136, v233, v1, v234
	s_add_i32 s53, 0, 0x10000
	s_add_i32 s54, 0, 0x14000
	s_lshl_b32 s50, s4, 2
	s_ashr_i32 s51, s83, 31
	s_ashr_i32 s52, s80, 31
	v_lshl_add_u64 v[140:141], s[10:11], 0, v[136:137]
	v_mov_b64_e32 v[142:143], 0x400
	v_mov_b64_e32 v[144:145], 0x3ff
	v_add_u32_e32 v169, s53, v168
	v_add_u32_e32 v170, s54, v168
	v_add_u32_e32 v171, 0, v0
	v_mov_b32_e32 v172, 0x358637bd
	s_mov_b32 s55, 0x80000
	s_barrier
	v_lshl_add_u32 v253, s35, 8, v201
	v_add_lshl_u32 v253, v253, s48, 2
	global_load_dword v245, v253, s[24:25]
	global_load_dword v246, v253, s[24:25] offset:64
	global_load_dword v247, v253, s[24:25] offset:128
	global_load_dword v248, v253, s[24:25] offset:192
	global_load_dword v249, v253, s[24:25] offset:512
	global_load_dword v250, v253, s[24:25] offset:576
	global_load_dword v251, v253, s[24:25] offset:640
	global_load_dword v252, v253, s[24:25] offset:704
	s_mov_b32 s99, 0
	s_branch .LBB0_700

; #define PG8_STAGE(bufoff, gbase, voff) do { _Pragma("unroll") for (int _i = 0; _i < 2; ++_i) \
;         __builtin_amdgcn_global_load_lds((const unsigned*)((const char*)(gbase) + (voff)[_i]), (PG8_LAS unsigned*)(lds + (bufoff) + ldsw + _i * 8192), 16, 0, 0); } while (0)
; #define PG8_LDA(dst, b, h) do { _Pragma("unroll") for (int m = 0; m < 4; ++m) _Pragma("unroll") for (int k = 0; k < 2; ++k) dst[m][k] = *(const PG8_LAS bf16x8*)(lds + PG8_SA(b, h) + aoff + m * 2048 + k * 1024); } while (0)
; #define PG8_LDB(dst, b, h) do { _Pragma("unroll") for (int n = 0; n < 2; ++n) _Pragma("unroll") for (int k = 0; k < 2; ++k) dst[n][k] = *(const PG8_LAS bf16x8*)(lds + PG8_SB(b, h) + boff + n * 2048 + k * 1024); } while (0)
; #define PG8_MMA(ai, bj, At, Bt) do { __builtin_amdgcn_s_setprio(1); _Pragma("unroll") for (int m = 0; m < 4; ++m) _Pragma("unroll") for (int n = 0; n < 2; ++n) _Pragma("unroll") for (int k = 0; k < 2; ++k) \
;         acc[ai][bj][m][n] = __builtin_amdgcn_mfma_f32_16x16x32_bf16(Bt[n][k], At[m][k], acc[ai][bj][m][n], 0, 0, 0); __builtin_amdgcn_s_setprio(0); } while (0)
; #define PG8_WAIT_V(n) asm volatile("s_waitcnt vmcnt(" #n ")" ::: "memory")
; #define PG8_WAIT_L(n) asm volatile("s_waitcnt lgkmcnt(" #n ")" ::: "memory")
; #define PG8_BAR __builtin_amdgcn_s_barrier()
; #define PG8_SCHED __builtin_amdgcn_sched_barrier(0)
; template <class Epi, class Sched, bool ALIGN_EPI = false, bool SP2 = false>
; __device__ __forceinline__ void gemm_phase(PG8_LAS unsigned char* lds, const Gemm g, const Sched& S, const Epi& E) {
;     ...
;             PG8_LDB(B0, 0, 0); PG8_LDB(B1, 0, 1); PG8_SCHED; PG8_LDA(At, 0, 0); PG8_STAGE(PG8_SA(1, 1), a1 + hstep, voffA);
;             PG8_WAIT_V(8); PG8_WAIT_L(0); PG8_BAR; PG8_MMA(0, 0, At, B0); PG8_MMA(0, 1, At, B1); PG8_BAR; PG8_SCHED;
.LBB0_710:
	s_andn2_b64 vcc, exec, s[18:19]
	s_cbranch_vccnz .LBB0_713
	s_add_u32 s6, s6, 0x80
	s_addc_u32 s7, s7, 0
	s_add_u32 s58, s30, 0x100
	s_addc_u32 s59, s31, 0
	s_mov_b32 s30, 0
	ds_read_b128 v[146:149], v169
	ds_read_b128 v[150:153], v169 offset:1024
	ds_read_b128 v[154:157], v169 offset:2048
	ds_read_b128 v[158:161], v169 offset:3072
	ds_read_b128 v[162:165], v170
	ds_read_b128 v[174:177], v170 offset:1024
	ds_read_b128 v[178:181], v170 offset:2048
	ds_read_b128 v[182:185], v170 offset:3072
	s_add_i32 s60, s30, 2
	s_add_u32 s61, s6, 0x80
	s_addc_u32 s31, s7, 0
	s_cmp_eq_u32 s49, s30
	s_cselect_b32 s30, s0, s61
	s_cselect_b32 s31, s1, s31
	s_cselect_b32 s63, s29, s59
	s_cselect_b32 s62, s28, s58
	v_lshl_add_u64 v[166:167], s[6:7], 0, v[138:139]
	s_add_i32 m0, s40, 0xc000
	ds_read_b128 v[186:189], v171
	ds_read_b128 v[190:193], v171 offset:1024
	ds_read_b128 v[194:197], v171 offset:2048
	ds_read_b128 v[202:205], v171 offset:3072
	ds_read_b128 v[206:209], v171 offset:4096
	ds_read_b128 v[210:213], v171 offset:5120
	ds_read_b128 v[214:217], v171 offset:6144
	ds_read_b128 v[218:221], v171 offset:7168
	global_load_lds_dwordx4 v[166:167], off
	v_lshl_add_u64 v[166:167], s[6:7], 0, v[140:141]
	s_add_i32 m0, s40, 0xe000
	s_nop 0
	global_load_lds_dwordx4 v[166:167], off
	s_cmp_eq_u32 s99, 0
	s_cbranch_scc1 .Lw8_1_0
	s_waitcnt vmcnt(16)
	s_branch .Lwj_1_0

; #define PG8_STAGE(bufoff, gbase, voff) do { _Pragma("unroll") for (int _i = 0; _i < 2; ++_i) \
;         __builtin_amdgcn_global_load_lds((const unsigned*)((const char*)(gbase) + (voff)[_i]), (PG8_LAS unsigned*)(lds + (bufoff) + ldsw + _i * 8192), 16, 0, 0); } while (0)
; #define PG8_LDA(dst, b, h) do { _Pragma("unroll") for (int m = 0; m < 4; ++m) _Pragma("unroll") for (int k = 0; k < 2; ++k) dst[m][k] = *(const PG8_LAS bf16x8*)(lds + PG8_SA(b, h) + aoff + m * 2048 + k * 1024); } while (0)
; #define PG8_MMA(ai, bj, At, Bt) do { __builtin_amdgcn_s_setprio(1); _Pragma("unroll") for (int m = 0; m < 4; ++m) _Pragma("unroll") for (int n = 0; n < 2; ++n) _Pragma("unroll") for (int k = 0; k < 2; ++k) \
;         acc[ai][bj][m][n] = __builtin_amdgcn_mfma_f32_16x16x32_bf16(Bt[n][k], At[m][k], acc[ai][bj][m][n], 0, 0, 0); __builtin_amdgcn_s_setprio(0); } while (0)
; #define PG8_WAIT_V(n) asm volatile("s_waitcnt vmcnt(" #n ")" ::: "memory")
; #define PG8_WAIT_L(n) asm volatile("s_waitcnt lgkmcnt(" #n ")" ::: "memory")
; #define PG8_BAR __builtin_amdgcn_s_barrier()
; #define PG8_SCHED __builtin_amdgcn_sched_barrier(0)
; template <class Epi, class Sched, bool ALIGN_EPI = false, bool SP2 = false>
; __device__ __forceinline__ void gemm_phase(PG8_LAS unsigned char* lds, const Gemm g, const Sched& S, const Epi& E) {
;     ...
;             PG8_WAIT_V(8); PG8_WAIT_L(0); PG8_BAR; PG8_MMA(0, 0, At, B0); PG8_MMA(0, 1, At, B1); PG8_BAR; PG8_SCHED;
;             PG8_LDA(At, 0, 1); PG8_STAGE(PG8_SB(0, 0), b2, voffB); PG8_STAGE(PG8_SB(0, 1), b2 + hstep, voffB); PG8_STAGE(PG8_SA(0, 0), a2, voffA);
;             PG8_WAIT_V(8); PG8_WAIT_L(0); PG8_BAR; PG8_MMA(1, 0, At, B0); PG8_MMA(1, 1, At, B1); PG8_BAR; PG8_SCHED;
.Lwj_1_0:
	s_waitcnt lgkmcnt(0)
	s_barrier
	s_setprio 1
	s_waitcnt lgkmcnt(0)
	v_mfma_f32_16x16x32_bf16 v[120:123], v[146:149], v[186:189], 0
	v_mfma_f32_16x16x32_bf16 v[124:127], v[154:157], v[186:189], 0
	v_mfma_f32_16x16x32_bf16 v[108:111], v[146:149], v[194:197], 0
	v_mfma_f32_16x16x32_bf16 v[104:107], v[154:157], v[194:197], 0
	v_mfma_f32_16x16x32_bf16 v[92:95], v[146:149], v[206:209], 0
	v_mfma_f32_16x16x32_bf16 v[88:91], v[154:157], v[206:209], 0
	v_mfma_f32_16x16x32_bf16 v[76:79], v[146:149], v[214:217], 0
	v_mfma_f32_16x16x32_bf16 v[72:75], v[154:157], v[214:217], 0
	v_mfma_f32_16x16x32_bf16 v[120:123], v[150:153], v[190:193], v[120:123]
	v_mfma_f32_16x16x32_bf16 v[124:127], v[158:161], v[190:193], v[124:127]
	v_mfma_f32_16x16x32_bf16 v[108:111], v[150:153], v[202:205], v[108:111]
	v_mfma_f32_16x16x32_bf16 v[104:107], v[158:161], v[202:205], v[104:107]
	v_mfma_f32_16x16x32_bf16 v[92:95], v[150:153], v[210:213], v[92:95]
	v_mfma_f32_16x16x32_bf16 v[88:91], v[158:161], v[210:213], v[88:91]
	v_mfma_f32_16x16x32_bf16 v[76:79], v[150:153], v[218:221], v[76:79]
	v_mfma_f32_16x16x32_bf16 v[72:75], v[158:161], v[218:221], v[72:75]
	s_setprio 0
	s_setprio 1
	v_mfma_f32_16x16x32_bf16 v[116:119], v[162:165], v[186:189], 0
	v_mfma_f32_16x16x32_bf16 v[112:115], v[178:181], v[186:189], 0
	v_mfma_f32_16x16x32_bf16 v[100:103], v[162:165], v[194:197], 0
	v_mfma_f32_16x16x32_bf16 v[96:99], v[178:181], v[194:197], 0
	v_mfma_f32_16x16x32_bf16 v[84:87], v[162:165], v[206:209], 0
	v_mfma_f32_16x16x32_bf16 v[80:83], v[178:181], v[206:209], 0
	v_mfma_f32_16x16x32_bf16 v[68:71], v[162:165], v[214:217], 0
	v_mfma_f32_16x16x32_bf16 v[64:67], v[178:181], v[214:217], 0
	v_mfma_f32_16x16x32_bf16 v[116:119], v[174:177], v[190:193], v[116:119]
	v_mfma_f32_16x16x32_bf16 v[112:115], v[182:185], v[190:193], v[112:115]
	v_mfma_f32_16x16x32_bf16 v[100:103], v[174:177], v[202:205], v[100:103]
	v_mfma_f32_16x16x32_bf16 v[96:99], v[182:185], v[202:205], v[96:99]
	v_mfma_f32_16x16x32_bf16 v[84:87], v[174:177], v[210:213], v[84:87]
	v_mfma_f32_16x16x32_bf16 v[80:83], v[182:185], v[210:213], v[80:83]
	v_mfma_f32_16x16x32_bf16 v[68:71], v[174:177], v[218:221], v[68:71]
	v_mfma_f32_16x16x32_bf16 v[64:67], v[182:185], v[218:221], v[64:67]
	s_setprio 0
	s_barrier
	s_add_i32 s61, s53, s39
	v_lshl_add_u64 v[166:167], s[62:63], 0, v[130:131]
	s_mov_b32 m0, s61
	ds_read_b128 v[186:189], v171 offset:16384
	ds_read_b128 v[190:193], v171 offset:17408
	ds_read_b128 v[194:197], v171 offset:18432
	ds_read_b128 v[202:205], v171 offset:19456
	ds_read_b128 v[206:209], v171 offset:20480
	ds_read_b128 v[210:213], v171 offset:21504
	ds_read_b128 v[214:217], v171 offset:22528
	ds_read_b128 v[218:221], v171 offset:23552
	global_load_lds_dwordx4 v[166:167], off
	s_add_i32 m0, s61, 0x2000
	v_lshl_add_u64 v[198:199], s[62:63], 0, v[134:135]
	s_add_u32 s62, s62, s10
	s_addc_u32 s63, s63, s11
	s_add_i32 s61, s54, s39
	global_load_lds_dwordx4 v[198:199], off
	v_lshl_add_u64 v[222:223], s[62:63], 0, v[130:131]
	s_mov_b32 m0, s61
	v_lshl_add_u64 v[224:225], s[62:63], 0, v[134:135]
	global_load_lds_dwordx4 v[222:223], off
	s_add_i32 m0, s61, 0x2000
	v_lshl_add_u64 v[226:227], s[30:31], 0, v[128:129]
	global_load_lds_dwordx4 v[224:225], off
	s_mov_b32 m0, s40
	v_lshl_add_u64 v[228:229], s[30:31], 0, v[132:133]
	global_load_lds_dwordx4 v[226:227], off
	s_mov_b32 m0, s41
	s_nop 0
	global_load_lds_dwordx4 v[228:229], off
	s_cmp_eq_u32 s99, 0
	s_cbranch_scc1 .Lw8_1_1
	s_waitcnt vmcnt(16)
	s_branch .Lwj_1_1

; #define PG8_STAGE(bufoff, gbase, voff) do { _Pragma("unroll") for (int _i = 0; _i < 2; ++_i) \
;         __builtin_amdgcn_global_load_lds((const unsigned*)((const char*)(gbase) + (voff)[_i]), (PG8_LAS unsigned*)(lds + (bufoff) + ldsw + _i * 8192), 16, 0, 0); } while (0)
; #define PG8_LDA(dst, b, h) do { _Pragma("unroll") for (int m = 0; m < 4; ++m) _Pragma("unroll") for (int k = 0; k < 2; ++k) dst[m][k] = *(const PG8_LAS bf16x8*)(lds + PG8_SA(b, h) + aoff + m * 2048 + k * 1024); } while (0)
; #define PG8_LDB(dst, b, h) do { _Pragma("unroll") for (int n = 0; n < 2; ++n) _Pragma("unroll") for (int k = 0; k < 2; ++k) dst[n][k] = *(const PG8_LAS bf16x8*)(lds + PG8_SB(b, h) + boff + n * 2048 + k * 1024); } while (0)
; #define PG8_MMA(ai, bj, At, Bt) do { __builtin_amdgcn_s_setprio(1); _Pragma("unroll") for (int m = 0; m < 4; ++m) _Pragma("unroll") for (int n = 0; n < 2; ++n) _Pragma("unroll") for (int k = 0; k < 2; ++k) \
;         acc[ai][bj][m][n] = __builtin_amdgcn_mfma_f32_16x16x32_bf16(Bt[n][k], At[m][k], acc[ai][bj][m][n], 0, 0, 0); __builtin_amdgcn_s_setprio(0); } while (0)
; #define PG8_WAIT_V(n) asm volatile("s_waitcnt vmcnt(" #n ")" ::: "memory")
; #define PG8_WAIT_L(n) asm volatile("s_waitcnt lgkmcnt(" #n ")" ::: "memory")
; #define PG8_BAR __builtin_amdgcn_s_barrier()
; #define PG8_SCHED __builtin_amdgcn_sched_barrier(0)
; template <class Epi, class Sched, bool ALIGN_EPI = false, bool SP2 = false>
; __device__ __forceinline__ void gemm_phase(PG8_LAS unsigned char* lds, const Gemm g, const Sched& S, const Epi& E) {
;     ...
;             PG8_WAIT_V(8); PG8_WAIT_L(0); PG8_BAR; PG8_MMA(1, 0, At, B0); PG8_MMA(1, 1, At, B1); PG8_BAR; PG8_SCHED;
;             PG8_LDB(B0, 1, 0); PG8_LDB(B1, 1, 1); PG8_SCHED; PG8_LDA(At, 1, 0); PG8_STAGE(PG8_SA(0, 1), a2 + hstep, voffA);
;             PG8_WAIT_V(8); PG8_WAIT_L(0); PG8_BAR; PG8_MMA(0, 0, At, B0); PG8_MMA(0, 1, At, B1); PG8_BAR; PG8_SCHED;
.Lwj_1_1:
	s_waitcnt lgkmcnt(0)
	s_barrier
	s_setprio 1
	s_waitcnt lgkmcnt(0)
	v_mfma_f32_16x16x32_bf16 v[60:63], v[146:149], v[186:189], 0
	v_mfma_f32_16x16x32_bf16 v[56:59], v[154:157], v[186:189], 0
	v_mfma_f32_16x16x32_bf16 v[44:47], v[146:149], v[194:197], 0
	v_mfma_f32_16x16x32_bf16 v[40:43], v[154:157], v[194:197], 0
	v_mfma_f32_16x16x32_bf16 v[28:31], v[146:149], v[206:209], 0
	v_mfma_f32_16x16x32_bf16 v[24:27], v[154:157], v[206:209], 0
	v_mfma_f32_16x16x32_bf16 v[12:15], v[146:149], v[214:217], 0
	v_mfma_f32_16x16x32_bf16 v[8:11], v[154:157], v[214:217], 0
	v_mfma_f32_16x16x32_bf16 v[60:63], v[150:153], v[190:193], v[60:63]
	v_mfma_f32_16x16x32_bf16 v[56:59], v[158:161], v[190:193], v[56:59]
	v_mfma_f32_16x16x32_bf16 v[44:47], v[150:153], v[202:205], v[44:47]
	v_mfma_f32_16x16x32_bf16 v[40:43], v[158:161], v[202:205], v[40:43]
	v_mfma_f32_16x16x32_bf16 v[28:31], v[150:153], v[210:213], v[28:31]
	v_mfma_f32_16x16x32_bf16 v[24:27], v[158:161], v[210:213], v[24:27]
	v_mfma_f32_16x16x32_bf16 v[12:15], v[150:153], v[218:221], v[12:15]
	v_mfma_f32_16x16x32_bf16 v[8:11], v[158:161], v[218:221], v[8:11]
	s_setprio 0
	s_setprio 1
	v_mfma_f32_16x16x32_bf16 v[52:55], v[162:165], v[186:189], 0
	v_mfma_f32_16x16x32_bf16 v[48:51], v[178:181], v[186:189], 0
	v_mfma_f32_16x16x32_bf16 v[36:39], v[162:165], v[194:197], 0
	v_mfma_f32_16x16x32_bf16 v[32:35], v[178:181], v[194:197], 0
	v_mfma_f32_16x16x32_bf16 v[20:23], v[162:165], v[206:209], 0
	v_mfma_f32_16x16x32_bf16 v[16:19], v[178:181], v[206:209], 0
	v_mfma_f32_16x16x32_bf16 v[0:3], v[162:165], v[214:217], 0
	v_mfma_f32_16x16x32_bf16 v[4:7], v[178:181], v[214:217], 0
	v_mfma_f32_16x16x32_bf16 v[52:55], v[174:177], v[190:193], v[52:55]
	v_mfma_f32_16x16x32_bf16 v[48:51], v[182:185], v[190:193], v[48:51]
	v_mfma_f32_16x16x32_bf16 v[36:39], v[174:177], v[202:205], v[36:39]
	v_mfma_f32_16x16x32_bf16 v[32:35], v[182:185], v[202:205], v[32:35]
	v_mfma_f32_16x16x32_bf16 v[20:23], v[174:177], v[210:213], v[20:23]
	v_mfma_f32_16x16x32_bf16 v[16:19], v[182:185], v[210:213], v[16:19]
	v_mfma_f32_16x16x32_bf16 v[0:3], v[174:177], v[218:221], v[0:3]
	v_mfma_f32_16x16x32_bf16 v[4:7], v[182:185], v[218:221], v[4:7]
	s_setprio 0
	s_barrier
	s_add_i32 s61, 0, 0x18000
	v_add_u32_e32 v136, s61, v168
	s_add_i32 s62, 0, 0x1c000
	ds_read_b128 v[146:149], v136
	ds_read_b128 v[150:153], v136 offset:1024
	ds_read_b128 v[154:157], v136 offset:2048
	ds_read_b128 v[158:161], v136 offset:3072
	v_add_u32_e32 v136, s62, v168
	ds_read_b128 v[162:165], v136
	ds_read_b128 v[174:177], v136 offset:1024
	ds_read_b128 v[178:181], v136 offset:2048
	ds_read_b128 v[182:185], v136 offset:3072
	s_add_u32 s30, s30, s10
	s_addc_u32 s31, s31, s11
	s_mov_b32 m0, s42
	v_lshl_add_u64 v[230:231], s[30:31], 0, v[128:129]
	ds_read_b128 v[186:189], v171 offset:32768
	ds_read_b128 v[190:193], v171 offset:33792
	ds_read_b128 v[194:197], v171 offset:34816
	ds_read_b128 v[202:205], v171 offset:35840
	ds_read_b128 v[206:209], v171 offset:36864
	ds_read_b128 v[210:213], v171 offset:37888
	ds_read_b128 v[214:217], v171 offset:38912
	ds_read_b128 v[218:221], v171 offset:39936
	global_load_lds_dwordx4 v[230:231], off
	v_lshl_add_u64 v[230:231], s[30:31], 0, v[132:133]
	s_mov_b32 m0, s43
	s_nop 0
	global_load_lds_dwordx4 v[230:231], off
	s_waitcnt vmcnt(8)
	s_waitcnt lgkmcnt(0)
	s_barrier
	s_setprio 1
	s_waitcnt lgkmcnt(0)
	v_mfma_f32_16x16x32_bf16 v[120:123], v[146:149], v[186:189], v[120:123]
	v_mfma_f32_16x16x32_bf16 v[124:127], v[154:157], v[186:189], v[124:127]
	v_mfma_f32_16x16x32_bf16 v[108:111], v[146:149], v[194:197], v[108:111]
	v_mfma_f32_16x16x32_bf16 v[104:107], v[154:157], v[194:197], v[104:107]
	v_mfma_f32_16x16x32_bf16 v[92:95], v[146:149], v[206:209], v[92:95]
	v_mfma_f32_16x16x32_bf16 v[88:91], v[154:157], v[206:209], v[88:91]
	v_mfma_f32_16x16x32_bf16 v[76:79], v[146:149], v[214:217], v[76:79]
	v_mfma_f32_16x16x32_bf16 v[72:75], v[154:157], v[214:217], v[72:75]
	v_mfma_f32_16x16x32_bf16 v[120:123], v[150:153], v[190:193], v[120:123]
	v_mfma_f32_16x16x32_bf16 v[124:127], v[158:161], v[190:193], v[124:127]
	v_mfma_f32_16x16x32_bf16 v[108:111], v[150:153], v[202:205], v[108:111]
	v_mfma_f32_16x16x32_bf16 v[104:107], v[158:161], v[202:205], v[104:107]
	v_mfma_f32_16x16x32_bf16 v[92:95], v[150:153], v[210:213], v[92:95]
	v_mfma_f32_16x16x32_bf16 v[88:91], v[158:161], v[210:213], v[88:91]
	v_mfma_f32_16x16x32_bf16 v[76:79], v[150:153], v[218:221], v[76:79]
	v_mfma_f32_16x16x32_bf16 v[72:75], v[158:161], v[218:221], v[72:75]
	s_setprio 0
	s_setprio 1
	v_mfma_f32_16x16x32_bf16 v[116:119], v[162:165], v[186:189], v[116:119]
	v_mfma_f32_16x16x32_bf16 v[112:115], v[178:181], v[186:189], v[112:115]
	v_mfma_f32_16x16x32_bf16 v[100:103], v[162:165], v[194:197], v[100:103]
	v_mfma_f32_16x16x32_bf16 v[96:99], v[178:181], v[194:197], v[96:99]
	v_mfma_f32_16x16x32_bf16 v[84:87], v[162:165], v[206:209], v[84:87]
	v_mfma_f32_16x16x32_bf16 v[80:83], v[178:181], v[206:209], v[80:83]
	v_mfma_f32_16x16x32_bf16 v[68:71], v[162:165], v[214:217], v[68:71]
	v_mfma_f32_16x16x32_bf16 v[64:67], v[178:181], v[214:217], v[64:67]
	v_mfma_f32_16x16x32_bf16 v[116:119], v[174:177], v[190:193], v[116:119]
	v_mfma_f32_16x16x32_bf16 v[112:115], v[182:185], v[190:193], v[112:115]
	v_mfma_f32_16x16x32_bf16 v[100:103], v[174:177], v[202:205], v[100:103]
	v_mfma_f32_16x16x32_bf16 v[96:99], v[182:185], v[202:205], v[96:99]
	v_mfma_f32_16x16x32_bf16 v[84:87], v[174:177], v[210:213], v[84:87]
	v_mfma_f32_16x16x32_bf16 v[80:83], v[182:185], v[210:213], v[80:83]
	v_mfma_f32_16x16x32_bf16 v[68:71], v[174:177], v[218:221], v[68:71]
	v_mfma_f32_16x16x32_bf16 v[64:67], v[182:185], v[218:221], v[64:67]
	s_setprio 0
	s_barrier
; #define PG8_STAGE(bufoff, gbase, voff) do { _Pragma("unroll") for (int _i = 0; _i < 2; ++_i) \
;         __builtin_amdgcn_global_load_lds((const unsigned*)((const char*)(gbase) + (voff)[_i]), (PG8_LAS unsigned*)(lds + (bufoff) + ldsw + _i * 8192), 16, 0, 0); } while (0)
; #define PG8_LDA(dst, b, h) do { _Pragma("unroll") for (int m = 0; m < 4; ++m) _Pragma("unroll") for (int k = 0; k < 2; ++k) dst[m][k] = *(const PG8_LAS bf16x8*)(lds + PG8_SA(b, h) + aoff + m * 2048 + k * 1024); } while (0)
; #define PG8_MMA(ai, bj, At, Bt) do { __builtin_amdgcn_s_setprio(1); _Pragma("unroll") for (int m = 0; m < 4; ++m) _Pragma("unroll") for (int n = 0; n < 2; ++n) _Pragma("unroll") for (int k = 0; k < 2; ++k) \
;         acc[ai][bj][m][n] = __builtin_amdgcn_mfma_f32_16x16x32_bf16(Bt[n][k], At[m][k], acc[ai][bj][m][n], 0, 0, 0); __builtin_amdgcn_s_setprio(0); } while (0)
; #define PG8_WAIT_V(n) asm volatile("s_waitcnt vmcnt(" #n ")" ::: "memory")
; #define PG8_WAIT_L(n) asm volatile("s_waitcnt lgkmcnt(" #n ")" ::: "memory")
; #define PG8_BAR __builtin_amdgcn_s_barrier()
; #define PG8_SCHED __builtin_amdgcn_sched_barrier(0)
; template <class Epi, class Sched, bool ALIGN_EPI = false, bool SP2 = false>
; __device__ __forceinline__ void gemm_phase(PG8_LAS unsigned char* lds, const Gemm g, const Sched& S, const Epi& E) {
;     ...
;             PG8_LDA(At, 1, 1); PG8_STAGE(PG8_SB(1, 0), b3, voffB); PG8_STAGE(PG8_SB(1, 1), b3 + hstep, voffB); PG8_STAGE(PG8_SA(1, 0), a3, voffA);
;             PG8_WAIT_V(8); PG8_WAIT_L(0); PG8_BAR; PG8_MMA(1, 0, At, B0); PG8_MMA(1, 1, At, B1); PG8_BAR; PG8_SCHED;
	s_add_i32 s30, s61, s39
	v_lshl_add_u64 v[166:167], v[166:167], 0, s[16:17]
	s_mov_b32 m0, s30
	ds_read_b128 v[186:189], v171 offset:49152
	ds_read_b128 v[190:193], v171 offset:50176
	ds_read_b128 v[194:197], v171 offset:51200
	ds_read_b128 v[202:205], v171 offset:52224
	ds_read_b128 v[206:209], v171 offset:53248
	ds_read_b128 v[210:213], v171 offset:54272
	ds_read_b128 v[214:217], v171 offset:55296
	ds_read_b128 v[218:221], v171 offset:56320
	global_load_lds_dwordx4 v[166:167], off
	v_lshl_add_u64 v[166:167], v[198:199], 0, s[16:17]
	s_add_i32 m0, s30, 0x2000
	s_add_i32 s30, s62, s39
	global_load_lds_dwordx4 v[166:167], off
	v_lshl_add_u64 v[166:167], v[222:223], 0, s[16:17]
	s_mov_b32 m0, s30
	s_nop 0
	global_load_lds_dwordx4 v[166:167], off
	v_lshl_add_u64 v[166:167], v[224:225], 0, s[16:17]
	s_add_i32 m0, s30, 0x2000
	s_nop 0
	global_load_lds_dwordx4 v[166:167], off
	v_lshl_add_u64 v[166:167], v[226:227], 0, s[16:17]
	s_mov_b32 m0, s45
	s_nop 0
	global_load_lds_dwordx4 v[166:167], off
	v_lshl_add_u64 v[166:167], v[228:229], 0, s[16:17]
	s_mov_b32 m0, s46
	s_nop 0
	global_load_lds_dwordx4 v[166:167], off
	s_waitcnt vmcnt(8)
	s_waitcnt lgkmcnt(0)
	s_barrier
	s_setprio 1
	s_waitcnt lgkmcnt(0)
	v_mfma_f32_16x16x32_bf16 v[60:63], v[146:149], v[186:189], v[60:63]
	v_mfma_f32_16x16x32_bf16 v[56:59], v[154:157], v[186:189], v[56:59]
	v_mfma_f32_16x16x32_bf16 v[44:47], v[146:149], v[194:197], v[44:47]
	v_mfma_f32_16x16x32_bf16 v[40:43], v[154:157], v[194:197], v[40:43]
	v_mfma_f32_16x16x32_bf16 v[28:31], v[146:149], v[206:209], v[28:31]
	v_mfma_f32_16x16x32_bf16 v[24:27], v[154:157], v[206:209], v[24:27]
	v_mfma_f32_16x16x32_bf16 v[12:15], v[146:149], v[214:217], v[12:15]
	v_mfma_f32_16x16x32_bf16 v[8:11], v[154:157], v[214:217], v[8:11]
	v_mfma_f32_16x16x32_bf16 v[60:63], v[150:153], v[190:193], v[60:63]
	v_mfma_f32_16x16x32_bf16 v[56:59], v[158:161], v[190:193], v[56:59]
	v_mfma_f32_16x16x32_bf16 v[44:47], v[150:153], v[202:205], v[44:47]
	v_mfma_f32_16x16x32_bf16 v[40:43], v[158:161], v[202:205], v[40:43]
	v_mfma_f32_16x16x32_bf16 v[28:31], v[150:153], v[210:213], v[28:31]
	v_mfma_f32_16x16x32_bf16 v[24:27], v[158:161], v[210:213], v[24:27]
	v_mfma_f32_16x16x32_bf16 v[12:15], v[150:153], v[218:221], v[12:15]
	v_mfma_f32_16x16x32_bf16 v[8:11], v[158:161], v[218:221], v[8:11]
	s_setprio 0
	s_setprio 1
	v_mfma_f32_16x16x32_bf16 v[52:55], v[162:165], v[186:189], v[52:55]
	v_mfma_f32_16x16x32_bf16 v[48:51], v[178:181], v[186:189], v[48:51]
	v_mfma_f32_16x16x32_bf16 v[36:39], v[162:165], v[194:197], v[36:39]
	v_mfma_f32_16x16x32_bf16 v[32:35], v[178:181], v[194:197], v[32:35]
	v_mfma_f32_16x16x32_bf16 v[20:23], v[162:165], v[206:209], v[20:23]
	v_mfma_f32_16x16x32_bf16 v[16:19], v[178:181], v[206:209], v[16:19]
	v_mfma_f32_16x16x32_bf16 v[0:3], v[162:165], v[214:217], v[0:3]
	v_mfma_f32_16x16x32_bf16 v[4:7], v[178:181], v[214:217], v[4:7]
	v_mfma_f32_16x16x32_bf16 v[52:55], v[174:177], v[190:193], v[52:55]
	v_mfma_f32_16x16x32_bf16 v[48:51], v[182:185], v[190:193], v[48:51]
	v_mfma_f32_16x16x32_bf16 v[36:39], v[174:177], v[202:205], v[36:39]
	v_mfma_f32_16x16x32_bf16 v[32:35], v[182:185], v[202:205], v[32:35]
	v_mfma_f32_16x16x32_bf16 v[20:23], v[174:177], v[210:213], v[20:23]
	v_mfma_f32_16x16x32_bf16 v[16:19], v[182:185], v[210:213], v[16:19]
	v_mfma_f32_16x16x32_bf16 v[0:3], v[174:177], v[218:221], v[0:3]
	v_mfma_f32_16x16x32_bf16 v[4:7], v[182:185], v[218:221], v[4:7]
	s_setprio 0
	s_barrier
	s_add_u32 s6, s6, 0x100
	s_addc_u32 s7, s7, 0
	s_add_u32 s58, s58, 0x100
	s_addc_u32 s59, s59, 0
	s_cmp_ge_i32 s60, s47
	s_mov_b32 s30, s60
	s_cbranch_scc1 .LBB0_713

;     __device__ __forceinline__ void operator()(const AccT& acc, const Unit& u, int wr, int wc, int fr_, int fq_) const {
;         int fr = fr_, fq = fq_; asm volatile("" : "+v"(fr), "+v"(fq));
;         const int pn = u.pn;
;         bf16_t* const KN = (bf16_t*)(ws + WS_RA); bf16_t* const VI = (bf16_t*)(ws + WS_VIMG); const float* const ssq_kv = (const float*)(ws + WS_SSQ) + T;
;         float ssv[2][4];
; #pragma unroll
;         for (int ai = 0; ai < 2; ++ai)
; #pragma unroll
;             for (int m = 0; m < 4; ++m) ssv[ai][m] = ssq_kv[(size_t)ROW_OF(ai, m)];
; #pragma unroll
;         for (int ai = 0; ai < 2; ++ai)
; #pragma unroll
;             for (int m = 0; m < 4; ++m) {
;                 const size_t row = (size_t)ROW_OF(ai, m);
;                 const float sc = __builtin_amdgcn_rsqf(ssv[ai][m] * (1.0f / KVLORA) + EPS);
;                 const int b = (int)(row >> 11), s = (int)(row & 2047);
;                 const f32x4 a0 = acc[ai][0][m][0] * sc, a1 = acc[ai][0][m][1] * sc, b0 = acc[ai][1][m][0] * sc, b1 = acc[ai][1][m][1] * sc;
.LBB0_715:
	s_mov_b32 s99, 1
	s_lshl_b32 s6, s35, 8
	v_mov_b32_e32 v167, v201
	v_mov_b32_e32 v173, v232
	s_add_i32 s6, s6, s48
	s_cmp_gt_i32 s34, 3
	v_add_u32_e32 v162, s6, v167
	v_ashrrev_i32_e32 v163, 31, v162
	v_lshl_add_u64 v[146:147], v[162:163], 2, s[24:25]
	v_add_u32_e32 v160, 16, v162
	v_mov_b32_e32 v166, v245
	v_ashrrev_i32_e32 v161, 31, v160
	v_add_u32_e32 v158, 32, v162
	v_add_u32_e32 v156, 48, v162
	v_add_u32_e32 v154, 0x80, v162
	v_add_u32_e32 v152, 0x90, v162
	v_add_u32_e32 v150, 0xa0, v162
	v_add_u32_e32 v146, 0xb0, v162
	v_lshl_add_u64 v[148:149], v[160:161], 2, s[24:25]
	v_ashrrev_i32_e32 v159, 31, v158
	v_ashrrev_i32_e32 v157, 31, v156
	v_ashrrev_i32_e32 v155, 31, v154
	v_ashrrev_i32_e32 v153, 31, v152
	v_ashrrev_i32_e32 v151, 31, v150
	v_ashrrev_i32_e32 v147, 31, v146
	v_lshl_add_u64 v[164:165], v[158:159], 2, s[24:25]
	v_lshl_add_u64 v[174:175], v[156:157], 2, s[24:25]
	v_lshl_add_u64 v[176:177], v[154:155], 2, s[24:25]
	v_lshl_add_u64 v[178:179], v[152:153], 2, s[24:25]
	v_lshl_add_u64 v[180:181], v[150:151], 2, s[24:25]
	v_lshl_add_u64 v[182:183], v[146:147], 2, s[24:25]
	v_mov_b32_e32 v161, v246
	v_mov_b32_e32 v159, v247
	v_mov_b32_e32 v157, v248
	v_mov_b32_e32 v155, v249
	v_mov_b32_e32 v153, v250
	v_mov_b32_e32 v151, v251
	v_mov_b32_e32 v147, v252
	v_lshlrev_b32_e32 v136, 6, v167
	v_lshlrev_b32_e32 v148, 3, v173
	v_and_b32_e32 v136, 0x1c0, v136
	s_cselect_b64 s[30:31], -1, 0
	s_lshl_b32 s58, s34, 9
	v_ashrrev_i32_e32 v149, 31, v148
	v_lshl_add_u64 v[174:175], s[26:27], 0, v[136:137]
	s_mov_b64 s[6:7], -1
	v_and_b32_e32 v163, 0x7ff, v162
	s_addk_i32 s58, 0xf800
	s_and_b64 vcc, exec, s[30:31]
	v_lshl_add_u64 v[148:149], v[148:149], 1, v[174:175]
	v_lshl_add_u32 v253, s57, 8, v201
	v_add_lshl_u32 v253, v253, s48, 2
	global_load_dword v245, v253, s[24:25]
	global_load_dword v246, v253, s[24:25] offset:64
	global_load_dword v247, v253, s[24:25] offset:128
	global_load_dword v248, v253, s[24:25] offset:192
	global_load_dword v249, v253, s[24:25] offset:512
	global_load_dword v250, v253, s[24:25] offset:576
	global_load_dword v251, v253, s[24:25] offset:640
	global_load_dword v252, v253, s[24:25] offset:704
	s_waitcnt vmcnt(8)
	v_fmamk_f32 v166, v166, 0x3b800000, v172
	v_rsq_f32_e32 v166, v166
	s_nop 0
	v_pk_mul_f32 v[122:123], v[122:123], v[166:167] op_sel_hi:[1,0]
	v_pk_mul_f32 v[120:121], v[120:121], v[166:167] op_sel_hi:[1,0]
	v_pk_mul_f32 v[126:127], v[126:127], v[166:167] op_sel_hi:[1,0]
	v_pk_mul_f32 v[124:125], v[124:125], v[166:167] op_sel_hi:[1,0]
	v_cvt_pk_bf16_f32 v120, v120, v121
	v_cvt_pk_bf16_f32 v121, v122, v123
	v_cvt_pk_bf16_f32 v122, v124, v125
	v_cvt_pk_bf16_f32 v123, v126, v127
	s_cbranch_vccz .LBB0_717
	v_and_b32_e32 v124, 0xfffff800, v162
	v_add_u32_e32 v124, s58, v124
	v_lshrrev_b32_e32 v125, 3, v163
	v_or_b32_e32 v124, v124, v125
	v_ashrrev_i32_e32 v125, 31, v124
	v_lshlrev_b64 v[124:125], 11, v[124:125]
	v_lshl_add_u64 v[164:165], v[148:149], 0, v[124:125]
	global_store_dwordx4 v[164:165], v[120:123], off nt
	s_mov_b64 s[6:7], 0

; #define PG8_STAGE(bufoff, gbase, voff) do { _Pragma("unroll") for (int _i = 0; _i < 2; ++_i) \
;         __builtin_amdgcn_global_load_lds((const unsigned*)((const char*)(gbase) + (voff)[_i]), (PG8_LAS unsigned*)(lds + (bufoff) + ldsw + _i * 8192), 16, 0, 0); } while (0)
; #define PG8_WAIT_V(n) asm volatile("s_waitcnt vmcnt(" #n ")" ::: "memory")
; #define PG8_BAR __builtin_amdgcn_s_barrier()
; template <class Epi, class Sched, bool ALIGN_EPI = false, bool SP2 = false>
; __device__ __forceinline__ void gemm_phase(PG8_LAS unsigned char* lds, const Gemm g, const Sched& S, const Epi& E) {
;     ...
;         PG8_STAGE(PG8_SB(1, 0), cB + kstep, voffB); PG8_STAGE(PG8_SA(1, 0), cA + kstep, voffA); PG8_STAGE(PG8_SB(1, 1), cB + hstep + kstep, voffB);
;         PG8_WAIT_V(6); PG8_BAR;
.LBB0_760:
	s_mov_b64 s[14:15], 0x80
	s_add_i32 m0, s37, 0x18000
	v_lshl_add_u64 v[8:9], v[8:9], 0, s[14:15]
	s_waitcnt vmcnt(2)
	s_barrier
	global_load_lds_dwordx4 v[8:9], off
	v_lshl_add_u64 v[4:5], v[4:5], 0, s[14:15]
	s_add_i32 m0, s37, 0x1a000
	s_add_i32 s42, s37, 0x8000
	global_load_lds_dwordx4 v[4:5], off
	v_lshl_add_u64 v[4:5], v[6:7], 0, s[14:15]
	s_mov_b32 m0, s42
	s_add_i32 s43, s37, 0xa000
	global_load_lds_dwordx4 v[4:5], off
	v_lshl_add_u64 v[4:5], v[10:11], 0, s[14:15]
	s_mov_b32 m0, s43
	v_lshl_add_u64 v[2:3], v[2:3], 0, s[14:15]
	global_load_lds_dwordx4 v[4:5], off
	s_add_i32 m0, s37, 0x1c000
	v_lshl_add_u64 v[0:1], v[0:1], 0, s[14:15]
	global_load_lds_dwordx4 v[2:3], off
	s_add_i32 m0, s37, 0x1e000
	s_lshr_b32 s1, s1, 26
	global_load_lds_dwordx4 v[0:1], off
	s_add_i32 s1, s0, s1
	v_lshlrev_b32_e32 v1, 2, v201
	s_ashr_i32 s44, s1, 6
	v_lshl_or_b32 v0, v201, 6, v238
	s_lshl_b32 s1, s2, 13
	v_and_b32_e32 v1, 32, v1
	v_bitop3_b32 v2, v0, s1, v1 bitop3:0xde
	s_lshl_b32 s1, s3, 5
	s_lshl_b32 s45, s2, 6
	s_and_b32 s46, s1, 0x60
	s_cmp_gt_i32 s0, 63
	s_cselect_b64 s[16:17], -1, 0
	s_add_i32 s47, s44, -2
	s_cmpk_lt_u32 s18, 0x100
	s_cselect_b64 s[18:19], -1, 0
	s_add_u32 s20, s90, 0x9000000
	v_add_u32_e32 v0, v237, v235
	s_addc_u32 s21, s91, 0
	v_mul_lo_u32 v0, s0, v0
	s_add_u32 s22, s90, 0xd000000
	v_readlane_b32 s48, v254, 23
	v_lshlrev_b32_e32 v0, 1, v0
	s_addc_u32 s23, s91, 0
	v_readlane_b32 s62, v254, 37
	v_add3_u32 v0, v233, v0, v234
	v_mov_b32_e32 v1, v205
	v_readlane_b32 s63, v254, 38
	s_add_u32 s24, s62, 0x1000
	v_lshl_add_u64 v[210:211], s[4:5], 0, v[0:1]
	v_add_u32_e32 v0, v236, v235
	s_addc_u32 s25, s63, 0
	v_mul_lo_u32 v0, s0, v0
	s_waitcnt vmcnt(6)
	v_readlane_b32 s50, v254, 25
	v_readlane_b32 s51, v254, 26
	s_add_u32 s26, s62, 0x2000
	v_lshlrev_b32_e32 v0, 1, v0
	v_lshl_or_b32 v245, s46, 7, v239
	v_readlane_b32 s49, v254, 24
	s_addc_u32 s27, s63, 0
	v_add3_u32 v0, v233, v0, v234
	s_add_i32 s50, 0, 0x10000
	s_add_i32 s51, 0, 0x14000
	v_readlane_b32 s52, v254, 27
	v_readlane_b32 s53, v254, 28
	s_ashr_i32 s48, s83, 31
	s_ashr_i32 s49, s80, 31
	v_lshl_add_u64 v[212:213], s[4:5], 0, v[0:1]
	v_mov_b64_e32 v[214:215], 0x400
	v_mov_b64_e32 v[216:217], 0x3ff
	v_add_u32_e32 v246, s50, v245
	v_add_u32_e32 v247, s51, v245
	v_add_u32_e32 v248, 0, v2
	s_barrier
	v_readlane_b32 s54, v254, 29
	v_readlane_b32 s55, v254, 30
	v_readlane_b32 s56, v254, 31
	v_readlane_b32 s57, v254, 32
	v_readlane_b32 s58, v254, 33
	v_readlane_b32 s59, v254, 34
	v_readlane_b32 s60, v254, 35
	v_readlane_b32 s61, v254, 36
	s_mov_b32 s99, 0
	s_branch .LBB0_763

; #define PG8_STAGE(bufoff, gbase, voff) do { _Pragma("unroll") for (int _i = 0; _i < 2; ++_i) \
;         __builtin_amdgcn_global_load_lds((const unsigned*)((const char*)(gbase) + (voff)[_i]), (PG8_LAS unsigned*)(lds + (bufoff) + ldsw + _i * 8192), 16, 0, 0); } while (0)
; #define PG8_LDA(dst, b, h) do { _Pragma("unroll") for (int m = 0; m < 4; ++m) _Pragma("unroll") for (int k = 0; k < 2; ++k) dst[m][k] = *(const PG8_LAS bf16x8*)(lds + PG8_SA(b, h) + aoff + m * 2048 + k * 1024); } while (0)
; #define PG8_LDB(dst, b, h) do { _Pragma("unroll") for (int n = 0; n < 2; ++n) _Pragma("unroll") for (int k = 0; k < 2; ++k) dst[n][k] = *(const PG8_LAS bf16x8*)(lds + PG8_SB(b, h) + boff + n * 2048 + k * 1024); } while (0)
; #define PG8_MMA(ai, bj, At, Bt) do { __builtin_amdgcn_s_setprio(1); _Pragma("unroll") for (int m = 0; m < 4; ++m) _Pragma("unroll") for (int n = 0; n < 2; ++n) _Pragma("unroll") for (int k = 0; k < 2; ++k) \
;         acc[ai][bj][m][n] = __builtin_amdgcn_mfma_f32_16x16x32_bf16(Bt[n][k], At[m][k], acc[ai][bj][m][n], 0, 0, 0); __builtin_amdgcn_s_setprio(0); } while (0)
; #define PG8_WAIT_V(n) asm volatile("s_waitcnt vmcnt(" #n ")" ::: "memory")
; #define PG8_WAIT_L(n) asm volatile("s_waitcnt lgkmcnt(" #n ")" ::: "memory")
; #define PG8_BAR __builtin_amdgcn_s_barrier()
; #define PG8_SCHED __builtin_amdgcn_sched_barrier(0)
; template <class Epi, class Sched, bool ALIGN_EPI = false, bool SP2 = false>
; __device__ __forceinline__ void gemm_phase(PG8_LAS unsigned char* lds, const Gemm g, const Sched& S, const Epi& E) {
;     ...
;             PG8_LDB(B0, 0, 0); PG8_LDB(B1, 0, 1); PG8_SCHED; PG8_LDA(At, 0, 0); PG8_STAGE(PG8_SA(1, 1), a1 + hstep, voffA);
;             PG8_WAIT_V(8); PG8_WAIT_L(0); PG8_BAR; PG8_MMA(0, 0, At, B0); PG8_MMA(0, 1, At, B1); PG8_BAR; PG8_SCHED;
.LBB0_773:
	s_andn2_b64 vcc, exec, s[16:17]
	s_cbranch_vccnz .LBB0_776
	s_add_u32 s10, s10, 0x80
	s_addc_u32 s11, s11, 0
	s_add_u32 s55, s30, 0x100
	s_addc_u32 s56, s31, 0
	s_mov_b32 s30, 0
	ds_read_b128 v[80:83], v246
	ds_read_b128 v[84:87], v246 offset:1024
	ds_read_b128 v[88:91], v246 offset:2048
	ds_read_b128 v[92:95], v246 offset:3072
	ds_read_b128 v[96:99], v247
	ds_read_b128 v[100:103], v247 offset:1024
	ds_read_b128 v[152:155], v247 offset:2048
	ds_read_b128 v[156:159], v247 offset:3072
	s_add_i32 s57, s30, 2
	s_add_u32 s58, s10, 0x80
	s_addc_u32 s31, s11, 0
	s_cmp_eq_u32 s47, s30
	s_cselect_b32 s30, s0, s58
	s_cselect_b32 s31, s1, s31
	s_cselect_b32 s59, s29, s56
	s_cselect_b32 s58, s28, s55
	v_lshl_add_u64 v[192:193], s[10:11], 0, v[210:211]
	s_add_i32 m0, s37, 0xc000
	ds_read_b128 v[160:163], v248
	ds_read_b128 v[164:167], v248 offset:1024
	ds_read_b128 v[168:171], v248 offset:2048
	ds_read_b128 v[172:175], v248 offset:3072
	ds_read_b128 v[176:179], v248 offset:4096
	ds_read_b128 v[180:183], v248 offset:5120
	ds_read_b128 v[184:187], v248 offset:6144
	ds_read_b128 v[188:191], v248 offset:7168
	global_load_lds_dwordx4 v[192:193], off
	v_lshl_add_u64 v[192:193], s[10:11], 0, v[212:213]
	s_add_i32 m0, s37, 0xe000
	s_nop 0
	global_load_lds_dwordx4 v[192:193], off
	s_cmp_eq_u32 s99, 0
	s_cbranch_scc1 .Lw8_2_0
	s_waitcnt vmcnt(16)
	s_branch .Lwj_2_0

; #define PG8_STAGE(bufoff, gbase, voff) do { _Pragma("unroll") for (int _i = 0; _i < 2; ++_i) \
;         __builtin_amdgcn_global_load_lds((const unsigned*)((const char*)(gbase) + (voff)[_i]), (PG8_LAS unsigned*)(lds + (bufoff) + ldsw + _i * 8192), 16, 0, 0); } while (0)
; #define PG8_LDA(dst, b, h) do { _Pragma("unroll") for (int m = 0; m < 4; ++m) _Pragma("unroll") for (int k = 0; k < 2; ++k) dst[m][k] = *(const PG8_LAS bf16x8*)(lds + PG8_SA(b, h) + aoff + m * 2048 + k * 1024); } while (0)
; #define PG8_MMA(ai, bj, At, Bt) do { __builtin_amdgcn_s_setprio(1); _Pragma("unroll") for (int m = 0; m < 4; ++m) _Pragma("unroll") for (int n = 0; n < 2; ++n) _Pragma("unroll") for (int k = 0; k < 2; ++k) \
;         acc[ai][bj][m][n] = __builtin_amdgcn_mfma_f32_16x16x32_bf16(Bt[n][k], At[m][k], acc[ai][bj][m][n], 0, 0, 0); __builtin_amdgcn_s_setprio(0); } while (0)
; #define PG8_WAIT_V(n) asm volatile("s_waitcnt vmcnt(" #n ")" ::: "memory")
; #define PG8_WAIT_L(n) asm volatile("s_waitcnt lgkmcnt(" #n ")" ::: "memory")
; #define PG8_BAR __builtin_amdgcn_s_barrier()
; #define PG8_SCHED __builtin_amdgcn_sched_barrier(0)
; template <class Epi, class Sched, bool ALIGN_EPI = false, bool SP2 = false>
; __device__ __forceinline__ void gemm_phase(PG8_LAS unsigned char* lds, const Gemm g, const Sched& S, const Epi& E) {
;     ...
;             PG8_WAIT_V(8); PG8_WAIT_L(0); PG8_BAR; PG8_MMA(0, 0, At, B0); PG8_MMA(0, 1, At, B1); PG8_BAR; PG8_SCHED;
;             PG8_LDA(At, 0, 1); PG8_STAGE(PG8_SB(0, 0), b2, voffB); PG8_STAGE(PG8_SB(0, 1), b2 + hstep, voffB); PG8_STAGE(PG8_SA(0, 0), a2, voffA);
;             PG8_WAIT_V(8); PG8_WAIT_L(0); PG8_BAR; PG8_MMA(1, 0, At, B0); PG8_MMA(1, 1, At, B1); PG8_BAR; PG8_SCHED;
.Lwj_2_0:
	s_waitcnt lgkmcnt(0)
	s_barrier
	s_setprio 1
	s_waitcnt lgkmcnt(0)
	v_mfma_f32_16x16x32_bf16 v[144:147], v[80:83], v[160:163], 0
	v_mfma_f32_16x16x32_bf16 v[136:139], v[88:91], v[160:163], 0
	v_mfma_f32_16x16x32_bf16 v[128:131], v[80:83], v[168:171], 0
	v_mfma_f32_16x16x32_bf16 v[120:123], v[88:91], v[168:171], 0
	v_mfma_f32_16x16x32_bf16 v[112:115], v[80:83], v[176:179], 0
	v_mfma_f32_16x16x32_bf16 v[104:107], v[88:91], v[176:179], 0
	v_mfma_f32_16x16x32_bf16 v[72:75], v[80:83], v[184:187], 0
	v_mfma_f32_16x16x32_bf16 v[64:67], v[88:91], v[184:187], 0
	v_mfma_f32_16x16x32_bf16 v[144:147], v[84:87], v[164:167], v[144:147]
	v_mfma_f32_16x16x32_bf16 v[136:139], v[92:95], v[164:167], v[136:139]
	v_mfma_f32_16x16x32_bf16 v[128:131], v[84:87], v[172:175], v[128:131]
	v_mfma_f32_16x16x32_bf16 v[120:123], v[92:95], v[172:175], v[120:123]
	v_mfma_f32_16x16x32_bf16 v[112:115], v[84:87], v[180:183], v[112:115]
	v_mfma_f32_16x16x32_bf16 v[104:107], v[92:95], v[180:183], v[104:107]
	v_mfma_f32_16x16x32_bf16 v[72:75], v[84:87], v[188:191], v[72:75]
	v_mfma_f32_16x16x32_bf16 v[64:67], v[92:95], v[188:191], v[64:67]
	s_setprio 0
	s_setprio 1
	v_mfma_f32_16x16x32_bf16 v[148:151], v[96:99], v[160:163], 0
	v_mfma_f32_16x16x32_bf16 v[140:143], v[152:155], v[160:163], 0
	v_mfma_f32_16x16x32_bf16 v[132:135], v[96:99], v[168:171], 0
	v_mfma_f32_16x16x32_bf16 v[124:127], v[152:155], v[168:171], 0
	v_mfma_f32_16x16x32_bf16 v[116:119], v[96:99], v[176:179], 0
	v_mfma_f32_16x16x32_bf16 v[108:111], v[152:155], v[176:179], 0
	v_mfma_f32_16x16x32_bf16 v[76:79], v[96:99], v[184:187], 0
	v_mfma_f32_16x16x32_bf16 v[68:71], v[152:155], v[184:187], 0
	v_mfma_f32_16x16x32_bf16 v[148:151], v[100:103], v[164:167], v[148:151]
	v_mfma_f32_16x16x32_bf16 v[140:143], v[156:159], v[164:167], v[140:143]
	v_mfma_f32_16x16x32_bf16 v[132:135], v[100:103], v[172:175], v[132:135]
	v_mfma_f32_16x16x32_bf16 v[124:127], v[156:159], v[172:175], v[124:127]
	v_mfma_f32_16x16x32_bf16 v[116:119], v[100:103], v[180:183], v[116:119]
	v_mfma_f32_16x16x32_bf16 v[108:111], v[156:159], v[180:183], v[108:111]
	v_mfma_f32_16x16x32_bf16 v[76:79], v[100:103], v[188:191], v[76:79]
	v_mfma_f32_16x16x32_bf16 v[68:71], v[156:159], v[188:191], v[68:71]
	s_setprio 0
	s_barrier
	s_add_i32 s60, s50, s36
	v_lshl_add_u64 v[192:193], s[58:59], 0, v[204:205]
	s_mov_b32 m0, s60
	ds_read_b128 v[160:163], v248 offset:16384
	ds_read_b128 v[164:167], v248 offset:17408
	ds_read_b128 v[168:171], v248 offset:18432
	ds_read_b128 v[172:175], v248 offset:19456
	ds_read_b128 v[176:179], v248 offset:20480
	ds_read_b128 v[180:183], v248 offset:21504
	ds_read_b128 v[184:187], v248 offset:22528
	ds_read_b128 v[188:191], v248 offset:23552
	global_load_lds_dwordx4 v[192:193], off
	s_add_i32 m0, s60, 0x2000
	v_lshl_add_u64 v[194:195], s[58:59], 0, v[208:209]
	s_add_u32 s58, s58, s4
	s_addc_u32 s59, s59, s5
	s_add_i32 s60, s51, s36
	global_load_lds_dwordx4 v[194:195], off
	v_lshl_add_u64 v[196:197], s[58:59], 0, v[204:205]
	s_mov_b32 m0, s60
	v_lshl_add_u64 v[198:199], s[58:59], 0, v[208:209]
	global_load_lds_dwordx4 v[196:197], off
	s_add_i32 m0, s60, 0x2000
	v_lshl_add_u64 v[218:219], s[30:31], 0, v[202:203]
	global_load_lds_dwordx4 v[198:199], off
	s_mov_b32 m0, s37
	v_lshl_add_u64 v[220:221], s[30:31], 0, v[206:207]
	global_load_lds_dwordx4 v[218:219], off
	s_mov_b32 m0, s38
	s_nop 0
	global_load_lds_dwordx4 v[220:221], off
	s_cmp_eq_u32 s99, 0
	s_cbranch_scc1 .Lw8_2_1
	s_waitcnt vmcnt(16)
	s_branch .Lwj_2_1

; #define PG8_STAGE(bufoff, gbase, voff) do { _Pragma("unroll") for (int _i = 0; _i < 2; ++_i) \
;         __builtin_amdgcn_global_load_lds((const unsigned*)((const char*)(gbase) + (voff)[_i]), (PG8_LAS unsigned*)(lds + (bufoff) + ldsw + _i * 8192), 16, 0, 0); } while (0)
; #define PG8_LDA(dst, b, h) do { _Pragma("unroll") for (int m = 0; m < 4; ++m) _Pragma("unroll") for (int k = 0; k < 2; ++k) dst[m][k] = *(const PG8_LAS bf16x8*)(lds + PG8_SA(b, h) + aoff + m * 2048 + k * 1024); } while (0)
; #define PG8_LDB(dst, b, h) do { _Pragma("unroll") for (int n = 0; n < 2; ++n) _Pragma("unroll") for (int k = 0; k < 2; ++k) dst[n][k] = *(const PG8_LAS bf16x8*)(lds + PG8_SB(b, h) + boff + n * 2048 + k * 1024); } while (0)
; #define PG8_MMA(ai, bj, At, Bt) do { __builtin_amdgcn_s_setprio(1); _Pragma("unroll") for (int m = 0; m < 4; ++m) _Pragma("unroll") for (int n = 0; n < 2; ++n) _Pragma("unroll") for (int k = 0; k < 2; ++k) \
;         acc[ai][bj][m][n] = __builtin_amdgcn_mfma_f32_16x16x32_bf16(Bt[n][k], At[m][k], acc[ai][bj][m][n], 0, 0, 0); __builtin_amdgcn_s_setprio(0); } while (0)
; #define PG8_WAIT_V(n) asm volatile("s_waitcnt vmcnt(" #n ")" ::: "memory")
; #define PG8_WAIT_L(n) asm volatile("s_waitcnt lgkmcnt(" #n ")" ::: "memory")
; #define PG8_BAR __builtin_amdgcn_s_barrier()
; #define PG8_SCHED __builtin_amdgcn_sched_barrier(0)
; template <class Epi, class Sched, bool ALIGN_EPI = false, bool SP2 = false>
; __device__ __forceinline__ void gemm_phase(PG8_LAS unsigned char* lds, const Gemm g, const Sched& S, const Epi& E) {
;     ...
;             PG8_WAIT_V(8); PG8_WAIT_L(0); PG8_BAR; PG8_MMA(1, 0, At, B0); PG8_MMA(1, 1, At, B1); PG8_BAR; PG8_SCHED;
;             PG8_LDB(B0, 1, 0); PG8_LDB(B1, 1, 1); PG8_SCHED; PG8_LDA(At, 1, 0); PG8_STAGE(PG8_SA(0, 1), a2 + hstep, voffA);
;             PG8_WAIT_V(8); PG8_WAIT_L(0); PG8_BAR; PG8_MMA(0, 0, At, B0); PG8_MMA(0, 1, At, B1); PG8_BAR; PG8_SCHED;
.Lwj_2_1:
	s_waitcnt lgkmcnt(0)
	s_barrier
	s_setprio 1
	s_waitcnt lgkmcnt(0)
	v_mfma_f32_16x16x32_bf16 v[56:59], v[80:83], v[160:163], 0
	v_mfma_f32_16x16x32_bf16 v[48:51], v[88:91], v[160:163], 0
	v_mfma_f32_16x16x32_bf16 v[40:43], v[80:83], v[168:171], 0
	v_mfma_f32_16x16x32_bf16 v[32:35], v[88:91], v[168:171], 0
	v_mfma_f32_16x16x32_bf16 v[24:27], v[80:83], v[176:179], 0
	v_mfma_f32_16x16x32_bf16 v[16:19], v[88:91], v[176:179], 0
	v_mfma_f32_16x16x32_bf16 v[8:11], v[80:83], v[184:187], 0
	v_mfma_f32_16x16x32_bf16 v[0:3], v[88:91], v[184:187], 0
	v_mfma_f32_16x16x32_bf16 v[56:59], v[84:87], v[164:167], v[56:59]
	v_mfma_f32_16x16x32_bf16 v[48:51], v[92:95], v[164:167], v[48:51]
	v_mfma_f32_16x16x32_bf16 v[40:43], v[84:87], v[172:175], v[40:43]
	v_mfma_f32_16x16x32_bf16 v[32:35], v[92:95], v[172:175], v[32:35]
	v_mfma_f32_16x16x32_bf16 v[24:27], v[84:87], v[180:183], v[24:27]
	v_mfma_f32_16x16x32_bf16 v[16:19], v[92:95], v[180:183], v[16:19]
	v_mfma_f32_16x16x32_bf16 v[8:11], v[84:87], v[188:191], v[8:11]
	v_mfma_f32_16x16x32_bf16 v[0:3], v[92:95], v[188:191], v[0:3]
	s_setprio 0
	s_setprio 1
	v_mfma_f32_16x16x32_bf16 v[60:63], v[96:99], v[160:163], 0
	v_mfma_f32_16x16x32_bf16 v[52:55], v[152:155], v[160:163], 0
	v_mfma_f32_16x16x32_bf16 v[44:47], v[96:99], v[168:171], 0
	v_mfma_f32_16x16x32_bf16 v[36:39], v[152:155], v[168:171], 0
	v_mfma_f32_16x16x32_bf16 v[28:31], v[96:99], v[176:179], 0
	v_mfma_f32_16x16x32_bf16 v[20:23], v[152:155], v[176:179], 0
	v_mfma_f32_16x16x32_bf16 v[12:15], v[96:99], v[184:187], 0
	v_mfma_f32_16x16x32_bf16 v[4:7], v[152:155], v[184:187], 0
	v_mfma_f32_16x16x32_bf16 v[60:63], v[100:103], v[164:167], v[60:63]
	v_mfma_f32_16x16x32_bf16 v[52:55], v[156:159], v[164:167], v[52:55]
	v_mfma_f32_16x16x32_bf16 v[44:47], v[100:103], v[172:175], v[44:47]
	v_mfma_f32_16x16x32_bf16 v[36:39], v[156:159], v[172:175], v[36:39]
	v_mfma_f32_16x16x32_bf16 v[28:31], v[100:103], v[180:183], v[28:31]
	v_mfma_f32_16x16x32_bf16 v[20:23], v[156:159], v[180:183], v[20:23]
	v_mfma_f32_16x16x32_bf16 v[12:15], v[100:103], v[188:191], v[12:15]
	v_mfma_f32_16x16x32_bf16 v[4:7], v[156:159], v[188:191], v[4:7]
	s_setprio 0
	s_barrier
	s_add_i32 s58, 0, 0x18000
	s_add_i32 s59, 0, 0x1c000
	v_add_u32_e32 v92, s58, v245
	v_add_u32_e32 v156, s59, v245
	ds_read_b128 v[80:83], v92
	ds_read_b128 v[84:87], v92 offset:1024
	ds_read_b128 v[88:91], v92 offset:2048
	ds_read_b128 v[92:95], v92 offset:3072
	ds_read_b128 v[96:99], v156
	ds_read_b128 v[100:103], v156 offset:1024
	ds_read_b128 v[152:155], v156 offset:2048
	ds_read_b128 v[156:159], v156 offset:3072
	s_add_u32 s30, s30, s4
	s_addc_u32 s31, s31, s5
	s_mov_b32 m0, s39
	v_lshl_add_u64 v[222:223], s[30:31], 0, v[202:203]
	ds_read_b128 v[160:163], v248 offset:32768
	ds_read_b128 v[164:167], v248 offset:33792
	ds_read_b128 v[168:171], v248 offset:34816
	ds_read_b128 v[172:175], v248 offset:35840
	ds_read_b128 v[176:179], v248 offset:36864
	ds_read_b128 v[180:183], v248 offset:37888
	ds_read_b128 v[184:187], v248 offset:38912
	ds_read_b128 v[188:191], v248 offset:39936
	global_load_lds_dwordx4 v[222:223], off
	v_lshl_add_u64 v[222:223], s[30:31], 0, v[206:207]
	s_mov_b32 m0, s40
	s_nop 0
	global_load_lds_dwordx4 v[222:223], off
	s_waitcnt vmcnt(8)
	s_waitcnt lgkmcnt(0)
	s_barrier
	s_setprio 1
	s_waitcnt lgkmcnt(0)
	v_mfma_f32_16x16x32_bf16 v[144:147], v[80:83], v[160:163], v[144:147]
	v_mfma_f32_16x16x32_bf16 v[136:139], v[88:91], v[160:163], v[136:139]
	v_mfma_f32_16x16x32_bf16 v[128:131], v[80:83], v[168:171], v[128:131]
	v_mfma_f32_16x16x32_bf16 v[120:123], v[88:91], v[168:171], v[120:123]
	v_mfma_f32_16x16x32_bf16 v[112:115], v[80:83], v[176:179], v[112:115]
	v_mfma_f32_16x16x32_bf16 v[104:107], v[88:91], v[176:179], v[104:107]
	v_mfma_f32_16x16x32_bf16 v[72:75], v[80:83], v[184:187], v[72:75]
	v_mfma_f32_16x16x32_bf16 v[64:67], v[88:91], v[184:187], v[64:67]
	v_mfma_f32_16x16x32_bf16 v[144:147], v[84:87], v[164:167], v[144:147]
	v_mfma_f32_16x16x32_bf16 v[136:139], v[92:95], v[164:167], v[136:139]
	v_mfma_f32_16x16x32_bf16 v[128:131], v[84:87], v[172:175], v[128:131]
	v_mfma_f32_16x16x32_bf16 v[120:123], v[92:95], v[172:175], v[120:123]
	v_mfma_f32_16x16x32_bf16 v[112:115], v[84:87], v[180:183], v[112:115]
	v_mfma_f32_16x16x32_bf16 v[104:107], v[92:95], v[180:183], v[104:107]
	v_mfma_f32_16x16x32_bf16 v[72:75], v[84:87], v[188:191], v[72:75]
	v_mfma_f32_16x16x32_bf16 v[64:67], v[92:95], v[188:191], v[64:67]
	s_setprio 0
	s_setprio 1
	v_mfma_f32_16x16x32_bf16 v[148:151], v[96:99], v[160:163], v[148:151]
	v_mfma_f32_16x16x32_bf16 v[140:143], v[152:155], v[160:163], v[140:143]
	v_mfma_f32_16x16x32_bf16 v[132:135], v[96:99], v[168:171], v[132:135]
	v_mfma_f32_16x16x32_bf16 v[124:127], v[152:155], v[168:171], v[124:127]
	v_mfma_f32_16x16x32_bf16 v[116:119], v[96:99], v[176:179], v[116:119]
	v_mfma_f32_16x16x32_bf16 v[108:111], v[152:155], v[176:179], v[108:111]
	v_mfma_f32_16x16x32_bf16 v[76:79], v[96:99], v[184:187], v[76:79]
	v_mfma_f32_16x16x32_bf16 v[68:71], v[152:155], v[184:187], v[68:71]
	v_mfma_f32_16x16x32_bf16 v[148:151], v[100:103], v[164:167], v[148:151]
	v_mfma_f32_16x16x32_bf16 v[140:143], v[156:159], v[164:167], v[140:143]
	v_mfma_f32_16x16x32_bf16 v[132:135], v[100:103], v[172:175], v[132:135]
	v_mfma_f32_16x16x32_bf16 v[124:127], v[156:159], v[172:175], v[124:127]
	v_mfma_f32_16x16x32_bf16 v[116:119], v[100:103], v[180:183], v[116:119]
	v_mfma_f32_16x16x32_bf16 v[108:111], v[156:159], v[180:183], v[108:111]
	v_mfma_f32_16x16x32_bf16 v[76:79], v[100:103], v[188:191], v[76:79]
	v_mfma_f32_16x16x32_bf16 v[68:71], v[156:159], v[188:191], v[68:71]
	s_setprio 0
	s_barrier
; #define PG8_STAGE(bufoff, gbase, voff) do { _Pragma("unroll") for (int _i = 0; _i < 2; ++_i) \
;         __builtin_amdgcn_global_load_lds((const unsigned*)((const char*)(gbase) + (voff)[_i]), (PG8_LAS unsigned*)(lds + (bufoff) + ldsw + _i * 8192), 16, 0, 0); } while (0)
; #define PG8_LDA(dst, b, h) do { _Pragma("unroll") for (int m = 0; m < 4; ++m) _Pragma("unroll") for (int k = 0; k < 2; ++k) dst[m][k] = *(const PG8_LAS bf16x8*)(lds + PG8_SA(b, h) + aoff + m * 2048 + k * 1024); } while (0)
; #define PG8_MMA(ai, bj, At, Bt) do { __builtin_amdgcn_s_setprio(1); _Pragma("unroll") for (int m = 0; m < 4; ++m) _Pragma("unroll") for (int n = 0; n < 2; ++n) _Pragma("unroll") for (int k = 0; k < 2; ++k) \
;         acc[ai][bj][m][n] = __builtin_amdgcn_mfma_f32_16x16x32_bf16(Bt[n][k], At[m][k], acc[ai][bj][m][n], 0, 0, 0); __builtin_amdgcn_s_setprio(0); } while (0)
; #define PG8_WAIT_V(n) asm volatile("s_waitcnt vmcnt(" #n ")" ::: "memory")
; #define PG8_WAIT_L(n) asm volatile("s_waitcnt lgkmcnt(" #n ")" ::: "memory")
; #define PG8_BAR __builtin_amdgcn_s_barrier()
; #define PG8_SCHED __builtin_amdgcn_sched_barrier(0)
; template <class Epi, class Sched, bool ALIGN_EPI = false, bool SP2 = false>
; __device__ __forceinline__ void gemm_phase(PG8_LAS unsigned char* lds, const Gemm g, const Sched& S, const Epi& E) {
;     ...
;             PG8_LDA(At, 1, 1); PG8_STAGE(PG8_SB(1, 0), b3, voffB); PG8_STAGE(PG8_SB(1, 1), b3 + hstep, voffB); PG8_STAGE(PG8_SA(1, 0), a3, voffA);
;             PG8_WAIT_V(8); PG8_WAIT_L(0); PG8_BAR; PG8_MMA(1, 0, At, B0); PG8_MMA(1, 1, At, B1); PG8_BAR; PG8_SCHED;
	s_add_i32 s30, s58, s36
	v_lshl_add_u64 v[192:193], v[192:193], 0, s[14:15]
	s_mov_b32 m0, s30
	ds_read_b128 v[160:163], v248 offset:49152
	ds_read_b128 v[164:167], v248 offset:50176
	ds_read_b128 v[168:171], v248 offset:51200
	ds_read_b128 v[172:175], v248 offset:52224
	ds_read_b128 v[176:179], v248 offset:53248
	ds_read_b128 v[180:183], v248 offset:54272
	ds_read_b128 v[184:187], v248 offset:55296
	ds_read_b128 v[188:191], v248 offset:56320
	global_load_lds_dwordx4 v[192:193], off
	v_lshl_add_u64 v[192:193], v[194:195], 0, s[14:15]
	s_add_i32 m0, s30, 0x2000
	s_add_i32 s30, s59, s36
	global_load_lds_dwordx4 v[192:193], off
	v_lshl_add_u64 v[192:193], v[196:197], 0, s[14:15]
	s_mov_b32 m0, s30
	s_nop 0
	global_load_lds_dwordx4 v[192:193], off
	v_lshl_add_u64 v[192:193], v[198:199], 0, s[14:15]
	s_add_i32 m0, s30, 0x2000
	s_nop 0
	global_load_lds_dwordx4 v[192:193], off
	v_lshl_add_u64 v[192:193], v[218:219], 0, s[14:15]
	s_mov_b32 m0, s42
	s_nop 0
	global_load_lds_dwordx4 v[192:193], off
	v_lshl_add_u64 v[192:193], v[220:221], 0, s[14:15]
	s_mov_b32 m0, s43
	s_nop 0
	global_load_lds_dwordx4 v[192:193], off
	s_waitcnt vmcnt(8)
	s_waitcnt lgkmcnt(0)
	s_barrier
	s_setprio 1
	s_waitcnt lgkmcnt(0)
	v_mfma_f32_16x16x32_bf16 v[56:59], v[80:83], v[160:163], v[56:59]
	v_mfma_f32_16x16x32_bf16 v[48:51], v[88:91], v[160:163], v[48:51]
	v_mfma_f32_16x16x32_bf16 v[40:43], v[80:83], v[168:171], v[40:43]
	v_mfma_f32_16x16x32_bf16 v[32:35], v[88:91], v[168:171], v[32:35]
	v_mfma_f32_16x16x32_bf16 v[24:27], v[80:83], v[176:179], v[24:27]
	v_mfma_f32_16x16x32_bf16 v[16:19], v[88:91], v[176:179], v[16:19]
	v_mfma_f32_16x16x32_bf16 v[8:11], v[80:83], v[184:187], v[8:11]
	v_mfma_f32_16x16x32_bf16 v[0:3], v[88:91], v[184:187], v[0:3]
	v_mfma_f32_16x16x32_bf16 v[56:59], v[84:87], v[164:167], v[56:59]
	v_mfma_f32_16x16x32_bf16 v[48:51], v[92:95], v[164:167], v[48:51]
	v_mfma_f32_16x16x32_bf16 v[40:43], v[84:87], v[172:175], v[40:43]
	v_mfma_f32_16x16x32_bf16 v[32:35], v[92:95], v[172:175], v[32:35]
	v_mfma_f32_16x16x32_bf16 v[24:27], v[84:87], v[180:183], v[24:27]
	v_mfma_f32_16x16x32_bf16 v[16:19], v[92:95], v[180:183], v[16:19]
	v_mfma_f32_16x16x32_bf16 v[8:11], v[84:87], v[188:191], v[8:11]
	v_mfma_f32_16x16x32_bf16 v[0:3], v[92:95], v[188:191], v[0:3]
	s_setprio 0
	s_setprio 1
	v_mfma_f32_16x16x32_bf16 v[60:63], v[96:99], v[160:163], v[60:63]
	v_mfma_f32_16x16x32_bf16 v[52:55], v[152:155], v[160:163], v[52:55]
	v_mfma_f32_16x16x32_bf16 v[44:47], v[96:99], v[168:171], v[44:47]
	v_mfma_f32_16x16x32_bf16 v[36:39], v[152:155], v[168:171], v[36:39]
	v_mfma_f32_16x16x32_bf16 v[28:31], v[96:99], v[176:179], v[28:31]
	v_mfma_f32_16x16x32_bf16 v[20:23], v[152:155], v[176:179], v[20:23]
	v_mfma_f32_16x16x32_bf16 v[12:15], v[96:99], v[184:187], v[12:15]
	v_mfma_f32_16x16x32_bf16 v[4:7], v[152:155], v[184:187], v[4:7]
	v_mfma_f32_16x16x32_bf16 v[60:63], v[100:103], v[164:167], v[60:63]
	v_mfma_f32_16x16x32_bf16 v[52:55], v[156:159], v[164:167], v[52:55]
	v_mfma_f32_16x16x32_bf16 v[44:47], v[100:103], v[172:175], v[44:47]
	v_mfma_f32_16x16x32_bf16 v[36:39], v[156:159], v[172:175], v[36:39]
	v_mfma_f32_16x16x32_bf16 v[28:31], v[100:103], v[180:183], v[28:31]
	v_mfma_f32_16x16x32_bf16 v[20:23], v[156:159], v[180:183], v[20:23]
	v_mfma_f32_16x16x32_bf16 v[12:15], v[100:103], v[188:191], v[12:15]
	v_mfma_f32_16x16x32_bf16 v[4:7], v[156:159], v[188:191], v[4:7]
	s_setprio 0
	s_barrier
	s_add_u32 s10, s10, 0x100
	s_addc_u32 s11, s11, 0
	s_add_u32 s55, s55, 0x100
	s_addc_u32 s56, s56, 0
	s_cmp_ge_i32 s57, s44
	s_mov_b32 s30, s57
	s_cbranch_scc1 .LBB0_776

;     __device__ __forceinline__ void operator()(const AccT& acc, const Unit& u, int wr, int wc, int fr_, int fq_) const {
;         int fr = fr_, fq = fq_; asm volatile("" : "+v"(fr), "+v"(fq));
;         const int c0 = u.pn * 128 + wc * 32 + 8 * fq;
;         const bf16_t* const U = (const bf16_t*)(ws + WS_RB); bf16_t* const A2 = (bf16_t*)(ws + WS_A2);
;         const f32x4 w0a = *(const f32x4*)(conv_w + c0), w0b = *(const f32x4*)(conv_w + c0 + 4);
;         const f32x4 w1a = *(const f32x4*)(conv_w + 1024 + c0), w1b = *(const f32x4*)(conv_w + 1024 + c0 + 4);
;         const f32x4 w2a = *(const f32x4*)(conv_w + 2048 + c0), w2b = *(const f32x4*)(conv_w + 2048 + c0 + 4);
; #pragma unroll
;         for (int ai = 0; ai < 2; ++ai) {
;             u32x4 uu[4][3];
; #pragma unroll
;             for (int m = 0; m < 4; ++m) { const size_t row = (size_t)ROW_OF(ai, m); const int s = (int)(row & 2047); const u32x4 z4 = {0u, 0u, 0u, 0u};
;                 uu[m][2] = *(const u32x4*)(U + row * 1024 + c0);
;                 uu[m][1] = s >= 1 ? *(const u32x4*)(U + (row - 1) * 1024 + c0) : z4;
;                 uu[m][0] = s >= 2 ? *(const u32x4*)(U + (row - 2) * 1024 + c0) : z4; }
.LBB0_778:
	s_mov_b32 s99, 1
	s_lshl_b32 s10, s64, 7
	v_mov_b32_e32 v152, v201
	v_mov_b32_e32 v80, v232
	s_or_b32 s10, s10, s46
	v_readlane_b32 s56, v254, 23
	v_lshl_add_u32 v220, v80, 3, s10
	s_lshl_b32 s10, s33, 8
	s_add_i32 s10, s10, s45
	v_add_u32_e32 v222, s10, v152
	v_ashrrev_i32_e32 v221, 31, v220
	v_ashrrev_i32_e32 v223, 31, v222
	v_lshlrev_b64 v[80:81], 2, v[220:221]
	v_readlane_b32 s70, v254, 37
	v_readlane_b32 s71, v254, 38
	v_lshlrev_b64 v[152:153], 11, v[222:223]
	v_lshl_add_u64 v[152:153], s[20:21], 0, v[152:153]
	v_lshl_add_u64 v[82:83], s[70:71], 0, v[80:81]
	global_load_dwordx4 v[88:91], v[82:83], off offset:16
	global_load_dwordx4 v[100:103], v[82:83], off
	v_lshl_add_u64 v[82:83], s[24:25], 0, v[80:81]
	v_lshl_add_u64 v[92:93], s[26:27], 0, v[80:81]
	v_lshl_add_u64 v[152:153], v[220:221], 1, v[152:153]
	global_load_dwordx4 v[84:87], v[82:83], off offset:16
	global_load_dwordx4 v[96:99], v[82:83], off
	s_nop 0
	global_load_dwordx4 v[80:83], v[92:93], off offset:16
	s_nop 0
	global_load_dwordx4 v[92:95], v[92:93], off
	v_and_b32_e32 v154, 0x7ff, v222
	global_load_dwordx4 v[188:191], v[152:153], off
	v_mov_b32_e32 v196, 0
	v_cmp_ne_u32_e32 vcc, 0, v154
	v_mov_b32_e32 v192, 0
	v_mov_b32_e32 v193, 0
	v_mov_b32_e32 v194, 0
	v_mov_b32_e32 v195, 0
	v_readlane_b32 s57, v254, 24
	v_readlane_b32 s58, v254, 25
	v_readlane_b32 s59, v254, 26
	v_readlane_b32 s60, v254, 27
	v_readlane_b32 s61, v254, 28
	v_readlane_b32 s62, v254, 29
	v_readlane_b32 s63, v254, 30
	v_readlane_b32 s64, v254, 31
	v_readlane_b32 s65, v254, 32
	v_readlane_b32 s66, v254, 33
	v_readlane_b32 s67, v254, 34
	v_readlane_b32 s68, v254, 35
	v_readlane_b32 s69, v254, 36
	s_and_saveexec_b64 s[10:11], vcc
	s_cbranch_execz .LBB0_780
	global_load_dwordx4 v[192:195], v[152:153], off offset:-2048

; #define PG8_STAGE(bufoff, gbase, voff) do { _Pragma("unroll") for (int _i = 0; _i < 2; ++_i) \
;         __builtin_amdgcn_global_load_lds((const unsigned*)((const char*)(gbase) + (voff)[_i]), (PG8_LAS unsigned*)(lds + (bufoff) + ldsw + _i * 8192), 16, 0, 0); } while (0)
; #define PG8_WAIT_V(n) asm volatile("s_waitcnt vmcnt(" #n ")" ::: "memory")
; #define PG8_BAR __builtin_amdgcn_s_barrier()
; template <class Epi, class Sched, bool ALIGN_EPI = false, bool SP2 = false>
; __device__ __forceinline__ void gemm_phase(PG8_LAS unsigned char* lds, const Gemm g, const Sched& S, const Epi& E) {
;     ...
;         PG8_STAGE(PG8_SB(1, 0), cB + kstep, voffB); PG8_STAGE(PG8_SA(1, 0), cA + kstep, voffA); PG8_STAGE(PG8_SB(1, 1), cB + hstep + kstep, voffB);
;         PG8_WAIT_V(6); PG8_BAR;
.LBB0_825:
	s_mov_b64 s[16:17], 0x80
	s_add_i32 m0, s39, 0x18000
	v_lshl_add_u64 v[8:9], v[8:9], 0, s[16:17]
	s_waitcnt vmcnt(2)
	s_barrier
	global_load_lds_dwordx4 v[8:9], off
	v_lshl_add_u64 v[4:5], v[4:5], 0, s[16:17]
	s_add_i32 m0, s39, 0x1a000
	s_add_i32 s44, s39, 0x8000
	global_load_lds_dwordx4 v[4:5], off
	v_lshl_add_u64 v[4:5], v[6:7], 0, s[16:17]
	s_mov_b32 m0, s44
	s_add_i32 s45, s39, 0xa000
	global_load_lds_dwordx4 v[4:5], off
	v_lshl_add_u64 v[4:5], v[10:11], 0, s[16:17]
	s_mov_b32 m0, s45
	v_lshl_add_u64 v[2:3], v[2:3], 0, s[16:17]
	global_load_lds_dwordx4 v[4:5], off
	s_add_i32 m0, s39, 0x1c000
	v_lshl_add_u64 v[0:1], v[0:1], 0, s[16:17]
	global_load_lds_dwordx4 v[2:3], off
	s_add_i32 m0, s39, 0x1e000
	s_lshr_b32 s1, s1, 26
	global_load_lds_dwordx4 v[0:1], off
	s_add_i32 s1, s0, s1
	v_lshlrev_b32_e32 v1, 2, v201
	s_ashr_i32 s46, s1, 6
	v_lshl_or_b32 v0, v201, 6, v238
	s_lshl_b32 s1, s4, 13
	v_and_b32_e32 v1, 32, v1
	v_bitop3_b32 v2, v0, s1, v1 bitop3:0xde
	s_lshl_b32 s1, s5, 5
	s_lshl_b32 s47, s4, 6
	s_and_b32 s48, s1, 0x60
	s_cmp_gt_i32 s0, 63
	s_cselect_b64 s[18:19], -1, 0
	s_add_i32 s49, s46, -2
	s_cmpk_lt_u32 s20, 0x100
	s_cselect_b64 s[20:21], -1, 0
	s_add_u32 s22, s90, 0x9000000
	v_add_u32_e32 v0, v237, v235
	s_addc_u32 s23, s91, 0
	v_mul_lo_u32 v0, s0, v0
	s_add_u32 s24, s90, 0xd000000
	v_readlane_b32 s64, v254, 23
	v_lshlrev_b32_e32 v0, 1, v0
	s_addc_u32 s25, s91, 0
	v_readlane_b32 s78, v254, 37
	v_add3_u32 v0, v233, v0, v234
	v_mov_b32_e32 v1, v205
	v_readlane_b32 s79, v254, 38
	s_add_u32 s26, s78, 0x1000
	v_lshl_add_u64 v[210:211], s[6:7], 0, v[0:1]
	v_add_u32_e32 v0, v236, v235
	s_addc_u32 s27, s79, 0
	v_mul_lo_u32 v0, s0, v0
	s_waitcnt vmcnt(6)
	s_add_u32 s28, s78, 0x2000
	v_lshlrev_b32_e32 v0, 1, v0
	v_lshl_or_b32 v245, s48, 7, v239
	s_addc_u32 s29, s79, 0
	v_add3_u32 v0, v233, v0, v234
	s_add_i32 s52, 0, 0x10000
	s_add_i32 s53, 0, 0x14000
	s_ashr_i32 s50, s83, 31
	s_ashr_i32 s51, s80, 31
	v_lshl_add_u64 v[212:213], s[6:7], 0, v[0:1]
	v_mov_b64_e32 v[214:215], 0x400
	v_mov_b64_e32 v[216:217], 0x3ff
	v_add_u32_e32 v246, s52, v245
	v_add_u32_e32 v247, s53, v245
	v_add_u32_e32 v248, 0, v2
	s_barrier
	v_readlane_b32 s65, v254, 24
	v_readlane_b32 s66, v254, 25
	v_readlane_b32 s67, v254, 26
	v_readlane_b32 s68, v254, 27
	v_readlane_b32 s69, v254, 28
	v_readlane_b32 s70, v254, 29
	v_readlane_b32 s71, v254, 30
	v_readlane_b32 s72, v254, 31
	v_readlane_b32 s73, v254, 32
	v_readlane_b32 s74, v254, 33
	v_readlane_b32 s75, v254, 34
	v_readlane_b32 s76, v254, 35
	v_readlane_b32 s77, v254, 36
	s_mov_b32 s99, 0
	s_branch .LBB0_828

; #define PG8_STAGE(bufoff, gbase, voff) do { _Pragma("unroll") for (int _i = 0; _i < 2; ++_i) \
;         __builtin_amdgcn_global_load_lds((const unsigned*)((const char*)(gbase) + (voff)[_i]), (PG8_LAS unsigned*)(lds + (bufoff) + ldsw + _i * 8192), 16, 0, 0); } while (0)
; #define PG8_LDA(dst, b, h) do { _Pragma("unroll") for (int m = 0; m < 4; ++m) _Pragma("unroll") for (int k = 0; k < 2; ++k) dst[m][k] = *(const PG8_LAS bf16x8*)(lds + PG8_SA(b, h) + aoff + m * 2048 + k * 1024); } while (0)
; #define PG8_LDB(dst, b, h) do { _Pragma("unroll") for (int n = 0; n < 2; ++n) _Pragma("unroll") for (int k = 0; k < 2; ++k) dst[n][k] = *(const PG8_LAS bf16x8*)(lds + PG8_SB(b, h) + boff + n * 2048 + k * 1024); } while (0)
; #define PG8_MMA(ai, bj, At, Bt) do { __builtin_amdgcn_s_setprio(1); _Pragma("unroll") for (int m = 0; m < 4; ++m) _Pragma("unroll") for (int n = 0; n < 2; ++n) _Pragma("unroll") for (int k = 0; k < 2; ++k) \
;         acc[ai][bj][m][n] = __builtin_amdgcn_mfma_f32_16x16x32_bf16(Bt[n][k], At[m][k], acc[ai][bj][m][n], 0, 0, 0); __builtin_amdgcn_s_setprio(0); } while (0)
; #define PG8_WAIT_V(n) asm volatile("s_waitcnt vmcnt(" #n ")" ::: "memory")
; #define PG8_WAIT_L(n) asm volatile("s_waitcnt lgkmcnt(" #n ")" ::: "memory")
; #define PG8_BAR __builtin_amdgcn_s_barrier()
; #define PG8_SCHED __builtin_amdgcn_sched_barrier(0)
; template <class Epi, class Sched, bool ALIGN_EPI = false, bool SP2 = false>
; __device__ __forceinline__ void gemm_phase(PG8_LAS unsigned char* lds, const Gemm g, const Sched& S, const Epi& E) {
;     ...
;             PG8_LDB(B0, 0, 0); PG8_LDB(B1, 0, 1); PG8_SCHED; PG8_LDA(At, 0, 0); PG8_STAGE(PG8_SA(1, 1), a1 + hstep, voffA);
;             PG8_WAIT_V(8); PG8_WAIT_L(0); PG8_BAR; PG8_MMA(0, 0, At, B0); PG8_MMA(0, 1, At, B1); PG8_BAR; PG8_SCHED;
.LBB0_838:
	s_andn2_b64 vcc, exec, s[18:19]
	s_cbranch_vccnz .LBB0_841
	s_add_u32 s10, s10, 0x80
	s_addc_u32 s11, s11, 0
	s_add_u32 s57, s34, 0x100
	s_addc_u32 s58, s35, 0
	s_mov_b32 s34, 0
	ds_read_b128 v[80:83], v246
	ds_read_b128 v[84:87], v246 offset:1024
	ds_read_b128 v[88:91], v246 offset:2048
	ds_read_b128 v[92:95], v246 offset:3072
	ds_read_b128 v[96:99], v247
	ds_read_b128 v[100:103], v247 offset:1024
	ds_read_b128 v[152:155], v247 offset:2048
	ds_read_b128 v[156:159], v247 offset:3072
	s_add_i32 s59, s34, 2
	s_add_u32 s60, s10, 0x80
	s_addc_u32 s35, s11, 0
	s_cmp_eq_u32 s49, s34
	s_cselect_b32 s34, s0, s60
	s_cselect_b32 s35, s1, s35
	s_cselect_b32 s61, s31, s58
	s_cselect_b32 s60, s30, s57
	v_lshl_add_u64 v[192:193], s[10:11], 0, v[210:211]
	s_add_i32 m0, s39, 0xc000
	ds_read_b128 v[160:163], v248
	ds_read_b128 v[164:167], v248 offset:1024
	ds_read_b128 v[168:171], v248 offset:2048
	ds_read_b128 v[172:175], v248 offset:3072
	ds_read_b128 v[176:179], v248 offset:4096
	ds_read_b128 v[180:183], v248 offset:5120
	ds_read_b128 v[184:187], v248 offset:6144
	ds_read_b128 v[188:191], v248 offset:7168
	global_load_lds_dwordx4 v[192:193], off
	v_lshl_add_u64 v[192:193], s[10:11], 0, v[212:213]
	s_add_i32 m0, s39, 0xe000
	s_nop 0
	global_load_lds_dwordx4 v[192:193], off
	s_cmp_eq_u32 s99, 0
	s_cbranch_scc1 .Lw8_3_0
	s_waitcnt vmcnt(16)
	s_branch .Lwj_3_0

; #define PG8_STAGE(bufoff, gbase, voff) do { _Pragma("unroll") for (int _i = 0; _i < 2; ++_i) \
;         __builtin_amdgcn_global_load_lds((const unsigned*)((const char*)(gbase) + (voff)[_i]), (PG8_LAS unsigned*)(lds + (bufoff) + ldsw + _i * 8192), 16, 0, 0); } while (0)
; #define PG8_LDA(dst, b, h) do { _Pragma("unroll") for (int m = 0; m < 4; ++m) _Pragma("unroll") for (int k = 0; k < 2; ++k) dst[m][k] = *(const PG8_LAS bf16x8*)(lds + PG8_SA(b, h) + aoff + m * 2048 + k * 1024); } while (0)
; #define PG8_MMA(ai, bj, At, Bt) do { __builtin_amdgcn_s_setprio(1); _Pragma("unroll") for (int m = 0; m < 4; ++m) _Pragma("unroll") for (int n = 0; n < 2; ++n) _Pragma("unroll") for (int k = 0; k < 2; ++k) \
;         acc[ai][bj][m][n] = __builtin_amdgcn_mfma_f32_16x16x32_bf16(Bt[n][k], At[m][k], acc[ai][bj][m][n], 0, 0, 0); __builtin_amdgcn_s_setprio(0); } while (0)
; #define PG8_WAIT_V(n) asm volatile("s_waitcnt vmcnt(" #n ")" ::: "memory")
; #define PG8_WAIT_L(n) asm volatile("s_waitcnt lgkmcnt(" #n ")" ::: "memory")
; #define PG8_BAR __builtin_amdgcn_s_barrier()
; #define PG8_SCHED __builtin_amdgcn_sched_barrier(0)
; template <class Epi, class Sched, bool ALIGN_EPI = false, bool SP2 = false>
; __device__ __forceinline__ void gemm_phase(PG8_LAS unsigned char* lds, const Gemm g, const Sched& S, const Epi& E) {
;     ...
;             PG8_WAIT_V(8); PG8_WAIT_L(0); PG8_BAR; PG8_MMA(0, 0, At, B0); PG8_MMA(0, 1, At, B1); PG8_BAR; PG8_SCHED;
;             PG8_LDA(At, 0, 1); PG8_STAGE(PG8_SB(0, 0), b2, voffB); PG8_STAGE(PG8_SB(0, 1), b2 + hstep, voffB); PG8_STAGE(PG8_SA(0, 0), a2, voffA);
;             PG8_WAIT_V(8); PG8_WAIT_L(0); PG8_BAR; PG8_MMA(1, 0, At, B0); PG8_MMA(1, 1, At, B1); PG8_BAR; PG8_SCHED;
.Lwj_3_0:
	s_waitcnt lgkmcnt(0)
	s_barrier
	s_setprio 1
	s_waitcnt lgkmcnt(0)
	v_mfma_f32_16x16x32_bf16 v[144:147], v[80:83], v[160:163], 0
	v_mfma_f32_16x16x32_bf16 v[136:139], v[88:91], v[160:163], 0
	v_mfma_f32_16x16x32_bf16 v[128:131], v[80:83], v[168:171], 0
	v_mfma_f32_16x16x32_bf16 v[120:123], v[88:91], v[168:171], 0
	v_mfma_f32_16x16x32_bf16 v[112:115], v[80:83], v[176:179], 0
	v_mfma_f32_16x16x32_bf16 v[104:107], v[88:91], v[176:179], 0
	v_mfma_f32_16x16x32_bf16 v[72:75], v[80:83], v[184:187], 0
	v_mfma_f32_16x16x32_bf16 v[64:67], v[88:91], v[184:187], 0
	v_mfma_f32_16x16x32_bf16 v[144:147], v[84:87], v[164:167], v[144:147]
	v_mfma_f32_16x16x32_bf16 v[136:139], v[92:95], v[164:167], v[136:139]
	v_mfma_f32_16x16x32_bf16 v[128:131], v[84:87], v[172:175], v[128:131]
	v_mfma_f32_16x16x32_bf16 v[120:123], v[92:95], v[172:175], v[120:123]
	v_mfma_f32_16x16x32_bf16 v[112:115], v[84:87], v[180:183], v[112:115]
	v_mfma_f32_16x16x32_bf16 v[104:107], v[92:95], v[180:183], v[104:107]
	v_mfma_f32_16x16x32_bf16 v[72:75], v[84:87], v[188:191], v[72:75]
	v_mfma_f32_16x16x32_bf16 v[64:67], v[92:95], v[188:191], v[64:67]
	s_setprio 0
	s_setprio 1
	v_mfma_f32_16x16x32_bf16 v[148:151], v[96:99], v[160:163], 0
	v_mfma_f32_16x16x32_bf16 v[140:143], v[152:155], v[160:163], 0
	v_mfma_f32_16x16x32_bf16 v[132:135], v[96:99], v[168:171], 0
	v_mfma_f32_16x16x32_bf16 v[124:127], v[152:155], v[168:171], 0
	v_mfma_f32_16x16x32_bf16 v[116:119], v[96:99], v[176:179], 0
	v_mfma_f32_16x16x32_bf16 v[108:111], v[152:155], v[176:179], 0
	v_mfma_f32_16x16x32_bf16 v[76:79], v[96:99], v[184:187], 0
	v_mfma_f32_16x16x32_bf16 v[68:71], v[152:155], v[184:187], 0
	v_mfma_f32_16x16x32_bf16 v[148:151], v[100:103], v[164:167], v[148:151]
	v_mfma_f32_16x16x32_bf16 v[140:143], v[156:159], v[164:167], v[140:143]
	v_mfma_f32_16x16x32_bf16 v[132:135], v[100:103], v[172:175], v[132:135]
	v_mfma_f32_16x16x32_bf16 v[124:127], v[156:159], v[172:175], v[124:127]
	v_mfma_f32_16x16x32_bf16 v[116:119], v[100:103], v[180:183], v[116:119]
	v_mfma_f32_16x16x32_bf16 v[108:111], v[156:159], v[180:183], v[108:111]
	v_mfma_f32_16x16x32_bf16 v[76:79], v[100:103], v[188:191], v[76:79]
	v_mfma_f32_16x16x32_bf16 v[68:71], v[156:159], v[188:191], v[68:71]
	s_setprio 0
	s_barrier
	s_add_i32 s62, s52, s38
	v_lshl_add_u64 v[192:193], s[60:61], 0, v[204:205]
	s_mov_b32 m0, s62
	ds_read_b128 v[160:163], v248 offset:16384
	ds_read_b128 v[164:167], v248 offset:17408
	ds_read_b128 v[168:171], v248 offset:18432
	ds_read_b128 v[172:175], v248 offset:19456
	ds_read_b128 v[176:179], v248 offset:20480
	ds_read_b128 v[180:183], v248 offset:21504
	ds_read_b128 v[184:187], v248 offset:22528
	ds_read_b128 v[188:191], v248 offset:23552
	global_load_lds_dwordx4 v[192:193], off
	s_add_i32 m0, s62, 0x2000
	v_lshl_add_u64 v[194:195], s[60:61], 0, v[208:209]
	s_add_u32 s60, s60, s6
	s_addc_u32 s61, s61, s7
	s_add_i32 s62, s53, s38
	global_load_lds_dwordx4 v[194:195], off
	v_lshl_add_u64 v[196:197], s[60:61], 0, v[204:205]
	s_mov_b32 m0, s62
	v_lshl_add_u64 v[198:199], s[60:61], 0, v[208:209]
	global_load_lds_dwordx4 v[196:197], off
	s_add_i32 m0, s62, 0x2000
	v_lshl_add_u64 v[218:219], s[34:35], 0, v[202:203]
	global_load_lds_dwordx4 v[198:199], off
	s_mov_b32 m0, s39
	v_lshl_add_u64 v[220:221], s[34:35], 0, v[206:207]
	global_load_lds_dwordx4 v[218:219], off
	s_mov_b32 m0, s40
	s_nop 0
	global_load_lds_dwordx4 v[220:221], off
	s_cmp_eq_u32 s99, 0
	s_cbranch_scc1 .Lw8_3_1
	s_waitcnt vmcnt(16)
	s_branch .Lwj_3_1

; #define PG8_STAGE(bufoff, gbase, voff) do { _Pragma("unroll") for (int _i = 0; _i < 2; ++_i) \
;         __builtin_amdgcn_global_load_lds((const unsigned*)((const char*)(gbase) + (voff)[_i]), (PG8_LAS unsigned*)(lds + (bufoff) + ldsw + _i * 8192), 16, 0, 0); } while (0)
; #define PG8_LDA(dst, b, h) do { _Pragma("unroll") for (int m = 0; m < 4; ++m) _Pragma("unroll") for (int k = 0; k < 2; ++k) dst[m][k] = *(const PG8_LAS bf16x8*)(lds + PG8_SA(b, h) + aoff + m * 2048 + k * 1024); } while (0)
; #define PG8_LDB(dst, b, h) do { _Pragma("unroll") for (int n = 0; n < 2; ++n) _Pragma("unroll") for (int k = 0; k < 2; ++k) dst[n][k] = *(const PG8_LAS bf16x8*)(lds + PG8_SB(b, h) + boff + n * 2048 + k * 1024); } while (0)
; #define PG8_MMA(ai, bj, At, Bt) do { __builtin_amdgcn_s_setprio(1); _Pragma("unroll") for (int m = 0; m < 4; ++m) _Pragma("unroll") for (int n = 0; n < 2; ++n) _Pragma("unroll") for (int k = 0; k < 2; ++k) \
;         acc[ai][bj][m][n] = __builtin_amdgcn_mfma_f32_16x16x32_bf16(Bt[n][k], At[m][k], acc[ai][bj][m][n], 0, 0, 0); __builtin_amdgcn_s_setprio(0); } while (0)
; #define PG8_WAIT_V(n) asm volatile("s_waitcnt vmcnt(" #n ")" ::: "memory")
; #define PG8_WAIT_L(n) asm volatile("s_waitcnt lgkmcnt(" #n ")" ::: "memory")
; #define PG8_BAR __builtin_amdgcn_s_barrier()
; #define PG8_SCHED __builtin_amdgcn_sched_barrier(0)
; template <class Epi, class Sched, bool ALIGN_EPI = false, bool SP2 = false>
; __device__ __forceinline__ void gemm_phase(PG8_LAS unsigned char* lds, const Gemm g, const Sched& S, const Epi& E) {
;     ...
;             PG8_WAIT_V(8); PG8_WAIT_L(0); PG8_BAR; PG8_MMA(1, 0, At, B0); PG8_MMA(1, 1, At, B1); PG8_BAR; PG8_SCHED;
;             PG8_LDB(B0, 1, 0); PG8_LDB(B1, 1, 1); PG8_SCHED; PG8_LDA(At, 1, 0); PG8_STAGE(PG8_SA(0, 1), a2 + hstep, voffA);
;             PG8_WAIT_V(8); PG8_WAIT_L(0); PG8_BAR; PG8_MMA(0, 0, At, B0); PG8_MMA(0, 1, At, B1); PG8_BAR; PG8_SCHED;
.Lwj_3_1:
	s_waitcnt lgkmcnt(0)
	s_barrier
	s_setprio 1
	s_waitcnt lgkmcnt(0)
	v_mfma_f32_16x16x32_bf16 v[56:59], v[80:83], v[160:163], 0
	v_mfma_f32_16x16x32_bf16 v[48:51], v[88:91], v[160:163], 0
	v_mfma_f32_16x16x32_bf16 v[40:43], v[80:83], v[168:171], 0
	v_mfma_f32_16x16x32_bf16 v[32:35], v[88:91], v[168:171], 0
	v_mfma_f32_16x16x32_bf16 v[24:27], v[80:83], v[176:179], 0
	v_mfma_f32_16x16x32_bf16 v[16:19], v[88:91], v[176:179], 0
	v_mfma_f32_16x16x32_bf16 v[8:11], v[80:83], v[184:187], 0
	v_mfma_f32_16x16x32_bf16 v[0:3], v[88:91], v[184:187], 0
	v_mfma_f32_16x16x32_bf16 v[56:59], v[84:87], v[164:167], v[56:59]
	v_mfma_f32_16x16x32_bf16 v[48:51], v[92:95], v[164:167], v[48:51]
	v_mfma_f32_16x16x32_bf16 v[40:43], v[84:87], v[172:175], v[40:43]
	v_mfma_f32_16x16x32_bf16 v[32:35], v[92:95], v[172:175], v[32:35]
	v_mfma_f32_16x16x32_bf16 v[24:27], v[84:87], v[180:183], v[24:27]
	v_mfma_f32_16x16x32_bf16 v[16:19], v[92:95], v[180:183], v[16:19]
	v_mfma_f32_16x16x32_bf16 v[8:11], v[84:87], v[188:191], v[8:11]
	v_mfma_f32_16x16x32_bf16 v[0:3], v[92:95], v[188:191], v[0:3]
	s_setprio 0
	s_setprio 1
	v_mfma_f32_16x16x32_bf16 v[60:63], v[96:99], v[160:163], 0
	v_mfma_f32_16x16x32_bf16 v[52:55], v[152:155], v[160:163], 0
	v_mfma_f32_16x16x32_bf16 v[44:47], v[96:99], v[168:171], 0
	v_mfma_f32_16x16x32_bf16 v[36:39], v[152:155], v[168:171], 0
	v_mfma_f32_16x16x32_bf16 v[28:31], v[96:99], v[176:179], 0
	v_mfma_f32_16x16x32_bf16 v[20:23], v[152:155], v[176:179], 0
	v_mfma_f32_16x16x32_bf16 v[12:15], v[96:99], v[184:187], 0
	v_mfma_f32_16x16x32_bf16 v[4:7], v[152:155], v[184:187], 0
	v_mfma_f32_16x16x32_bf16 v[60:63], v[100:103], v[164:167], v[60:63]
	v_mfma_f32_16x16x32_bf16 v[52:55], v[156:159], v[164:167], v[52:55]
	v_mfma_f32_16x16x32_bf16 v[44:47], v[100:103], v[172:175], v[44:47]
	v_mfma_f32_16x16x32_bf16 v[36:39], v[156:159], v[172:175], v[36:39]
	v_mfma_f32_16x16x32_bf16 v[28:31], v[100:103], v[180:183], v[28:31]
	v_mfma_f32_16x16x32_bf16 v[20:23], v[156:159], v[180:183], v[20:23]
	v_mfma_f32_16x16x32_bf16 v[12:15], v[100:103], v[188:191], v[12:15]
	v_mfma_f32_16x16x32_bf16 v[4:7], v[156:159], v[188:191], v[4:7]
	s_setprio 0
	s_barrier
	s_add_i32 s60, 0, 0x18000
	s_add_i32 s61, 0, 0x1c000
	v_add_u32_e32 v92, s60, v245
	v_add_u32_e32 v156, s61, v245
	ds_read_b128 v[80:83], v92
	ds_read_b128 v[84:87], v92 offset:1024
	ds_read_b128 v[88:91], v92 offset:2048
	ds_read_b128 v[92:95], v92 offset:3072
	ds_read_b128 v[96:99], v156
	ds_read_b128 v[100:103], v156 offset:1024
	ds_read_b128 v[152:155], v156 offset:2048
	ds_read_b128 v[156:159], v156 offset:3072
	s_add_u32 s34, s34, s6
	s_addc_u32 s35, s35, s7
	s_mov_b32 m0, s41
	v_lshl_add_u64 v[222:223], s[34:35], 0, v[202:203]
	ds_read_b128 v[160:163], v248 offset:32768
	ds_read_b128 v[164:167], v248 offset:33792
	ds_read_b128 v[168:171], v248 offset:34816
	ds_read_b128 v[172:175], v248 offset:35840
	ds_read_b128 v[176:179], v248 offset:36864
	ds_read_b128 v[180:183], v248 offset:37888
	ds_read_b128 v[184:187], v248 offset:38912
	ds_read_b128 v[188:191], v248 offset:39936
	global_load_lds_dwordx4 v[222:223], off
	v_lshl_add_u64 v[222:223], s[34:35], 0, v[206:207]
	s_mov_b32 m0, s42
	s_nop 0
	global_load_lds_dwordx4 v[222:223], off
	s_waitcnt vmcnt(8)
	s_waitcnt lgkmcnt(0)
	s_barrier
	s_setprio 1
	s_waitcnt lgkmcnt(0)
	v_mfma_f32_16x16x32_bf16 v[144:147], v[80:83], v[160:163], v[144:147]
	v_mfma_f32_16x16x32_bf16 v[136:139], v[88:91], v[160:163], v[136:139]
	v_mfma_f32_16x16x32_bf16 v[128:131], v[80:83], v[168:171], v[128:131]
	v_mfma_f32_16x16x32_bf16 v[120:123], v[88:91], v[168:171], v[120:123]
	v_mfma_f32_16x16x32_bf16 v[112:115], v[80:83], v[176:179], v[112:115]
	v_mfma_f32_16x16x32_bf16 v[104:107], v[88:91], v[176:179], v[104:107]
	v_mfma_f32_16x16x32_bf16 v[72:75], v[80:83], v[184:187], v[72:75]
	v_mfma_f32_16x16x32_bf16 v[64:67], v[88:91], v[184:187], v[64:67]
	v_mfma_f32_16x16x32_bf16 v[144:147], v[84:87], v[164:167], v[144:147]
	v_mfma_f32_16x16x32_bf16 v[136:139], v[92:95], v[164:167], v[136:139]
	v_mfma_f32_16x16x32_bf16 v[128:131], v[84:87], v[172:175], v[128:131]
	v_mfma_f32_16x16x32_bf16 v[120:123], v[92:95], v[172:175], v[120:123]
	v_mfma_f32_16x16x32_bf16 v[112:115], v[84:87], v[180:183], v[112:115]
	v_mfma_f32_16x16x32_bf16 v[104:107], v[92:95], v[180:183], v[104:107]
	v_mfma_f32_16x16x32_bf16 v[72:75], v[84:87], v[188:191], v[72:75]
	v_mfma_f32_16x16x32_bf16 v[64:67], v[92:95], v[188:191], v[64:67]
	s_setprio 0
	s_setprio 1
	v_mfma_f32_16x16x32_bf16 v[148:151], v[96:99], v[160:163], v[148:151]
	v_mfma_f32_16x16x32_bf16 v[140:143], v[152:155], v[160:163], v[140:143]
	v_mfma_f32_16x16x32_bf16 v[132:135], v[96:99], v[168:171], v[132:135]
	v_mfma_f32_16x16x32_bf16 v[124:127], v[152:155], v[168:171], v[124:127]
	v_mfma_f32_16x16x32_bf16 v[116:119], v[96:99], v[176:179], v[116:119]
	v_mfma_f32_16x16x32_bf16 v[108:111], v[152:155], v[176:179], v[108:111]
	v_mfma_f32_16x16x32_bf16 v[76:79], v[96:99], v[184:187], v[76:79]
	v_mfma_f32_16x16x32_bf16 v[68:71], v[152:155], v[184:187], v[68:71]
	v_mfma_f32_16x16x32_bf16 v[148:151], v[100:103], v[164:167], v[148:151]
	v_mfma_f32_16x16x32_bf16 v[140:143], v[156:159], v[164:167], v[140:143]
	v_mfma_f32_16x16x32_bf16 v[132:135], v[100:103], v[172:175], v[132:135]
	v_mfma_f32_16x16x32_bf16 v[124:127], v[156:159], v[172:175], v[124:127]
	v_mfma_f32_16x16x32_bf16 v[116:119], v[100:103], v[180:183], v[116:119]
	v_mfma_f32_16x16x32_bf16 v[108:111], v[156:159], v[180:183], v[108:111]
	v_mfma_f32_16x16x32_bf16 v[76:79], v[100:103], v[188:191], v[76:79]
	v_mfma_f32_16x16x32_bf16 v[68:71], v[156:159], v[188:191], v[68:71]
	s_setprio 0
	s_barrier
; #define PG8_STAGE(bufoff, gbase, voff) do { _Pragma("unroll") for (int _i = 0; _i < 2; ++_i) \
;         __builtin_amdgcn_global_load_lds((const unsigned*)((const char*)(gbase) + (voff)[_i]), (PG8_LAS unsigned*)(lds + (bufoff) + ldsw + _i * 8192), 16, 0, 0); } while (0)
; #define PG8_LDA(dst, b, h) do { _Pragma("unroll") for (int m = 0; m < 4; ++m) _Pragma("unroll") for (int k = 0; k < 2; ++k) dst[m][k] = *(const PG8_LAS bf16x8*)(lds + PG8_SA(b, h) + aoff + m * 2048 + k * 1024); } while (0)
; #define PG8_MMA(ai, bj, At, Bt) do { __builtin_amdgcn_s_setprio(1); _Pragma("unroll") for (int m = 0; m < 4; ++m) _Pragma("unroll") for (int n = 0; n < 2; ++n) _Pragma("unroll") for (int k = 0; k < 2; ++k) \
;         acc[ai][bj][m][n] = __builtin_amdgcn_mfma_f32_16x16x32_bf16(Bt[n][k], At[m][k], acc[ai][bj][m][n], 0, 0, 0); __builtin_amdgcn_s_setprio(0); } while (0)
; #define PG8_WAIT_V(n) asm volatile("s_waitcnt vmcnt(" #n ")" ::: "memory")
; #define PG8_WAIT_L(n) asm volatile("s_waitcnt lgkmcnt(" #n ")" ::: "memory")
; #define PG8_BAR __builtin_amdgcn_s_barrier()
; #define PG8_SCHED __builtin_amdgcn_sched_barrier(0)
; template <class Epi, class Sched, bool ALIGN_EPI = false, bool SP2 = false>
; __device__ __forceinline__ void gemm_phase(PG8_LAS unsigned char* lds, const Gemm g, const Sched& S, const Epi& E) {
;     ...
;             PG8_LDA(At, 1, 1); PG8_STAGE(PG8_SB(1, 0), b3, voffB); PG8_STAGE(PG8_SB(1, 1), b3 + hstep, voffB); PG8_STAGE(PG8_SA(1, 0), a3, voffA);
;             PG8_WAIT_V(8); PG8_WAIT_L(0); PG8_BAR; PG8_MMA(1, 0, At, B0); PG8_MMA(1, 1, At, B1); PG8_BAR; PG8_SCHED;
	s_add_i32 s34, s60, s38
	v_lshl_add_u64 v[192:193], v[192:193], 0, s[16:17]
	s_mov_b32 m0, s34
	ds_read_b128 v[160:163], v248 offset:49152
	ds_read_b128 v[164:167], v248 offset:50176
	ds_read_b128 v[168:171], v248 offset:51200
	ds_read_b128 v[172:175], v248 offset:52224
	ds_read_b128 v[176:179], v248 offset:53248
	ds_read_b128 v[180:183], v248 offset:54272
	ds_read_b128 v[184:187], v248 offset:55296
	ds_read_b128 v[188:191], v248 offset:56320
	global_load_lds_dwordx4 v[192:193], off
	v_lshl_add_u64 v[192:193], v[194:195], 0, s[16:17]
	s_add_i32 m0, s34, 0x2000
	s_add_i32 s34, s61, s38
	global_load_lds_dwordx4 v[192:193], off
	v_lshl_add_u64 v[192:193], v[196:197], 0, s[16:17]
	s_mov_b32 m0, s34
	s_nop 0
	global_load_lds_dwordx4 v[192:193], off
	v_lshl_add_u64 v[192:193], v[198:199], 0, s[16:17]
	s_add_i32 m0, s34, 0x2000
	s_nop 0
	global_load_lds_dwordx4 v[192:193], off
	v_lshl_add_u64 v[192:193], v[218:219], 0, s[16:17]
	s_mov_b32 m0, s44
	s_nop 0
	global_load_lds_dwordx4 v[192:193], off
	v_lshl_add_u64 v[192:193], v[220:221], 0, s[16:17]
	s_mov_b32 m0, s45
	s_nop 0
	global_load_lds_dwordx4 v[192:193], off
	s_waitcnt vmcnt(8)
	s_waitcnt lgkmcnt(0)
	s_barrier
	s_setprio 1
	s_waitcnt lgkmcnt(0)
	v_mfma_f32_16x16x32_bf16 v[56:59], v[80:83], v[160:163], v[56:59]
	v_mfma_f32_16x16x32_bf16 v[48:51], v[88:91], v[160:163], v[48:51]
	v_mfma_f32_16x16x32_bf16 v[40:43], v[80:83], v[168:171], v[40:43]
	v_mfma_f32_16x16x32_bf16 v[32:35], v[88:91], v[168:171], v[32:35]
	v_mfma_f32_16x16x32_bf16 v[24:27], v[80:83], v[176:179], v[24:27]
	v_mfma_f32_16x16x32_bf16 v[16:19], v[88:91], v[176:179], v[16:19]
	v_mfma_f32_16x16x32_bf16 v[8:11], v[80:83], v[184:187], v[8:11]
	v_mfma_f32_16x16x32_bf16 v[0:3], v[88:91], v[184:187], v[0:3]
	v_mfma_f32_16x16x32_bf16 v[56:59], v[84:87], v[164:167], v[56:59]
	v_mfma_f32_16x16x32_bf16 v[48:51], v[92:95], v[164:167], v[48:51]
	v_mfma_f32_16x16x32_bf16 v[40:43], v[84:87], v[172:175], v[40:43]
	v_mfma_f32_16x16x32_bf16 v[32:35], v[92:95], v[172:175], v[32:35]
	v_mfma_f32_16x16x32_bf16 v[24:27], v[84:87], v[180:183], v[24:27]
	v_mfma_f32_16x16x32_bf16 v[16:19], v[92:95], v[180:183], v[16:19]
	v_mfma_f32_16x16x32_bf16 v[8:11], v[84:87], v[188:191], v[8:11]
	v_mfma_f32_16x16x32_bf16 v[0:3], v[92:95], v[188:191], v[0:3]
	s_setprio 0
	s_setprio 1
	v_mfma_f32_16x16x32_bf16 v[60:63], v[96:99], v[160:163], v[60:63]
	v_mfma_f32_16x16x32_bf16 v[52:55], v[152:155], v[160:163], v[52:55]
	v_mfma_f32_16x16x32_bf16 v[44:47], v[96:99], v[168:171], v[44:47]
	v_mfma_f32_16x16x32_bf16 v[36:39], v[152:155], v[168:171], v[36:39]
	v_mfma_f32_16x16x32_bf16 v[28:31], v[96:99], v[176:179], v[28:31]
	v_mfma_f32_16x16x32_bf16 v[20:23], v[152:155], v[176:179], v[20:23]
	v_mfma_f32_16x16x32_bf16 v[12:15], v[96:99], v[184:187], v[12:15]
	v_mfma_f32_16x16x32_bf16 v[4:7], v[152:155], v[184:187], v[4:7]
	v_mfma_f32_16x16x32_bf16 v[60:63], v[100:103], v[164:167], v[60:63]
	v_mfma_f32_16x16x32_bf16 v[52:55], v[156:159], v[164:167], v[52:55]
	v_mfma_f32_16x16x32_bf16 v[44:47], v[100:103], v[172:175], v[44:47]
	v_mfma_f32_16x16x32_bf16 v[36:39], v[156:159], v[172:175], v[36:39]
	v_mfma_f32_16x16x32_bf16 v[28:31], v[100:103], v[180:183], v[28:31]
	v_mfma_f32_16x16x32_bf16 v[20:23], v[156:159], v[180:183], v[20:23]
	v_mfma_f32_16x16x32_bf16 v[12:15], v[100:103], v[188:191], v[12:15]
	v_mfma_f32_16x16x32_bf16 v[4:7], v[156:159], v[188:191], v[4:7]
	s_setprio 0
	s_barrier
	s_add_u32 s10, s10, 0x100
	s_addc_u32 s11, s11, 0
	s_add_u32 s57, s57, 0x100
	s_addc_u32 s58, s58, 0
	s_cmp_ge_i32 s59, s46
	s_mov_b32 s34, s59
	s_cbranch_scc1 .LBB0_841

;     __device__ __forceinline__ void operator()(const AccT& acc, const Unit& u, int wr, int wc, int fr_, int fq_) const {
;         int fr = fr_, fq = fq_; asm volatile("" : "+v"(fr), "+v"(fq));
;         const int c0 = u.pn * 128 + wc * 32 + 8 * fq;
;         const bf16_t* const U = (const bf16_t*)(ws + WS_RB); bf16_t* const A2 = (bf16_t*)(ws + WS_A2);
;         const f32x4 w0a = *(const f32x4*)(conv_w + c0), w0b = *(const f32x4*)(conv_w + c0 + 4);
;         const f32x4 w1a = *(const f32x4*)(conv_w + 1024 + c0), w1b = *(const f32x4*)(conv_w + 1024 + c0 + 4);
;         const f32x4 w2a = *(const f32x4*)(conv_w + 2048 + c0), w2b = *(const f32x4*)(conv_w + 2048 + c0 + 4);
; #pragma unroll
;         for (int ai = 0; ai < 2; ++ai) {
;             u32x4 uu[4][3];
; #pragma unroll
;             for (int m = 0; m < 4; ++m) { const size_t row = (size_t)ROW_OF(ai, m); const int s = (int)(row & 2047); const u32x4 z4 = {0u, 0u, 0u, 0u};
;                 uu[m][2] = *(const u32x4*)(U + row * 1024 + c0);
;                 uu[m][1] = s >= 1 ? *(const u32x4*)(U + (row - 1) * 1024 + c0) : z4;
;                 uu[m][0] = s >= 2 ? *(const u32x4*)(U + (row - 2) * 1024 + c0) : z4; }
.LBB0_843:
	s_mov_b32 s99, 1
	s_lshl_b32 s10, s56, 7
	v_mov_b32_e32 v152, v201
	v_mov_b32_e32 v80, v232
	s_or_b32 s10, s10, s48
	v_readlane_b32 s56, v254, 23
	v_lshl_add_u32 v220, v80, 3, s10
	s_lshl_b32 s10, s33, 8
	s_add_i32 s10, s10, s47
	v_add_u32_e32 v222, s10, v152
	v_ashrrev_i32_e32 v221, 31, v220
	v_ashrrev_i32_e32 v223, 31, v222
	v_lshlrev_b64 v[80:81], 2, v[220:221]
	v_readlane_b32 s70, v254, 37
	v_readlane_b32 s71, v254, 38
	v_lshlrev_b64 v[152:153], 11, v[222:223]
	v_lshl_add_u64 v[152:153], s[22:23], 0, v[152:153]
	v_lshl_add_u64 v[82:83], s[70:71], 0, v[80:81]
	global_load_dwordx4 v[88:91], v[82:83], off offset:16
	global_load_dwordx4 v[100:103], v[82:83], off
	v_lshl_add_u64 v[82:83], s[26:27], 0, v[80:81]
	v_lshl_add_u64 v[92:93], s[28:29], 0, v[80:81]
	v_lshl_add_u64 v[152:153], v[220:221], 1, v[152:153]
	global_load_dwordx4 v[84:87], v[82:83], off offset:16
	global_load_dwordx4 v[96:99], v[82:83], off
	s_nop 0
	global_load_dwordx4 v[80:83], v[92:93], off offset:16
	s_nop 0
	global_load_dwordx4 v[92:95], v[92:93], off
	v_and_b32_e32 v154, 0x7ff, v222
	global_load_dwordx4 v[188:191], v[152:153], off
	v_mov_b32_e32 v196, 0
	v_cmp_ne_u32_e32 vcc, 0, v154
	v_mov_b32_e32 v192, 0
	v_mov_b32_e32 v193, 0
	v_mov_b32_e32 v194, 0
	v_mov_b32_e32 v195, 0
	v_readlane_b32 s57, v254, 24
	v_readlane_b32 s58, v254, 25
	v_readlane_b32 s59, v254, 26
	v_readlane_b32 s60, v254, 27
	v_readlane_b32 s61, v254, 28
	v_readlane_b32 s62, v254, 29
	v_readlane_b32 s63, v254, 30
	v_readlane_b32 s64, v254, 31
	v_readlane_b32 s65, v254, 32
	v_readlane_b32 s66, v254, 33
	v_readlane_b32 s67, v254, 34
	v_readlane_b32 s68, v254, 35
	v_readlane_b32 s69, v254, 36
	s_and_saveexec_b64 s[10:11], vcc
	s_cbranch_execz .LBB0_845
	global_load_dwordx4 v[192:195], v[152:153], off offset:-2048

;     __device__ __forceinline__ void operator()(const AccT& acc, const Unit& u, int wr, int wc, int fr_, int fq_) const {
;     ...
;         float ssv[2][4];
; #pragma unroll
;         for (int ai = 0; ai < 2; ++ai)
; #pragma unroll
;             for (int m = 0; m < 4; ++m) ssv[ai][m] = ssq_kv[(size_t)ROW_OF(ai, m)];
.LBB0_888:
	s_mov_b64 s[14:15], 0x80
	s_add_i32 m0, s38, 0x18000
	v_lshl_add_u64 v[8:9], v[8:9], 0, s[14:15]
	s_waitcnt vmcnt(2)
	s_barrier
	global_load_lds_dwordx4 v[8:9], off
	v_lshl_add_u64 v[4:5], v[4:5], 0, s[14:15]
	s_add_i32 m0, s38, 0x1a000
	s_add_i32 s43, s38, 0x8000
	global_load_lds_dwordx4 v[4:5], off
	v_lshl_add_u64 v[4:5], v[6:7], 0, s[14:15]
	s_mov_b32 m0, s43
	s_add_i32 s44, s38, 0xa000
	global_load_lds_dwordx4 v[4:5], off
	v_lshl_add_u64 v[4:5], v[10:11], 0, s[14:15]
	s_mov_b32 m0, s44
	v_lshl_add_u64 v[2:3], v[2:3], 0, s[14:15]
	global_load_lds_dwordx4 v[4:5], off
	s_add_i32 m0, s38, 0x1c000
	v_lshl_add_u64 v[0:1], v[0:1], 0, s[14:15]
	global_load_lds_dwordx4 v[2:3], off
	s_add_i32 m0, s38, 0x1e000
	s_lshr_b32 s1, s1, 26
	global_load_lds_dwordx4 v[0:1], off
	s_add_i32 s1, s0, s1
	s_and_b32 s2, s2, 3
	s_ashr_i32 s45, s1, 6
	s_lshl_b32 s46, s3, 6
	s_lshl_b32 s1, s3, 13
	s_cmp_gt_i32 s0, 63
	s_cselect_b64 s[16:17], -1, 0
	s_add_i32 s47, s45, -2
	v_lshlrev_b32_e32 v1, 2, v201
	s_cmpk_lt_u32 s18, 0x100
	v_lshl_or_b32 v0, v201, 6, v238
	v_and_b32_e32 v1, 32, v1
	s_cselect_b64 s[18:19], -1, 0
	s_add_u32 s20, s90, 0x5000000
	v_bitop3_b32 v0, v0, s1, v1 bitop3:0xde
	s_addc_u32 s21, s91, 0
	v_add_u32_e32 v1, v237, v235
	s_add_u32 s22, s90, 0x20000
	v_mul_lo_u32 v1, s0, v1
	s_addc_u32 s23, s91, 0
	s_lshl_b32 s1, s2, 9
	v_lshlrev_b32_e32 v1, 1, v1
	s_add_u32 s1, s90, s1
	v_add3_u32 v136, v233, v1, v234
	v_add_u32_e32 v1, v236, v235
	s_addc_u32 s3, s91, 0
	v_mul_lo_u32 v1, s0, v1
	s_waitcnt vmcnt(6)
	s_add_u32 s24, s1, 0x1b000000
	v_lshlrev_b32_e32 v1, 1, v1
	v_lshl_or_b32 v168, s2, 12, v239
	s_addc_u32 s25, s3, 0
	v_lshl_add_u64 v[138:139], s[6:7], 0, v[136:137]
	v_add3_u32 v136, v233, v1, v234
	s_add_i32 s51, 0, 0x10000
	s_add_i32 s52, 0, 0x14000
	s_lshl_b32 s48, s2, 2
	s_ashr_i32 s49, s83, 31
	s_ashr_i32 s50, s80, 31
	v_lshl_add_u64 v[140:141], s[6:7], 0, v[136:137]
	v_mov_b64_e32 v[142:143], 0x400
	v_mov_b64_e32 v[144:145], 0x3ff
	v_add_u32_e32 v169, s51, v168
	v_add_u32_e32 v170, s52, v168
	v_add_u32_e32 v171, 0, v0
	v_mov_b32_e32 v172, 0x358637bd
	s_mov_b32 s53, 0x80000
	s_barrier
	v_lshl_add_u32 v253, s31, 8, v201
	v_add_lshl_u32 v253, v253, s46, 2
	global_load_dword v245, v253, s[22:23]
	global_load_dword v246, v253, s[22:23] offset:64
	global_load_dword v247, v253, s[22:23] offset:128
	global_load_dword v248, v253, s[22:23] offset:192
	global_load_dword v249, v253, s[22:23] offset:512
	global_load_dword v250, v253, s[22:23] offset:576
	global_load_dword v251, v253, s[22:23] offset:640
	global_load_dword v252, v253, s[22:23] offset:704
	s_mov_b32 s99, 0
	s_branch .LBB0_891

; #define PG8_STAGE(bufoff, gbase, voff) do { _Pragma("unroll") for (int _i = 0; _i < 2; ++_i) \
;         __builtin_amdgcn_global_load_lds((const unsigned*)((const char*)(gbase) + (voff)[_i]), (PG8_LAS unsigned*)(lds + (bufoff) + ldsw + _i * 8192), 16, 0, 0); } while (0)
; #define PG8_LDA(dst, b, h) do { _Pragma("unroll") for (int m = 0; m < 4; ++m) _Pragma("unroll") for (int k = 0; k < 2; ++k) dst[m][k] = *(const PG8_LAS bf16x8*)(lds + PG8_SA(b, h) + aoff + m * 2048 + k * 1024); } while (0)
; #define PG8_LDB(dst, b, h) do { _Pragma("unroll") for (int n = 0; n < 2; ++n) _Pragma("unroll") for (int k = 0; k < 2; ++k) dst[n][k] = *(const PG8_LAS bf16x8*)(lds + PG8_SB(b, h) + boff + n * 2048 + k * 1024); } while (0)
; #define PG8_MMA(ai, bj, At, Bt) do { __builtin_amdgcn_s_setprio(1); _Pragma("unroll") for (int m = 0; m < 4; ++m) _Pragma("unroll") for (int n = 0; n < 2; ++n) _Pragma("unroll") for (int k = 0; k < 2; ++k) \
;         acc[ai][bj][m][n] = __builtin_amdgcn_mfma_f32_16x16x32_bf16(Bt[n][k], At[m][k], acc[ai][bj][m][n], 0, 0, 0); __builtin_amdgcn_s_setprio(0); } while (0)
; #define PG8_WAIT_V(n) asm volatile("s_waitcnt vmcnt(" #n ")" ::: "memory")
; #define PG8_WAIT_L(n) asm volatile("s_waitcnt lgkmcnt(" #n ")" ::: "memory")
; #define PG8_BAR __builtin_amdgcn_s_barrier()
; #define PG8_SCHED __builtin_amdgcn_sched_barrier(0)
; template <class Epi, class Sched, bool ALIGN_EPI = false, bool SP2 = false>
; __device__ __forceinline__ void gemm_phase(PG8_LAS unsigned char* lds, const Gemm g, const Sched& S, const Epi& E) {
;     ...
;             PG8_LDB(B0, 0, 0); PG8_LDB(B1, 0, 1); PG8_SCHED; PG8_LDA(At, 0, 0); PG8_STAGE(PG8_SA(1, 1), a1 + hstep, voffA);
;             PG8_WAIT_V(8); PG8_WAIT_L(0); PG8_BAR; PG8_MMA(0, 0, At, B0); PG8_MMA(0, 1, At, B1); PG8_BAR; PG8_SCHED;
.LBB0_901:
	s_andn2_b64 vcc, exec, s[16:17]
	s_cbranch_vccnz .LBB0_904
	s_add_u32 s4, s4, 0x80
	s_addc_u32 s5, s5, 0
	s_add_u32 s56, s28, 0x100
	s_addc_u32 s57, s29, 0
	s_mov_b32 s28, 0
	ds_read_b128 v[146:149], v169
	ds_read_b128 v[150:153], v169 offset:1024
	ds_read_b128 v[154:157], v169 offset:2048
	ds_read_b128 v[158:161], v169 offset:3072
	ds_read_b128 v[162:165], v170
	ds_read_b128 v[174:177], v170 offset:1024
	ds_read_b128 v[178:181], v170 offset:2048
	ds_read_b128 v[182:185], v170 offset:3072
	s_add_i32 s58, s28, 2
	s_add_u32 s59, s4, 0x80
	s_addc_u32 s29, s5, 0
	s_cmp_eq_u32 s47, s28
	s_cselect_b32 s28, s0, s59
	s_cselect_b32 s29, s1, s29
	s_cselect_b32 s61, s27, s57
	s_cselect_b32 s60, s26, s56
	v_lshl_add_u64 v[166:167], s[4:5], 0, v[138:139]
	s_add_i32 m0, s38, 0xc000
	ds_read_b128 v[186:189], v171
	ds_read_b128 v[190:193], v171 offset:1024
	ds_read_b128 v[194:197], v171 offset:2048
	ds_read_b128 v[202:205], v171 offset:3072
	ds_read_b128 v[206:209], v171 offset:4096
	ds_read_b128 v[210:213], v171 offset:5120
	ds_read_b128 v[214:217], v171 offset:6144
	ds_read_b128 v[218:221], v171 offset:7168
	global_load_lds_dwordx4 v[166:167], off
	v_lshl_add_u64 v[166:167], s[4:5], 0, v[140:141]
	s_add_i32 m0, s38, 0xe000
	s_nop 0
	global_load_lds_dwordx4 v[166:167], off
	s_cmp_eq_u32 s99, 0
	s_cbranch_scc1 .Lw8_4_0
	s_waitcnt vmcnt(16)
	s_branch .Lwj_4_0

; #define PG8_STAGE(bufoff, gbase, voff) do { _Pragma("unroll") for (int _i = 0; _i < 2; ++_i) \
;         __builtin_amdgcn_global_load_lds((const unsigned*)((const char*)(gbase) + (voff)[_i]), (PG8_LAS unsigned*)(lds + (bufoff) + ldsw + _i * 8192), 16, 0, 0); } while (0)
; #define PG8_LDA(dst, b, h) do { _Pragma("unroll") for (int m = 0; m < 4; ++m) _Pragma("unroll") for (int k = 0; k < 2; ++k) dst[m][k] = *(const PG8_LAS bf16x8*)(lds + PG8_SA(b, h) + aoff + m * 2048 + k * 1024); } while (0)
; #define PG8_LDB(dst, b, h) do { _Pragma("unroll") for (int n = 0; n < 2; ++n) _Pragma("unroll") for (int k = 0; k < 2; ++k) dst[n][k] = *(const PG8_LAS bf16x8*)(lds + PG8_SB(b, h) + boff + n * 2048 + k * 1024); } while (0)
; #define PG8_MMA(ai, bj, At, Bt) do { __builtin_amdgcn_s_setprio(1); _Pragma("unroll") for (int m = 0; m < 4; ++m) _Pragma("unroll") for (int n = 0; n < 2; ++n) _Pragma("unroll") for (int k = 0; k < 2; ++k) \
;         acc[ai][bj][m][n] = __builtin_amdgcn_mfma_f32_16x16x32_bf16(Bt[n][k], At[m][k], acc[ai][bj][m][n], 0, 0, 0); __builtin_amdgcn_s_setprio(0); } while (0)
; #define PG8_WAIT_V(n) asm volatile("s_waitcnt vmcnt(" #n ")" ::: "memory")
; #define PG8_WAIT_L(n) asm volatile("s_waitcnt lgkmcnt(" #n ")" ::: "memory")
; #define PG8_BAR __builtin_amdgcn_s_barrier()
; #define PG8_SCHED __builtin_amdgcn_sched_barrier(0)
; template <class Epi, class Sched, bool ALIGN_EPI = false, bool SP2 = false>
; __device__ __forceinline__ void gemm_phase(PG8_LAS unsigned char* lds, const Gemm g, const Sched& S, const Epi& E) {
;     ...
;             PG8_LDB(B0, 0, 0); PG8_LDB(B1, 0, 1); PG8_SCHED; PG8_LDA(At, 0, 0); PG8_STAGE(PG8_SA(1, 1), a1 + hstep, voffA);
;             PG8_WAIT_V(8); PG8_WAIT_L(0); PG8_BAR; PG8_MMA(0, 0, At, B0); PG8_MMA(0, 1, At, B1); PG8_BAR; PG8_SCHED;
;             PG8_LDA(At, 0, 1); PG8_STAGE(PG8_SB(0, 0), b2, voffB); PG8_STAGE(PG8_SB(0, 1), b2 + hstep, voffB); PG8_STAGE(PG8_SA(0, 0), a2, voffA);
;             PG8_WAIT_V(8); PG8_WAIT_L(0); PG8_BAR; PG8_MMA(1, 0, At, B0); PG8_MMA(1, 1, At, B1); PG8_BAR; PG8_SCHED;
.Lwj_4_0:
	s_waitcnt lgkmcnt(0)
	s_barrier
	s_setprio 1
	s_waitcnt lgkmcnt(0)
	v_mfma_f32_16x16x32_bf16 v[120:123], v[146:149], v[186:189], 0
	v_mfma_f32_16x16x32_bf16 v[124:127], v[154:157], v[186:189], 0
	v_mfma_f32_16x16x32_bf16 v[108:111], v[146:149], v[194:197], 0
	v_mfma_f32_16x16x32_bf16 v[104:107], v[154:157], v[194:197], 0
	v_mfma_f32_16x16x32_bf16 v[92:95], v[146:149], v[206:209], 0
	v_mfma_f32_16x16x32_bf16 v[88:91], v[154:157], v[206:209], 0
	v_mfma_f32_16x16x32_bf16 v[76:79], v[146:149], v[214:217], 0
	v_mfma_f32_16x16x32_bf16 v[72:75], v[154:157], v[214:217], 0
	v_mfma_f32_16x16x32_bf16 v[120:123], v[150:153], v[190:193], v[120:123]
	v_mfma_f32_16x16x32_bf16 v[124:127], v[158:161], v[190:193], v[124:127]
	v_mfma_f32_16x16x32_bf16 v[108:111], v[150:153], v[202:205], v[108:111]
	v_mfma_f32_16x16x32_bf16 v[104:107], v[158:161], v[202:205], v[104:107]
	v_mfma_f32_16x16x32_bf16 v[92:95], v[150:153], v[210:213], v[92:95]
	v_mfma_f32_16x16x32_bf16 v[88:91], v[158:161], v[210:213], v[88:91]
	v_mfma_f32_16x16x32_bf16 v[76:79], v[150:153], v[218:221], v[76:79]
	v_mfma_f32_16x16x32_bf16 v[72:75], v[158:161], v[218:221], v[72:75]
	s_setprio 0
	s_setprio 1
	v_mfma_f32_16x16x32_bf16 v[116:119], v[162:165], v[186:189], 0
	v_mfma_f32_16x16x32_bf16 v[112:115], v[178:181], v[186:189], 0
	v_mfma_f32_16x16x32_bf16 v[100:103], v[162:165], v[194:197], 0
	v_mfma_f32_16x16x32_bf16 v[96:99], v[178:181], v[194:197], 0
	v_mfma_f32_16x16x32_bf16 v[84:87], v[162:165], v[206:209], 0
	v_mfma_f32_16x16x32_bf16 v[80:83], v[178:181], v[206:209], 0
	v_mfma_f32_16x16x32_bf16 v[68:71], v[162:165], v[214:217], 0
	v_mfma_f32_16x16x32_bf16 v[64:67], v[178:181], v[214:217], 0
	v_mfma_f32_16x16x32_bf16 v[116:119], v[174:177], v[190:193], v[116:119]
	v_mfma_f32_16x16x32_bf16 v[112:115], v[182:185], v[190:193], v[112:115]
	v_mfma_f32_16x16x32_bf16 v[100:103], v[174:177], v[202:205], v[100:103]
	v_mfma_f32_16x16x32_bf16 v[96:99], v[182:185], v[202:205], v[96:99]
	v_mfma_f32_16x16x32_bf16 v[84:87], v[174:177], v[210:213], v[84:87]
	v_mfma_f32_16x16x32_bf16 v[80:83], v[182:185], v[210:213], v[80:83]
	v_mfma_f32_16x16x32_bf16 v[68:71], v[174:177], v[218:221], v[68:71]
	v_mfma_f32_16x16x32_bf16 v[64:67], v[182:185], v[218:221], v[64:67]
	s_setprio 0
	s_barrier
	s_add_i32 s59, s51, s37
	v_lshl_add_u64 v[166:167], s[60:61], 0, v[130:131]
	s_mov_b32 m0, s59
	ds_read_b128 v[186:189], v171 offset:16384
	ds_read_b128 v[190:193], v171 offset:17408
	ds_read_b128 v[194:197], v171 offset:18432
	ds_read_b128 v[202:205], v171 offset:19456
	ds_read_b128 v[206:209], v171 offset:20480
	ds_read_b128 v[210:213], v171 offset:21504
	ds_read_b128 v[214:217], v171 offset:22528
	ds_read_b128 v[218:221], v171 offset:23552
	global_load_lds_dwordx4 v[166:167], off
	s_add_i32 m0, s59, 0x2000
	v_lshl_add_u64 v[198:199], s[60:61], 0, v[134:135]
	s_add_u32 s60, s60, s6
	s_addc_u32 s61, s61, s7
	s_add_i32 s59, s52, s37
	global_load_lds_dwordx4 v[198:199], off
	v_lshl_add_u64 v[222:223], s[60:61], 0, v[130:131]
	s_mov_b32 m0, s59
	v_lshl_add_u64 v[224:225], s[60:61], 0, v[134:135]
	global_load_lds_dwordx4 v[222:223], off
	s_add_i32 m0, s59, 0x2000
	v_lshl_add_u64 v[226:227], s[28:29], 0, v[128:129]
	global_load_lds_dwordx4 v[224:225], off
	s_mov_b32 m0, s38
	v_lshl_add_u64 v[228:229], s[28:29], 0, v[132:133]
	global_load_lds_dwordx4 v[226:227], off
	s_mov_b32 m0, s39
	s_nop 0
	global_load_lds_dwordx4 v[228:229], off
	s_cmp_eq_u32 s99, 0
	s_cbranch_scc1 .Lw8_4_1
	s_waitcnt vmcnt(16)
	s_branch .Lwj_4_1

; #define PG8_STAGE(bufoff, gbase, voff) do { _Pragma("unroll") for (int _i = 0; _i < 2; ++_i) \
;         __builtin_amdgcn_global_load_lds((const unsigned*)((const char*)(gbase) + (voff)[_i]), (PG8_LAS unsigned*)(lds + (bufoff) + ldsw + _i * 8192), 16, 0, 0); } while (0)
; #define PG8_LDA(dst, b, h) do { _Pragma("unroll") for (int m = 0; m < 4; ++m) _Pragma("unroll") for (int k = 0; k < 2; ++k) dst[m][k] = *(const PG8_LAS bf16x8*)(lds + PG8_SA(b, h) + aoff + m * 2048 + k * 1024); } while (0)
; #define PG8_LDB(dst, b, h) do { _Pragma("unroll") for (int n = 0; n < 2; ++n) _Pragma("unroll") for (int k = 0; k < 2; ++k) dst[n][k] = *(const PG8_LAS bf16x8*)(lds + PG8_SB(b, h) + boff + n * 2048 + k * 1024); } while (0)
; #define PG8_MMA(ai, bj, At, Bt) do { __builtin_amdgcn_s_setprio(1); _Pragma("unroll") for (int m = 0; m < 4; ++m) _Pragma("unroll") for (int n = 0; n < 2; ++n) _Pragma("unroll") for (int k = 0; k < 2; ++k) \
;         acc[ai][bj][m][n] = __builtin_amdgcn_mfma_f32_16x16x32_bf16(Bt[n][k], At[m][k], acc[ai][bj][m][n], 0, 0, 0); __builtin_amdgcn_s_setprio(0); } while (0)
; #define PG8_WAIT_V(n) asm volatile("s_waitcnt vmcnt(" #n ")" ::: "memory")
; #define PG8_WAIT_L(n) asm volatile("s_waitcnt lgkmcnt(" #n ")" ::: "memory")
; #define PG8_BAR __builtin_amdgcn_s_barrier()
; #define PG8_SCHED __builtin_amdgcn_sched_barrier(0)
; template <class Epi, class Sched, bool ALIGN_EPI = false, bool SP2 = false>
; __device__ __forceinline__ void gemm_phase(PG8_LAS unsigned char* lds, const Gemm g, const Sched& S, const Epi& E) {
;     ...
;             PG8_WAIT_V(8); PG8_WAIT_L(0); PG8_BAR; PG8_MMA(1, 0, At, B0); PG8_MMA(1, 1, At, B1); PG8_BAR; PG8_SCHED;
;             PG8_LDB(B0, 1, 0); PG8_LDB(B1, 1, 1); PG8_SCHED; PG8_LDA(At, 1, 0); PG8_STAGE(PG8_SA(0, 1), a2 + hstep, voffA);
;             PG8_WAIT_V(8); PG8_WAIT_L(0); PG8_BAR; PG8_MMA(0, 0, At, B0); PG8_MMA(0, 1, At, B1); PG8_BAR; PG8_SCHED;
.Lwj_4_1:
	s_waitcnt lgkmcnt(0)
	s_barrier
	s_setprio 1
	s_waitcnt lgkmcnt(0)
	v_mfma_f32_16x16x32_bf16 v[60:63], v[146:149], v[186:189], 0
	v_mfma_f32_16x16x32_bf16 v[56:59], v[154:157], v[186:189], 0
	v_mfma_f32_16x16x32_bf16 v[44:47], v[146:149], v[194:197], 0
	v_mfma_f32_16x16x32_bf16 v[40:43], v[154:157], v[194:197], 0
	v_mfma_f32_16x16x32_bf16 v[28:31], v[146:149], v[206:209], 0
	v_mfma_f32_16x16x32_bf16 v[24:27], v[154:157], v[206:209], 0
	v_mfma_f32_16x16x32_bf16 v[12:15], v[146:149], v[214:217], 0
	v_mfma_f32_16x16x32_bf16 v[8:11], v[154:157], v[214:217], 0
	v_mfma_f32_16x16x32_bf16 v[60:63], v[150:153], v[190:193], v[60:63]
	v_mfma_f32_16x16x32_bf16 v[56:59], v[158:161], v[190:193], v[56:59]
	v_mfma_f32_16x16x32_bf16 v[44:47], v[150:153], v[202:205], v[44:47]
	v_mfma_f32_16x16x32_bf16 v[40:43], v[158:161], v[202:205], v[40:43]
	v_mfma_f32_16x16x32_bf16 v[28:31], v[150:153], v[210:213], v[28:31]
	v_mfma_f32_16x16x32_bf16 v[24:27], v[158:161], v[210:213], v[24:27]
	v_mfma_f32_16x16x32_bf16 v[12:15], v[150:153], v[218:221], v[12:15]
	v_mfma_f32_16x16x32_bf16 v[8:11], v[158:161], v[218:221], v[8:11]
	s_setprio 0
	s_setprio 1
	v_mfma_f32_16x16x32_bf16 v[52:55], v[162:165], v[186:189], 0
	v_mfma_f32_16x16x32_bf16 v[48:51], v[178:181], v[186:189], 0
	v_mfma_f32_16x16x32_bf16 v[36:39], v[162:165], v[194:197], 0
	v_mfma_f32_16x16x32_bf16 v[32:35], v[178:181], v[194:197], 0
	v_mfma_f32_16x16x32_bf16 v[20:23], v[162:165], v[206:209], 0
	v_mfma_f32_16x16x32_bf16 v[16:19], v[178:181], v[206:209], 0
	v_mfma_f32_16x16x32_bf16 v[0:3], v[162:165], v[214:217], 0
	v_mfma_f32_16x16x32_bf16 v[4:7], v[178:181], v[214:217], 0
	v_mfma_f32_16x16x32_bf16 v[52:55], v[174:177], v[190:193], v[52:55]
	v_mfma_f32_16x16x32_bf16 v[48:51], v[182:185], v[190:193], v[48:51]
	v_mfma_f32_16x16x32_bf16 v[36:39], v[174:177], v[202:205], v[36:39]
	v_mfma_f32_16x16x32_bf16 v[32:35], v[182:185], v[202:205], v[32:35]
	v_mfma_f32_16x16x32_bf16 v[20:23], v[174:177], v[210:213], v[20:23]
	v_mfma_f32_16x16x32_bf16 v[16:19], v[182:185], v[210:213], v[16:19]
	v_mfma_f32_16x16x32_bf16 v[0:3], v[174:177], v[218:221], v[0:3]
	v_mfma_f32_16x16x32_bf16 v[4:7], v[182:185], v[218:221], v[4:7]
	s_setprio 0
	s_barrier
	s_add_i32 s59, 0, 0x18000
	v_add_u32_e32 v136, s59, v168
	s_add_i32 s60, 0, 0x1c000
	ds_read_b128 v[146:149], v136
	ds_read_b128 v[150:153], v136 offset:1024
	ds_read_b128 v[154:157], v136 offset:2048
	ds_read_b128 v[158:161], v136 offset:3072
	v_add_u32_e32 v136, s60, v168
	ds_read_b128 v[162:165], v136
	ds_read_b128 v[174:177], v136 offset:1024
	ds_read_b128 v[178:181], v136 offset:2048
	ds_read_b128 v[182:185], v136 offset:3072
	s_add_u32 s28, s28, s6
	s_addc_u32 s29, s29, s7
	s_mov_b32 m0, s40
	v_lshl_add_u64 v[230:231], s[28:29], 0, v[128:129]
	ds_read_b128 v[186:189], v171 offset:32768
	ds_read_b128 v[190:193], v171 offset:33792
	ds_read_b128 v[194:197], v171 offset:34816
	ds_read_b128 v[202:205], v171 offset:35840
	ds_read_b128 v[206:209], v171 offset:36864
	ds_read_b128 v[210:213], v171 offset:37888
	ds_read_b128 v[214:217], v171 offset:38912
	ds_read_b128 v[218:221], v171 offset:39936
	global_load_lds_dwordx4 v[230:231], off
	v_lshl_add_u64 v[230:231], s[28:29], 0, v[132:133]
	s_mov_b32 m0, s41
	s_nop 0
	global_load_lds_dwordx4 v[230:231], off
	s_waitcnt vmcnt(8)
	s_waitcnt lgkmcnt(0)
	s_barrier
	s_setprio 1
	s_waitcnt lgkmcnt(0)
	v_mfma_f32_16x16x32_bf16 v[120:123], v[146:149], v[186:189], v[120:123]
	v_mfma_f32_16x16x32_bf16 v[124:127], v[154:157], v[186:189], v[124:127]
	v_mfma_f32_16x16x32_bf16 v[108:111], v[146:149], v[194:197], v[108:111]
	v_mfma_f32_16x16x32_bf16 v[104:107], v[154:157], v[194:197], v[104:107]
	v_mfma_f32_16x16x32_bf16 v[92:95], v[146:149], v[206:209], v[92:95]
	v_mfma_f32_16x16x32_bf16 v[88:91], v[154:157], v[206:209], v[88:91]
	v_mfma_f32_16x16x32_bf16 v[76:79], v[146:149], v[214:217], v[76:79]
	v_mfma_f32_16x16x32_bf16 v[72:75], v[154:157], v[214:217], v[72:75]
	v_mfma_f32_16x16x32_bf16 v[120:123], v[150:153], v[190:193], v[120:123]
	v_mfma_f32_16x16x32_bf16 v[124:127], v[158:161], v[190:193], v[124:127]
	v_mfma_f32_16x16x32_bf16 v[108:111], v[150:153], v[202:205], v[108:111]
	v_mfma_f32_16x16x32_bf16 v[104:107], v[158:161], v[202:205], v[104:107]
	v_mfma_f32_16x16x32_bf16 v[92:95], v[150:153], v[210:213], v[92:95]
	v_mfma_f32_16x16x32_bf16 v[88:91], v[158:161], v[210:213], v[88:91]
	v_mfma_f32_16x16x32_bf16 v[76:79], v[150:153], v[218:221], v[76:79]
	v_mfma_f32_16x16x32_bf16 v[72:75], v[158:161], v[218:221], v[72:75]
	s_setprio 0
	s_setprio 1
	v_mfma_f32_16x16x32_bf16 v[116:119], v[162:165], v[186:189], v[116:119]
	v_mfma_f32_16x16x32_bf16 v[112:115], v[178:181], v[186:189], v[112:115]
	v_mfma_f32_16x16x32_bf16 v[100:103], v[162:165], v[194:197], v[100:103]
	v_mfma_f32_16x16x32_bf16 v[96:99], v[178:181], v[194:197], v[96:99]
	v_mfma_f32_16x16x32_bf16 v[84:87], v[162:165], v[206:209], v[84:87]
	v_mfma_f32_16x16x32_bf16 v[80:83], v[178:181], v[206:209], v[80:83]
	v_mfma_f32_16x16x32_bf16 v[68:71], v[162:165], v[214:217], v[68:71]
	v_mfma_f32_16x16x32_bf16 v[64:67], v[178:181], v[214:217], v[64:67]
	v_mfma_f32_16x16x32_bf16 v[116:119], v[174:177], v[190:193], v[116:119]
	v_mfma_f32_16x16x32_bf16 v[112:115], v[182:185], v[190:193], v[112:115]
	v_mfma_f32_16x16x32_bf16 v[100:103], v[174:177], v[202:205], v[100:103]
	v_mfma_f32_16x16x32_bf16 v[96:99], v[182:185], v[202:205], v[96:99]
	v_mfma_f32_16x16x32_bf16 v[84:87], v[174:177], v[210:213], v[84:87]
	v_mfma_f32_16x16x32_bf16 v[80:83], v[182:185], v[210:213], v[80:83]
	v_mfma_f32_16x16x32_bf16 v[68:71], v[174:177], v[218:221], v[68:71]
	v_mfma_f32_16x16x32_bf16 v[64:67], v[182:185], v[218:221], v[64:67]
	s_setprio 0
	s_barrier
; #define PG8_STAGE(bufoff, gbase, voff) do { _Pragma("unroll") for (int _i = 0; _i < 2; ++_i) \
;         __builtin_amdgcn_global_load_lds((const unsigned*)((const char*)(gbase) + (voff)[_i]), (PG8_LAS unsigned*)(lds + (bufoff) + ldsw + _i * 8192), 16, 0, 0); } while (0)
; #define PG8_LDA(dst, b, h) do { _Pragma("unroll") for (int m = 0; m < 4; ++m) _Pragma("unroll") for (int k = 0; k < 2; ++k) dst[m][k] = *(const PG8_LAS bf16x8*)(lds + PG8_SA(b, h) + aoff + m * 2048 + k * 1024); } while (0)
; #define PG8_MMA(ai, bj, At, Bt) do { __builtin_amdgcn_s_setprio(1); _Pragma("unroll") for (int m = 0; m < 4; ++m) _Pragma("unroll") for (int n = 0; n < 2; ++n) _Pragma("unroll") for (int k = 0; k < 2; ++k) \
;         acc[ai][bj][m][n] = __builtin_amdgcn_mfma_f32_16x16x32_bf16(Bt[n][k], At[m][k], acc[ai][bj][m][n], 0, 0, 0); __builtin_amdgcn_s_setprio(0); } while (0)
; #define PG8_WAIT_V(n) asm volatile("s_waitcnt vmcnt(" #n ")" ::: "memory")
; #define PG8_WAIT_L(n) asm volatile("s_waitcnt lgkmcnt(" #n ")" ::: "memory")
; #define PG8_BAR __builtin_amdgcn_s_barrier()
; #define PG8_SCHED __builtin_amdgcn_sched_barrier(0)
; template <class Epi, class Sched, bool ALIGN_EPI = false, bool SP2 = false>
; __device__ __forceinline__ void gemm_phase(PG8_LAS unsigned char* lds, const Gemm g, const Sched& S, const Epi& E) {
;     ...
;         for (int t = 0; t < nt; t += 2) {
;     ...
;             PG8_LDA(At, 1, 1); PG8_STAGE(PG8_SB(1, 0), b3, voffB); PG8_STAGE(PG8_SB(1, 1), b3 + hstep, voffB); PG8_STAGE(PG8_SA(1, 0), a3, voffA);
;             PG8_WAIT_V(8); PG8_WAIT_L(0); PG8_BAR; PG8_MMA(1, 0, At, B0); PG8_MMA(1, 1, At, B1); PG8_BAR; PG8_SCHED;
	s_add_i32 s28, s59, s37
	v_lshl_add_u64 v[166:167], v[166:167], 0, s[14:15]
	s_mov_b32 m0, s28
	ds_read_b128 v[186:189], v171 offset:49152
	ds_read_b128 v[190:193], v171 offset:50176
	ds_read_b128 v[194:197], v171 offset:51200
	ds_read_b128 v[202:205], v171 offset:52224
	ds_read_b128 v[206:209], v171 offset:53248
	ds_read_b128 v[210:213], v171 offset:54272
	ds_read_b128 v[214:217], v171 offset:55296
	ds_read_b128 v[218:221], v171 offset:56320
	global_load_lds_dwordx4 v[166:167], off
	v_lshl_add_u64 v[166:167], v[198:199], 0, s[14:15]
	s_add_i32 m0, s28, 0x2000
	s_add_i32 s28, s60, s37
	global_load_lds_dwordx4 v[166:167], off
	v_lshl_add_u64 v[166:167], v[222:223], 0, s[14:15]
	s_mov_b32 m0, s28
	s_nop 0
	global_load_lds_dwordx4 v[166:167], off
	v_lshl_add_u64 v[166:167], v[224:225], 0, s[14:15]
	s_add_i32 m0, s28, 0x2000
	s_nop 0
	global_load_lds_dwordx4 v[166:167], off
	v_lshl_add_u64 v[166:167], v[226:227], 0, s[14:15]
	s_mov_b32 m0, s43
	s_nop 0
	global_load_lds_dwordx4 v[166:167], off
	v_lshl_add_u64 v[166:167], v[228:229], 0, s[14:15]
	s_mov_b32 m0, s44
	s_nop 0
	global_load_lds_dwordx4 v[166:167], off
	s_waitcnt vmcnt(8)
	s_waitcnt lgkmcnt(0)
	s_barrier
	s_setprio 1
	s_waitcnt lgkmcnt(0)
	v_mfma_f32_16x16x32_bf16 v[60:63], v[146:149], v[186:189], v[60:63]
	v_mfma_f32_16x16x32_bf16 v[56:59], v[154:157], v[186:189], v[56:59]
	v_mfma_f32_16x16x32_bf16 v[44:47], v[146:149], v[194:197], v[44:47]
	v_mfma_f32_16x16x32_bf16 v[40:43], v[154:157], v[194:197], v[40:43]
	v_mfma_f32_16x16x32_bf16 v[28:31], v[146:149], v[206:209], v[28:31]
	v_mfma_f32_16x16x32_bf16 v[24:27], v[154:157], v[206:209], v[24:27]
	v_mfma_f32_16x16x32_bf16 v[12:15], v[146:149], v[214:217], v[12:15]
	v_mfma_f32_16x16x32_bf16 v[8:11], v[154:157], v[214:217], v[8:11]
	v_mfma_f32_16x16x32_bf16 v[60:63], v[150:153], v[190:193], v[60:63]
	v_mfma_f32_16x16x32_bf16 v[56:59], v[158:161], v[190:193], v[56:59]
	v_mfma_f32_16x16x32_bf16 v[44:47], v[150:153], v[202:205], v[44:47]
	v_mfma_f32_16x16x32_bf16 v[40:43], v[158:161], v[202:205], v[40:43]
	v_mfma_f32_16x16x32_bf16 v[28:31], v[150:153], v[210:213], v[28:31]
	v_mfma_f32_16x16x32_bf16 v[24:27], v[158:161], v[210:213], v[24:27]
	v_mfma_f32_16x16x32_bf16 v[12:15], v[150:153], v[218:221], v[12:15]
	v_mfma_f32_16x16x32_bf16 v[8:11], v[158:161], v[218:221], v[8:11]
	s_setprio 0
	s_setprio 1
	v_mfma_f32_16x16x32_bf16 v[52:55], v[162:165], v[186:189], v[52:55]
	v_mfma_f32_16x16x32_bf16 v[48:51], v[178:181], v[186:189], v[48:51]
	v_mfma_f32_16x16x32_bf16 v[36:39], v[162:165], v[194:197], v[36:39]
	v_mfma_f32_16x16x32_bf16 v[32:35], v[178:181], v[194:197], v[32:35]
	v_mfma_f32_16x16x32_bf16 v[20:23], v[162:165], v[206:209], v[20:23]
	v_mfma_f32_16x16x32_bf16 v[16:19], v[178:181], v[206:209], v[16:19]
	v_mfma_f32_16x16x32_bf16 v[0:3], v[162:165], v[214:217], v[0:3]
	v_mfma_f32_16x16x32_bf16 v[4:7], v[178:181], v[214:217], v[4:7]
	v_mfma_f32_16x16x32_bf16 v[52:55], v[174:177], v[190:193], v[52:55]
	v_mfma_f32_16x16x32_bf16 v[48:51], v[182:185], v[190:193], v[48:51]
	v_mfma_f32_16x16x32_bf16 v[36:39], v[174:177], v[202:205], v[36:39]
	v_mfma_f32_16x16x32_bf16 v[32:35], v[182:185], v[202:205], v[32:35]
	v_mfma_f32_16x16x32_bf16 v[20:23], v[174:177], v[210:213], v[20:23]
	v_mfma_f32_16x16x32_bf16 v[16:19], v[182:185], v[210:213], v[16:19]
	v_mfma_f32_16x16x32_bf16 v[0:3], v[174:177], v[218:221], v[0:3]
	v_mfma_f32_16x16x32_bf16 v[4:7], v[182:185], v[218:221], v[4:7]
	s_setprio 0
	s_barrier
	s_add_u32 s4, s4, 0x100
	s_addc_u32 s5, s5, 0
	s_add_u32 s56, s56, 0x100
	s_addc_u32 s57, s57, 0
	s_cmp_ge_i32 s58, s45
	s_mov_b32 s28, s58
	s_cbranch_scc1 .LBB0_904

;     __device__ __forceinline__ void operator()(const AccT& acc, const Unit& u, int wr, int wc, int fr_, int fq_) const {
;     ...
;         bf16_t* const KN = (bf16_t*)(ws + WS_RA); bf16_t* const VI = (bf16_t*)(ws + WS_VIMG); const float* const ssq_kv = (const float*)(ws + WS_SSQ) + T;
;         float ssv[2][4];
; #pragma unroll
;         for (int ai = 0; ai < 2; ++ai)
; #pragma unroll
;             for (int m = 0; m < 4; ++m) ssv[ai][m] = ssq_kv[(size_t)ROW_OF(ai, m)];
; #pragma unroll
;         for (int ai = 0; ai < 2; ++ai)
; #pragma unroll
;             for (int m = 0; m < 4; ++m) {
;                 const size_t row = (size_t)ROW_OF(ai, m);
;                 const float sc = __builtin_amdgcn_rsqf(ssv[ai][m] * (1.0f / KVLORA) + EPS);
;                 const int b = (int)(row >> 11), s = (int)(row & 2047);
;                 const f32x4 a0 = acc[ai][0][m][0] * sc, a1 = acc[ai][0][m][1] * sc, b0 = acc[ai][1][m][0] * sc, b1 = acc[ai][1][m][1] * sc;
;                 if (pn < 4) {
.LBB0_906:
	s_mov_b32 s99, 1
	s_lshl_b32 s4, s31, 8
	v_mov_b32_e32 v167, v201
	v_mov_b32_e32 v173, v232
	s_add_i32 s4, s4, s46
	s_cmp_gt_i32 s30, 3
	v_add_u32_e32 v162, s4, v167
	v_ashrrev_i32_e32 v163, 31, v162
	v_lshl_add_u64 v[146:147], v[162:163], 2, s[22:23]
	v_add_u32_e32 v160, 16, v162
	v_mov_b32_e32 v166, v245
	v_ashrrev_i32_e32 v161, 31, v160
	v_add_u32_e32 v158, 32, v162
	v_add_u32_e32 v156, 48, v162
	v_add_u32_e32 v154, 0x80, v162
	v_add_u32_e32 v152, 0x90, v162
	v_add_u32_e32 v150, 0xa0, v162
	v_add_u32_e32 v146, 0xb0, v162
	v_lshl_add_u64 v[148:149], v[160:161], 2, s[22:23]
	v_ashrrev_i32_e32 v159, 31, v158
	v_ashrrev_i32_e32 v157, 31, v156
	v_ashrrev_i32_e32 v155, 31, v154
	v_ashrrev_i32_e32 v153, 31, v152
	v_ashrrev_i32_e32 v151, 31, v150
	v_ashrrev_i32_e32 v147, 31, v146
	v_lshl_add_u64 v[164:165], v[158:159], 2, s[22:23]
	v_lshl_add_u64 v[174:175], v[156:157], 2, s[22:23]
	v_lshl_add_u64 v[176:177], v[154:155], 2, s[22:23]
	v_lshl_add_u64 v[178:179], v[152:153], 2, s[22:23]
	v_lshl_add_u64 v[180:181], v[150:151], 2, s[22:23]
	v_lshl_add_u64 v[182:183], v[146:147], 2, s[22:23]
	v_mov_b32_e32 v161, v246
	v_mov_b32_e32 v159, v247
	v_mov_b32_e32 v157, v248
	v_mov_b32_e32 v155, v249
	v_mov_b32_e32 v153, v250
	v_mov_b32_e32 v151, v251
	v_mov_b32_e32 v147, v252
	v_lshlrev_b32_e32 v136, 6, v167
	v_lshlrev_b32_e32 v148, 3, v173
	v_and_b32_e32 v136, 0x1c0, v136
	s_cselect_b64 s[28:29], -1, 0
	s_lshl_b32 s56, s30, 9
	v_ashrrev_i32_e32 v149, 31, v148
	v_lshl_add_u64 v[174:175], s[24:25], 0, v[136:137]
	s_mov_b64 s[4:5], -1
	v_and_b32_e32 v163, 0x7ff, v162
	s_addk_i32 s56, 0xf800
	s_and_b64 vcc, exec, s[28:29]
	v_lshl_add_u64 v[148:149], v[148:149], 1, v[174:175]
	v_lshl_add_u32 v253, s55, 8, v201
	v_add_lshl_u32 v253, v253, s46, 2
	global_load_dword v245, v253, s[22:23]
	global_load_dword v246, v253, s[22:23] offset:64
	global_load_dword v247, v253, s[22:23] offset:128
	global_load_dword v248, v253, s[22:23] offset:192
	global_load_dword v249, v253, s[22:23] offset:512
	global_load_dword v250, v253, s[22:23] offset:576
	global_load_dword v251, v253, s[22:23] offset:640
	global_load_dword v252, v253, s[22:23] offset:704
	s_waitcnt vmcnt(8)
	v_fmamk_f32 v166, v166, 0x3b800000, v172
	v_rsq_f32_e32 v166, v166
	s_nop 0
	v_pk_mul_f32 v[122:123], v[122:123], v[166:167] op_sel_hi:[1,0]
	v_pk_mul_f32 v[120:121], v[120:121], v[166:167] op_sel_hi:[1,0]
	v_pk_mul_f32 v[126:127], v[126:127], v[166:167] op_sel_hi:[1,0]
	v_pk_mul_f32 v[124:125], v[124:125], v[166:167] op_sel_hi:[1,0]
	v_cvt_pk_bf16_f32 v120, v120, v121
	v_cvt_pk_bf16_f32 v121, v122, v123
	v_cvt_pk_bf16_f32 v122, v124, v125
	v_cvt_pk_bf16_f32 v123, v126, v127
	s_cbranch_vccz .LBB0_908
	v_and_b32_e32 v124, 0xfffff800, v162
	v_add_u32_e32 v124, s56, v124
	v_lshrrev_b32_e32 v125, 3, v163
	v_or_b32_e32 v124, v124, v125
	v_ashrrev_i32_e32 v125, 31, v124
	v_lshlrev_b64 v[124:125], 11, v[124:125]
	v_lshl_add_u64 v[164:165], v[148:149], 0, v[124:125]
	global_store_dwordx4 v[164:165], v[120:123], off nt
	s_mov_b64 s[4:5], 0

; #define PG8_STAGE(bufoff, gbase, voff) do { _Pragma("unroll") for (int _i = 0; _i < 2; ++_i) \
;         __builtin_amdgcn_global_load_lds((const unsigned*)((const char*)(gbase) + (voff)[_i]), (PG8_LAS unsigned*)(lds + (bufoff) + ldsw + _i * 8192), 16, 0, 0); } while (0)
; #define PG8_WAIT_V(n) asm volatile("s_waitcnt vmcnt(" #n ")" ::: "memory")
; #define PG8_BAR __builtin_amdgcn_s_barrier()
; template <class Epi, class Sched, bool ALIGN_EPI = false, bool SP2 = false>
; __device__ __forceinline__ void gemm_phase(PG8_LAS unsigned char* lds, const Gemm g, const Sched& S, const Epi& E) {
;     ...
;     if constexpr (SP2) {
;         PG8_STAGE(PG8_SB(0, 0), cB, voffB); PG8_STAGE(PG8_SB(0, 1), cB + hstep, voffB); PG8_STAGE(PG8_SA(0, 0), cA, voffA); PG8_STAGE(PG8_SA(0, 1), cA + hstep, voffA);
;         if (wr == 1) PG8_BAR;
;         PG8_WAIT_V(2); PG8_BAR;
;         PG8_STAGE(PG8_SB(1, 0), cB + kstep, voffB); PG8_STAGE(PG8_SA(1, 0), cA + kstep, voffA); PG8_STAGE(PG8_SB(1, 1), cB + hstep + kstep, voffB);
;         PG8_WAIT_V(6); PG8_BAR;
;     __device__ __forceinline__ void operator()(const AccT& acc, const Unit& u, int wr, int wc, int fr_, int fq_) const {
;     ...
;         float ssv[2][4];
; #pragma unroll
;         for (int ai = 0; ai < 2; ++ai)
; #pragma unroll
;             for (int m = 0; m < 4; ++m) ssv[ai][m] = ssq_q[(size_t)ROW_OF(ai, m)];
.LBB0_999:
	s_mov_b64 s[18:19], 0x80
	s_add_i32 m0, s37, 0x18000
	v_lshl_add_u64 v[8:9], v[8:9], 0, s[18:19]
	s_waitcnt vmcnt(2)
	s_barrier
	global_load_lds_dwordx4 v[8:9], off
	v_lshl_add_u64 v[4:5], v[4:5], 0, s[18:19]
	s_add_i32 m0, s37, 0x1a000
	s_add_i32 s42, s37, 0x8000
	global_load_lds_dwordx4 v[4:5], off
	v_lshl_add_u64 v[4:5], v[6:7], 0, s[18:19]
	s_mov_b32 m0, s42
	s_add_i32 s43, s37, 0xa000
	global_load_lds_dwordx4 v[4:5], off
	v_lshl_add_u64 v[4:5], v[10:11], 0, s[18:19]
	s_mov_b32 m0, s43
	v_lshl_add_u64 v[2:3], v[2:3], 0, s[18:19]
	global_load_lds_dwordx4 v[4:5], off
	s_add_i32 m0, s37, 0x1c000
	v_lshl_add_u64 v[0:1], v[0:1], 0, s[18:19]
	global_load_lds_dwordx4 v[2:3], off
	s_add_i32 m0, s37, 0x1e000
	s_lshr_b32 s1, s1, 26
	global_load_lds_dwordx4 v[0:1], off
	s_add_i32 s1, s0, s1
	v_lshlrev_b32_e32 v1, 2, v201
	s_ashr_i32 s44, s1, 6
	v_lshl_or_b32 v0, v201, 6, v238
	s_lshl_b32 s1, s3, 13
	v_and_b32_e32 v1, 32, v1
	v_bitop3_b32 v0, v0, s1, v1 bitop3:0xde
	v_add_u32_e32 v1, v237, v235
	s_and_b32 s2, s2, 3
	s_lshl_b32 s45, s3, 6
	v_mul_lo_u32 v1, s0, v1
	s_cmp_gt_i32 s0, 63
	v_lshlrev_b32_e32 v1, 1, v1
	s_cselect_b64 s[20:21], -1, 0
	s_add_i32 s46, s44, -2
	v_add3_u32 v168, v233, v1, v234
	v_add_u32_e32 v1, v236, v235
	s_cmpk_lt_u32 s11, 0x100
	v_mul_lo_u32 v1, s0, v1
	s_waitcnt vmcnt(6)
	s_cselect_b64 s[22:23], -1, 0
	s_add_u32 s24, s90, 0x100000
	v_lshlrev_b32_e32 v1, 1, v1
	v_lshl_or_b32 v194, s2, 12, v239
	s_addc_u32 s25, s91, 0
	s_lshl_b32 s1, s2, 6
	v_lshl_add_u64 v[170:171], s[12:13], 0, v[168:169]
	v_add3_u32 v168, v233, v1, v234
	s_add_i32 s52, 0, 0x10000
	s_add_i32 s53, 0, 0x14000
	s_or_b32 s47, s1, 0xfffffc00
	s_lshl_b32 s48, s2, 2
	s_ashr_i32 s49, s83, 31
	s_ashr_i32 s50, s80, 31
	v_lshl_add_u64 v[172:173], s[12:13], 0, v[168:169]
	v_mov_b64_e32 v[174:175], 0x300
	v_mov_b64_e32 v[176:177], 0x2ff
	s_movk_i32 s51, 0x61
	v_add_u32_e32 v195, s52, v194
	v_add_u32_e32 v196, s53, v194
	v_add_u32_e32 v197, 0, v0
	v_mov_b32_e32 v198, 0x358637bd
	s_movk_i32 s54, 0x3000
	s_barrier
	v_lshl_add_u32 v253, s10, 8, v201
	v_add_lshl_u32 v253, v253, s45, 2
	global_load_dword v245, v253, s[90:91]
	global_load_dword v246, v253, s[90:91] offset:64
	global_load_dword v247, v253, s[90:91] offset:128
	global_load_dword v248, v253, s[90:91] offset:192
	global_load_dword v249, v253, s[90:91] offset:512
	global_load_dword v250, v253, s[90:91] offset:576
	global_load_dword v251, v253, s[90:91] offset:640
	global_load_dword v252, v253, s[90:91] offset:704
	s_mov_b32 s99, 0
	s_branch .LBB0_1002

; #define PG8_STAGE(bufoff, gbase, voff) do { _Pragma("unroll") for (int _i = 0; _i < 2; ++_i) \
;         __builtin_amdgcn_global_load_lds((const unsigned*)((const char*)(gbase) + (voff)[_i]), (PG8_LAS unsigned*)(lds + (bufoff) + ldsw + _i * 8192), 16, 0, 0); } while (0)
; #define PG8_LDA(dst, b, h) do { _Pragma("unroll") for (int m = 0; m < 4; ++m) _Pragma("unroll") for (int k = 0; k < 2; ++k) dst[m][k] = *(const PG8_LAS bf16x8*)(lds + PG8_SA(b, h) + aoff + m * 2048 + k * 1024); } while (0)
; #define PG8_LDB(dst, b, h) do { _Pragma("unroll") for (int n = 0; n < 2; ++n) _Pragma("unroll") for (int k = 0; k < 2; ++k) dst[n][k] = *(const PG8_LAS bf16x8*)(lds + PG8_SB(b, h) + boff + n * 2048 + k * 1024); } while (0)
; #define PG8_MMA(ai, bj, At, Bt) do { __builtin_amdgcn_s_setprio(1); _Pragma("unroll") for (int m = 0; m < 4; ++m) _Pragma("unroll") for (int n = 0; n < 2; ++n) _Pragma("unroll") for (int k = 0; k < 2; ++k) \
;         acc[ai][bj][m][n] = __builtin_amdgcn_mfma_f32_16x16x32_bf16(Bt[n][k], At[m][k], acc[ai][bj][m][n], 0, 0, 0); __builtin_amdgcn_s_setprio(0); } while (0)
; #define PG8_WAIT_V(n) asm volatile("s_waitcnt vmcnt(" #n ")" ::: "memory")
; #define PG8_WAIT_L(n) asm volatile("s_waitcnt lgkmcnt(" #n ")" ::: "memory")
; #define PG8_BAR __builtin_amdgcn_s_barrier()
; #define PG8_SCHED __builtin_amdgcn_sched_barrier(0)
; template <class Epi, class Sched, bool ALIGN_EPI = false, bool SP2 = false>
; __device__ __forceinline__ void gemm_phase(PG8_LAS unsigned char* lds, const Gemm g, const Sched& S, const Epi& E) {
;     ...
;         for (int t = 0; t < nt; t += 2) {
;             if constexpr (Epi::HAS_MID) { if (t == Epi::MID_T) E.mid(acc, cur, wr, wc, fr, fq); }
;             const bool last = (t == nt - 2);
;             const char* a1 = cA + (size_t)(t + 1) * kstep;
;             const char* a2 = last ? nA : cA + (size_t)(t + 2) * kstep; const char* b2 = last ? nB : cB + (size_t)(t + 2) * kstep;
;             const char* a3 = a2 + kstep; const char* b3 = b2 + kstep;
;             if (last && has_next) S.a_ready(nxt);
;             if constexpr (SP2) {
;             PG8_LDB(B0, 0, 0); PG8_LDB(B1, 0, 1); PG8_SCHED; PG8_LDA(At, 0, 0); PG8_STAGE(PG8_SA(1, 1), a1 + hstep, voffA);
;             PG8_WAIT_V(8); PG8_WAIT_L(0); PG8_BAR; PG8_MMA(0, 0, At, B0); PG8_MMA(0, 1, At, B1); PG8_BAR; PG8_SCHED;
.LBB0_1008:
	s_waitcnt vmcnt(0)
	s_andn2_b64 vcc, exec, s[20:21]
	s_cbranch_vccnz .LBB0_1011
	s_add_u32 s4, s4, 0x80
	s_addc_u32 s5, s5, 0
	s_add_u32 s11, s6, 0x100
	s_addc_u32 s29, s7, 0
	s_mov_b32 s6, 0
	ds_read_b128 v[128:131], v195
	ds_read_b128 v[132:135], v195 offset:1024
	ds_read_b128 v[136:139], v195 offset:2048
	ds_read_b128 v[140:143], v195 offset:3072
	ds_read_b128 v[144:147], v196
	ds_read_b128 v[148:151], v196 offset:1024
	ds_read_b128 v[152:155], v196 offset:2048
	ds_read_b128 v[156:159], v196 offset:3072
	s_add_i32 s56, s6, 2
	s_add_u32 s57, s4, 0x80
	s_addc_u32 s7, s5, 0
	s_cmp_eq_u32 s46, s6
	s_cselect_b32 s6, s0, s57
	s_cselect_b32 s7, s1, s7
	s_cselect_b32 s59, s27, s29
	s_cselect_b32 s58, s26, s11
	v_lshl_add_u64 v[218:219], s[4:5], 0, v[170:171]
	s_add_i32 m0, s37, 0xc000
	ds_read_b128 v[178:181], v197
	ds_read_b128 v[182:185], v197 offset:1024
	ds_read_b128 v[186:189], v197 offset:2048
	ds_read_b128 v[190:193], v197 offset:3072
	ds_read_b128 v[202:205], v197 offset:4096
	ds_read_b128 v[206:209], v197 offset:5120
	ds_read_b128 v[210:213], v197 offset:6144
	ds_read_b128 v[214:217], v197 offset:7168
	global_load_lds_dwordx4 v[218:219], off
	v_lshl_add_u64 v[218:219], s[4:5], 0, v[172:173]
	s_add_i32 m0, s37, 0xe000
	s_nop 0
	global_load_lds_dwordx4 v[218:219], off
	s_cmp_eq_u32 s99, 0
	s_cbranch_scc1 .Lw8_5_0
	s_waitcnt vmcnt(16)
	s_branch .Lwj_5_0

; #define PG8_STAGE(bufoff, gbase, voff) do { _Pragma("unroll") for (int _i = 0; _i < 2; ++_i) \
;         __builtin_amdgcn_global_load_lds((const unsigned*)((const char*)(gbase) + (voff)[_i]), (PG8_LAS unsigned*)(lds + (bufoff) + ldsw + _i * 8192), 16, 0, 0); } while (0)
; #define PG8_LDA(dst, b, h) do { _Pragma("unroll") for (int m = 0; m < 4; ++m) _Pragma("unroll") for (int k = 0; k < 2; ++k) dst[m][k] = *(const PG8_LAS bf16x8*)(lds + PG8_SA(b, h) + aoff + m * 2048 + k * 1024); } while (0)
; #define PG8_MMA(ai, bj, At, Bt) do { __builtin_amdgcn_s_setprio(1); _Pragma("unroll") for (int m = 0; m < 4; ++m) _Pragma("unroll") for (int n = 0; n < 2; ++n) _Pragma("unroll") for (int k = 0; k < 2; ++k) \
;         acc[ai][bj][m][n] = __builtin_amdgcn_mfma_f32_16x16x32_bf16(Bt[n][k], At[m][k], acc[ai][bj][m][n], 0, 0, 0); __builtin_amdgcn_s_setprio(0); } while (0)
; #define PG8_WAIT_V(n) asm volatile("s_waitcnt vmcnt(" #n ")" ::: "memory")
; #define PG8_WAIT_L(n) asm volatile("s_waitcnt lgkmcnt(" #n ")" ::: "memory")
; #define PG8_BAR __builtin_amdgcn_s_barrier()
; #define PG8_SCHED __builtin_amdgcn_sched_barrier(0)
; template <class Epi, class Sched, bool ALIGN_EPI = false, bool SP2 = false>
; __device__ __forceinline__ void gemm_phase(PG8_LAS unsigned char* lds, const Gemm g, const Sched& S, const Epi& E) {
;     ...
;             PG8_WAIT_V(8); PG8_WAIT_L(0); PG8_BAR; PG8_MMA(0, 0, At, B0); PG8_MMA(0, 1, At, B1); PG8_BAR; PG8_SCHED;
;             PG8_LDA(At, 0, 1); PG8_STAGE(PG8_SB(0, 0), b2, voffB); PG8_STAGE(PG8_SB(0, 1), b2 + hstep, voffB); PG8_STAGE(PG8_SA(0, 0), a2, voffA);
.Lwj_5_0:
	s_waitcnt lgkmcnt(0)
	s_barrier
	s_setprio 1
	s_waitcnt lgkmcnt(0)
	v_mfma_f32_16x16x32_bf16 v[124:127], v[128:131], v[178:181], 0
	v_mfma_f32_16x16x32_bf16 v[120:123], v[136:139], v[178:181], 0
	v_mfma_f32_16x16x32_bf16 v[108:111], v[128:131], v[186:189], 0
	v_mfma_f32_16x16x32_bf16 v[104:107], v[136:139], v[186:189], 0
	v_mfma_f32_16x16x32_bf16 v[92:95], v[128:131], v[202:205], 0
	v_mfma_f32_16x16x32_bf16 v[88:91], v[136:139], v[202:205], 0
	v_mfma_f32_16x16x32_bf16 v[76:79], v[128:131], v[210:213], 0
	v_mfma_f32_16x16x32_bf16 v[72:75], v[136:139], v[210:213], 0
	v_mfma_f32_16x16x32_bf16 v[124:127], v[132:135], v[182:185], v[124:127]
	v_mfma_f32_16x16x32_bf16 v[120:123], v[140:143], v[182:185], v[120:123]
	v_mfma_f32_16x16x32_bf16 v[108:111], v[132:135], v[190:193], v[108:111]
	v_mfma_f32_16x16x32_bf16 v[104:107], v[140:143], v[190:193], v[104:107]
	v_mfma_f32_16x16x32_bf16 v[92:95], v[132:135], v[206:209], v[92:95]
	v_mfma_f32_16x16x32_bf16 v[88:91], v[140:143], v[206:209], v[88:91]
	v_mfma_f32_16x16x32_bf16 v[76:79], v[132:135], v[214:217], v[76:79]
	v_mfma_f32_16x16x32_bf16 v[72:75], v[140:143], v[214:217], v[72:75]
	s_setprio 0
	s_setprio 1
	v_mfma_f32_16x16x32_bf16 v[116:119], v[144:147], v[178:181], 0
	v_mfma_f32_16x16x32_bf16 v[112:115], v[152:155], v[178:181], 0
	v_mfma_f32_16x16x32_bf16 v[100:103], v[144:147], v[186:189], 0
	v_mfma_f32_16x16x32_bf16 v[96:99], v[152:155], v[186:189], 0
	v_mfma_f32_16x16x32_bf16 v[84:87], v[144:147], v[202:205], 0
	v_mfma_f32_16x16x32_bf16 v[80:83], v[152:155], v[202:205], 0
	v_mfma_f32_16x16x32_bf16 v[68:71], v[144:147], v[210:213], 0
	v_mfma_f32_16x16x32_bf16 v[64:67], v[152:155], v[210:213], 0
	v_mfma_f32_16x16x32_bf16 v[116:119], v[148:151], v[182:185], v[116:119]
	v_mfma_f32_16x16x32_bf16 v[112:115], v[156:159], v[182:185], v[112:115]
	v_mfma_f32_16x16x32_bf16 v[100:103], v[148:151], v[190:193], v[100:103]
	v_mfma_f32_16x16x32_bf16 v[96:99], v[156:159], v[190:193], v[96:99]
	v_mfma_f32_16x16x32_bf16 v[84:87], v[148:151], v[206:209], v[84:87]
	v_mfma_f32_16x16x32_bf16 v[80:83], v[156:159], v[206:209], v[80:83]
	v_mfma_f32_16x16x32_bf16 v[68:71], v[148:151], v[214:217], v[68:71]
	v_mfma_f32_16x16x32_bf16 v[64:67], v[156:159], v[214:217], v[64:67]
	s_setprio 0
	s_barrier
	s_add_i32 s57, s52, s36
	v_lshl_add_u64 v[218:219], s[58:59], 0, v[162:163]
	s_mov_b32 m0, s57
	ds_read_b128 v[178:181], v197 offset:16384
	ds_read_b128 v[182:185], v197 offset:17408
	ds_read_b128 v[186:189], v197 offset:18432
	ds_read_b128 v[190:193], v197 offset:19456
	ds_read_b128 v[202:205], v197 offset:20480
	ds_read_b128 v[206:209], v197 offset:21504
	ds_read_b128 v[210:213], v197 offset:22528
	ds_read_b128 v[214:217], v197 offset:23552
	global_load_lds_dwordx4 v[218:219], off
	s_add_i32 m0, s57, 0x2000
	v_lshl_add_u64 v[220:221], s[58:59], 0, v[166:167]
	s_add_u32 s58, s58, s12
	s_addc_u32 s59, s59, s13
	s_add_i32 s57, s53, s36
	global_load_lds_dwordx4 v[220:221], off
	v_lshl_add_u64 v[222:223], s[58:59], 0, v[162:163]
	s_mov_b32 m0, s57
	v_lshl_add_u64 v[224:225], s[58:59], 0, v[166:167]
	global_load_lds_dwordx4 v[222:223], off
	s_add_i32 m0, s57, 0x2000
	v_lshl_add_u64 v[226:227], s[6:7], 0, v[160:161]
	global_load_lds_dwordx4 v[224:225], off
	s_mov_b32 m0, s37
	v_lshl_add_u64 v[228:229], s[6:7], 0, v[164:165]
	global_load_lds_dwordx4 v[226:227], off
	s_mov_b32 m0, s38
	s_nop 0
	global_load_lds_dwordx4 v[228:229], off
	s_cmp_eq_u32 s99, 0
	s_cbranch_scc1 .Lw8_5_1
	s_waitcnt vmcnt(16)
	s_branch .Lwj_5_1

; #define PG8_STAGE(bufoff, gbase, voff) do { _Pragma("unroll") for (int _i = 0; _i < 2; ++_i) \
;         __builtin_amdgcn_global_load_lds((const unsigned*)((const char*)(gbase) + (voff)[_i]), (PG8_LAS unsigned*)(lds + (bufoff) + ldsw + _i * 8192), 16, 0, 0); } while (0)
; #define PG8_LDA(dst, b, h) do { _Pragma("unroll") for (int m = 0; m < 4; ++m) _Pragma("unroll") for (int k = 0; k < 2; ++k) dst[m][k] = *(const PG8_LAS bf16x8*)(lds + PG8_SA(b, h) + aoff + m * 2048 + k * 1024); } while (0)
; #define PG8_LDB(dst, b, h) do { _Pragma("unroll") for (int n = 0; n < 2; ++n) _Pragma("unroll") for (int k = 0; k < 2; ++k) dst[n][k] = *(const PG8_LAS bf16x8*)(lds + PG8_SB(b, h) + boff + n * 2048 + k * 1024); } while (0)
; #define PG8_MMA(ai, bj, At, Bt) do { __builtin_amdgcn_s_setprio(1); _Pragma("unroll") for (int m = 0; m < 4; ++m) _Pragma("unroll") for (int n = 0; n < 2; ++n) _Pragma("unroll") for (int k = 0; k < 2; ++k) \
;         acc[ai][bj][m][n] = __builtin_amdgcn_mfma_f32_16x16x32_bf16(Bt[n][k], At[m][k], acc[ai][bj][m][n], 0, 0, 0); __builtin_amdgcn_s_setprio(0); } while (0)
; #define PG8_WAIT_V(n) asm volatile("s_waitcnt vmcnt(" #n ")" ::: "memory")
; #define PG8_WAIT_L(n) asm volatile("s_waitcnt lgkmcnt(" #n ")" ::: "memory")
; #define PG8_BAR __builtin_amdgcn_s_barrier()
; #define PG8_SCHED __builtin_amdgcn_sched_barrier(0)
; template <class Epi, class Sched, bool ALIGN_EPI = false, bool SP2 = false>
; __device__ __forceinline__ void gemm_phase(PG8_LAS unsigned char* lds, const Gemm g, const Sched& S, const Epi& E) {
;     ...
;             PG8_WAIT_V(8); PG8_WAIT_L(0); PG8_BAR; PG8_MMA(1, 0, At, B0); PG8_MMA(1, 1, At, B1); PG8_BAR; PG8_SCHED;
;             PG8_LDB(B0, 1, 0); PG8_LDB(B1, 1, 1); PG8_SCHED; PG8_LDA(At, 1, 0); PG8_STAGE(PG8_SA(0, 1), a2 + hstep, voffA);
;             PG8_WAIT_V(8); PG8_WAIT_L(0); PG8_BAR; PG8_MMA(0, 0, At, B0); PG8_MMA(0, 1, At, B1); PG8_BAR; PG8_SCHED;
.Lwj_5_1:
	s_waitcnt lgkmcnt(0)
	s_barrier
	s_setprio 1
	s_waitcnt lgkmcnt(0)
	v_mfma_f32_16x16x32_bf16 v[60:63], v[128:131], v[178:181], 0
	v_mfma_f32_16x16x32_bf16 v[56:59], v[136:139], v[178:181], 0
	v_mfma_f32_16x16x32_bf16 v[44:47], v[128:131], v[186:189], 0
	v_mfma_f32_16x16x32_bf16 v[40:43], v[136:139], v[186:189], 0
	v_mfma_f32_16x16x32_bf16 v[28:31], v[128:131], v[202:205], 0
	v_mfma_f32_16x16x32_bf16 v[24:27], v[136:139], v[202:205], 0
	v_mfma_f32_16x16x32_bf16 v[12:15], v[128:131], v[210:213], 0
	v_mfma_f32_16x16x32_bf16 v[8:11], v[136:139], v[210:213], 0
	v_mfma_f32_16x16x32_bf16 v[60:63], v[132:135], v[182:185], v[60:63]
	v_mfma_f32_16x16x32_bf16 v[56:59], v[140:143], v[182:185], v[56:59]
	v_mfma_f32_16x16x32_bf16 v[44:47], v[132:135], v[190:193], v[44:47]
	v_mfma_f32_16x16x32_bf16 v[40:43], v[140:143], v[190:193], v[40:43]
	v_mfma_f32_16x16x32_bf16 v[28:31], v[132:135], v[206:209], v[28:31]
	v_mfma_f32_16x16x32_bf16 v[24:27], v[140:143], v[206:209], v[24:27]
	v_mfma_f32_16x16x32_bf16 v[12:15], v[132:135], v[214:217], v[12:15]
	v_mfma_f32_16x16x32_bf16 v[8:11], v[140:143], v[214:217], v[8:11]
	s_setprio 0
	s_setprio 1
	v_mfma_f32_16x16x32_bf16 v[52:55], v[144:147], v[178:181], 0
	v_mfma_f32_16x16x32_bf16 v[48:51], v[152:155], v[178:181], 0
	v_mfma_f32_16x16x32_bf16 v[36:39], v[144:147], v[186:189], 0
	v_mfma_f32_16x16x32_bf16 v[32:35], v[152:155], v[186:189], 0
	v_mfma_f32_16x16x32_bf16 v[20:23], v[144:147], v[202:205], 0
	v_mfma_f32_16x16x32_bf16 v[16:19], v[152:155], v[202:205], 0
	v_mfma_f32_16x16x32_bf16 v[4:7], v[144:147], v[210:213], 0
	v_mfma_f32_16x16x32_bf16 v[0:3], v[152:155], v[210:213], 0
	v_mfma_f32_16x16x32_bf16 v[52:55], v[148:151], v[182:185], v[52:55]
	v_mfma_f32_16x16x32_bf16 v[48:51], v[156:159], v[182:185], v[48:51]
	v_mfma_f32_16x16x32_bf16 v[36:39], v[148:151], v[190:193], v[36:39]
	v_mfma_f32_16x16x32_bf16 v[32:35], v[156:159], v[190:193], v[32:35]
	v_mfma_f32_16x16x32_bf16 v[20:23], v[148:151], v[206:209], v[20:23]
	v_mfma_f32_16x16x32_bf16 v[16:19], v[156:159], v[206:209], v[16:19]
	v_mfma_f32_16x16x32_bf16 v[4:7], v[148:151], v[214:217], v[4:7]
	v_mfma_f32_16x16x32_bf16 v[0:3], v[156:159], v[214:217], v[0:3]
	s_setprio 0
	s_barrier
	s_add_i32 s57, 0, 0x18000
	s_add_i32 s58, 0, 0x1c000
	v_add_u32_e32 v140, s57, v194
	v_add_u32_e32 v156, s58, v194
	ds_read_b128 v[128:131], v140
	ds_read_b128 v[132:135], v140 offset:1024
	ds_read_b128 v[136:139], v140 offset:2048
	ds_read_b128 v[140:143], v140 offset:3072
	ds_read_b128 v[144:147], v156
	ds_read_b128 v[148:151], v156 offset:1024
	ds_read_b128 v[152:155], v156 offset:2048
	ds_read_b128 v[156:159], v156 offset:3072
	s_add_u32 s6, s6, s12
	s_addc_u32 s7, s7, s13
	s_mov_b32 m0, s39
	v_lshl_add_u64 v[230:231], s[6:7], 0, v[160:161]
	ds_read_b128 v[178:181], v197 offset:32768
	ds_read_b128 v[182:185], v197 offset:33792
	ds_read_b128 v[186:189], v197 offset:34816
	ds_read_b128 v[190:193], v197 offset:35840
	ds_read_b128 v[202:205], v197 offset:36864
	ds_read_b128 v[206:209], v197 offset:37888
	ds_read_b128 v[210:213], v197 offset:38912
	ds_read_b128 v[214:217], v197 offset:39936
	global_load_lds_dwordx4 v[230:231], off
	v_lshl_add_u64 v[230:231], s[6:7], 0, v[164:165]
	s_mov_b32 m0, s40
	s_nop 0
	global_load_lds_dwordx4 v[230:231], off
	s_waitcnt vmcnt(8)
	s_waitcnt lgkmcnt(0)
	s_barrier
	s_setprio 1
	s_waitcnt lgkmcnt(0)
	v_mfma_f32_16x16x32_bf16 v[124:127], v[128:131], v[178:181], v[124:127]
	v_mfma_f32_16x16x32_bf16 v[120:123], v[136:139], v[178:181], v[120:123]
	v_mfma_f32_16x16x32_bf16 v[108:111], v[128:131], v[186:189], v[108:111]
	v_mfma_f32_16x16x32_bf16 v[104:107], v[136:139], v[186:189], v[104:107]
	v_mfma_f32_16x16x32_bf16 v[92:95], v[128:131], v[202:205], v[92:95]
	v_mfma_f32_16x16x32_bf16 v[88:91], v[136:139], v[202:205], v[88:91]
	v_mfma_f32_16x16x32_bf16 v[76:79], v[128:131], v[210:213], v[76:79]
	v_mfma_f32_16x16x32_bf16 v[72:75], v[136:139], v[210:213], v[72:75]
	v_mfma_f32_16x16x32_bf16 v[124:127], v[132:135], v[182:185], v[124:127]
	v_mfma_f32_16x16x32_bf16 v[120:123], v[140:143], v[182:185], v[120:123]
	v_mfma_f32_16x16x32_bf16 v[108:111], v[132:135], v[190:193], v[108:111]
	v_mfma_f32_16x16x32_bf16 v[104:107], v[140:143], v[190:193], v[104:107]
	v_mfma_f32_16x16x32_bf16 v[92:95], v[132:135], v[206:209], v[92:95]
	v_mfma_f32_16x16x32_bf16 v[88:91], v[140:143], v[206:209], v[88:91]
	v_mfma_f32_16x16x32_bf16 v[76:79], v[132:135], v[214:217], v[76:79]
	v_mfma_f32_16x16x32_bf16 v[72:75], v[140:143], v[214:217], v[72:75]
	s_setprio 0
	s_setprio 1
	v_mfma_f32_16x16x32_bf16 v[116:119], v[144:147], v[178:181], v[116:119]
	v_mfma_f32_16x16x32_bf16 v[112:115], v[152:155], v[178:181], v[112:115]
	v_mfma_f32_16x16x32_bf16 v[100:103], v[144:147], v[186:189], v[100:103]
	v_mfma_f32_16x16x32_bf16 v[96:99], v[152:155], v[186:189], v[96:99]
	v_mfma_f32_16x16x32_bf16 v[84:87], v[144:147], v[202:205], v[84:87]
	v_mfma_f32_16x16x32_bf16 v[80:83], v[152:155], v[202:205], v[80:83]
	v_mfma_f32_16x16x32_bf16 v[68:71], v[144:147], v[210:213], v[68:71]
	v_mfma_f32_16x16x32_bf16 v[64:67], v[152:155], v[210:213], v[64:67]
	v_mfma_f32_16x16x32_bf16 v[116:119], v[148:151], v[182:185], v[116:119]
	v_mfma_f32_16x16x32_bf16 v[112:115], v[156:159], v[182:185], v[112:115]
	v_mfma_f32_16x16x32_bf16 v[100:103], v[148:151], v[190:193], v[100:103]
	v_mfma_f32_16x16x32_bf16 v[96:99], v[156:159], v[190:193], v[96:99]
	v_mfma_f32_16x16x32_bf16 v[84:87], v[148:151], v[206:209], v[84:87]
	v_mfma_f32_16x16x32_bf16 v[80:83], v[156:159], v[206:209], v[80:83]
	v_mfma_f32_16x16x32_bf16 v[68:71], v[148:151], v[214:217], v[68:71]
	v_mfma_f32_16x16x32_bf16 v[64:67], v[156:159], v[214:217], v[64:67]
	s_setprio 0
	s_barrier
; #define PG8_STAGE(bufoff, gbase, voff) do { _Pragma("unroll") for (int _i = 0; _i < 2; ++_i) \
;         __builtin_amdgcn_global_load_lds((const unsigned*)((const char*)(gbase) + (voff)[_i]), (PG8_LAS unsigned*)(lds + (bufoff) + ldsw + _i * 8192), 16, 0, 0); } while (0)
; #define PG8_LDA(dst, b, h) do { _Pragma("unroll") for (int m = 0; m < 4; ++m) _Pragma("unroll") for (int k = 0; k < 2; ++k) dst[m][k] = *(const PG8_LAS bf16x8*)(lds + PG8_SA(b, h) + aoff + m * 2048 + k * 1024); } while (0)
; #define PG8_MMA(ai, bj, At, Bt) do { __builtin_amdgcn_s_setprio(1); _Pragma("unroll") for (int m = 0; m < 4; ++m) _Pragma("unroll") for (int n = 0; n < 2; ++n) _Pragma("unroll") for (int k = 0; k < 2; ++k) \
;         acc[ai][bj][m][n] = __builtin_amdgcn_mfma_f32_16x16x32_bf16(Bt[n][k], At[m][k], acc[ai][bj][m][n], 0, 0, 0); __builtin_amdgcn_s_setprio(0); } while (0)
; #define PG8_WAIT_V(n) asm volatile("s_waitcnt vmcnt(" #n ")" ::: "memory")
; #define PG8_WAIT_L(n) asm volatile("s_waitcnt lgkmcnt(" #n ")" ::: "memory")
; #define PG8_BAR __builtin_amdgcn_s_barrier()
; #define PG8_SCHED __builtin_amdgcn_sched_barrier(0)
; template <class Epi, class Sched, bool ALIGN_EPI = false, bool SP2 = false>
; __device__ __forceinline__ void gemm_phase(PG8_LAS unsigned char* lds, const Gemm g, const Sched& S, const Epi& E) {
;     ...
;         for (int t = 0; t < nt; t += 2) {
;     ...
;             PG8_LDA(At, 1, 1); PG8_STAGE(PG8_SB(1, 0), b3, voffB); PG8_STAGE(PG8_SB(1, 1), b3 + hstep, voffB); PG8_STAGE(PG8_SA(1, 0), a3, voffA);
;             PG8_WAIT_V(8); PG8_WAIT_L(0); PG8_BAR; PG8_MMA(1, 0, At, B0); PG8_MMA(1, 1, At, B1); PG8_BAR; PG8_SCHED;
	s_add_i32 s6, s57, s36
	v_lshl_add_u64 v[218:219], v[218:219], 0, s[18:19]
	s_mov_b32 m0, s6
	ds_read_b128 v[178:181], v197 offset:49152
	ds_read_b128 v[182:185], v197 offset:50176
	ds_read_b128 v[186:189], v197 offset:51200
	ds_read_b128 v[190:193], v197 offset:52224
	ds_read_b128 v[202:205], v197 offset:53248
	ds_read_b128 v[206:209], v197 offset:54272
	ds_read_b128 v[210:213], v197 offset:55296
	ds_read_b128 v[214:217], v197 offset:56320
	global_load_lds_dwordx4 v[218:219], off
	v_lshl_add_u64 v[218:219], v[220:221], 0, s[18:19]
	s_add_i32 m0, s6, 0x2000
	s_add_i32 s6, s58, s36
	global_load_lds_dwordx4 v[218:219], off
	v_lshl_add_u64 v[218:219], v[222:223], 0, s[18:19]
	s_mov_b32 m0, s6
	s_nop 0
	global_load_lds_dwordx4 v[218:219], off
	v_lshl_add_u64 v[218:219], v[224:225], 0, s[18:19]
	s_add_i32 m0, s6, 0x2000
	s_nop 0
	global_load_lds_dwordx4 v[218:219], off
	v_lshl_add_u64 v[218:219], v[226:227], 0, s[18:19]
	s_mov_b32 m0, s42
	s_nop 0
	global_load_lds_dwordx4 v[218:219], off
	v_lshl_add_u64 v[218:219], v[228:229], 0, s[18:19]
	s_mov_b32 m0, s43
	s_nop 0
	global_load_lds_dwordx4 v[218:219], off
	s_waitcnt vmcnt(8)
	s_waitcnt lgkmcnt(0)
	s_barrier
	s_setprio 1
	s_waitcnt lgkmcnt(0)
	v_mfma_f32_16x16x32_bf16 v[60:63], v[128:131], v[178:181], v[60:63]
	v_mfma_f32_16x16x32_bf16 v[56:59], v[136:139], v[178:181], v[56:59]
	v_mfma_f32_16x16x32_bf16 v[44:47], v[128:131], v[186:189], v[44:47]
	v_mfma_f32_16x16x32_bf16 v[40:43], v[136:139], v[186:189], v[40:43]
	v_mfma_f32_16x16x32_bf16 v[28:31], v[128:131], v[202:205], v[28:31]
	v_mfma_f32_16x16x32_bf16 v[24:27], v[136:139], v[202:205], v[24:27]
	v_mfma_f32_16x16x32_bf16 v[12:15], v[128:131], v[210:213], v[12:15]
	v_mfma_f32_16x16x32_bf16 v[8:11], v[136:139], v[210:213], v[8:11]
	v_mfma_f32_16x16x32_bf16 v[60:63], v[132:135], v[182:185], v[60:63]
	v_mfma_f32_16x16x32_bf16 v[56:59], v[140:143], v[182:185], v[56:59]
	v_mfma_f32_16x16x32_bf16 v[44:47], v[132:135], v[190:193], v[44:47]
	v_mfma_f32_16x16x32_bf16 v[40:43], v[140:143], v[190:193], v[40:43]
	v_mfma_f32_16x16x32_bf16 v[28:31], v[132:135], v[206:209], v[28:31]
	v_mfma_f32_16x16x32_bf16 v[24:27], v[140:143], v[206:209], v[24:27]
	v_mfma_f32_16x16x32_bf16 v[12:15], v[132:135], v[214:217], v[12:15]
	v_mfma_f32_16x16x32_bf16 v[8:11], v[140:143], v[214:217], v[8:11]
	s_setprio 0
	s_setprio 1
	v_mfma_f32_16x16x32_bf16 v[52:55], v[144:147], v[178:181], v[52:55]
	v_mfma_f32_16x16x32_bf16 v[48:51], v[152:155], v[178:181], v[48:51]
	v_mfma_f32_16x16x32_bf16 v[36:39], v[144:147], v[186:189], v[36:39]
	v_mfma_f32_16x16x32_bf16 v[32:35], v[152:155], v[186:189], v[32:35]
	v_mfma_f32_16x16x32_bf16 v[20:23], v[144:147], v[202:205], v[20:23]
	v_mfma_f32_16x16x32_bf16 v[16:19], v[152:155], v[202:205], v[16:19]
	v_mfma_f32_16x16x32_bf16 v[4:7], v[144:147], v[210:213], v[4:7]
	v_mfma_f32_16x16x32_bf16 v[0:3], v[152:155], v[210:213], v[0:3]
	v_mfma_f32_16x16x32_bf16 v[52:55], v[148:151], v[182:185], v[52:55]
	v_mfma_f32_16x16x32_bf16 v[48:51], v[156:159], v[182:185], v[48:51]
	v_mfma_f32_16x16x32_bf16 v[36:39], v[148:151], v[190:193], v[36:39]
	v_mfma_f32_16x16x32_bf16 v[32:35], v[156:159], v[190:193], v[32:35]
	v_mfma_f32_16x16x32_bf16 v[20:23], v[148:151], v[206:209], v[20:23]
	v_mfma_f32_16x16x32_bf16 v[16:19], v[156:159], v[206:209], v[16:19]
	v_mfma_f32_16x16x32_bf16 v[4:7], v[148:151], v[214:217], v[4:7]
	v_mfma_f32_16x16x32_bf16 v[0:3], v[156:159], v[214:217], v[0:3]
	s_setprio 0
	s_barrier
	s_add_u32 s4, s4, 0x100
	s_addc_u32 s5, s5, 0
	s_add_u32 s11, s11, 0x100
	s_addc_u32 s29, s29, 0
	s_cmp_ge_i32 s56, s44
	s_mov_b32 s6, s56
	s_cbranch_scc1 .LBB0_1011

;     __device__ __forceinline__ void operator()(const AccT& acc, const Unit& u, int wr, int wc, int fr_, int fq_) const {
;     ...
;         bf16_t* const QI = (bf16_t*)(ws + WS_QIMG); const float* const ssq_q = (const float*)(ws + WS_SSQ); const float* const rope = (const float*)(ws + WS_ROPE);
;         float ssv[2][4];
; #pragma unroll
;         for (int ai = 0; ai < 2; ++ai)
; #pragma unroll
;             for (int m = 0; m < 4; ++m) ssv[ai][m] = ssq_q[(size_t)ROW_OF(ai, m)];
; #pragma unroll
;         for (int aim = 0; aim < 4; ++aim) { const int ai = aim >> 1;
;             f32x4 cs[4][4];
;             if (pn >= 4) {
; #pragma unroll
;                 for (int m = 2 * (aim & 1); m < 2 * (aim & 1) + 2; ++m) { const f32x4* cp = (const f32x4*)(rope + (size_t)ROW_OF(ai, m) * 64 + 16 * fq);
; #pragma unroll
;                     for (int j = 0; j < 4; ++j) cs[m][j] = cp[j]; }
;             }
; #pragma unroll
;             for (int m = 2 * (aim & 1); m < 2 * (aim & 1) + 2; ++m) {
;                 const size_t row = (size_t)ROW_OF(ai, m);
;                 const float sc = QSCALE * __builtin_amdgcn_rsqf(ssv[ai][m] * (1.0f / QLORA) + EPS);
;                 const int b = (int)(row >> 11), s = (int)(row & 2047);
;                 const f32x4 a0 = acc[ai][0][m][0] * sc, a1 = acc[ai][0][m][1] * sc, b0 = acc[ai][1][m][0] * sc, b1 = acc[ai][1][m][1] * sc;
;                 if (pn < 4) {
;                     const int ks = 2 * wc + (fq >> 1), h = fq & 1;
;                     bf16_t* p = QI + ((size_t)((b * 8 + 2 * pn) * 64 + (s >> 5))) * 6144 + (ks * 2 + h) * 256 + (s & 31) * 8;
;                     st16(p, pk8(a0, a1)); st16(p + (size_t)64 * 6144, pk8(b0, b1));
;                 } else {
;                     const int head = 4 * (pn - 4) + wc;
;                     const f32x4 c0 = cs[m][0], c1 = cs[m][1], c2 = cs[m][2], c3 = cs[m][3];
;                     f32x4 o1a, o1b, o2a, o2b;
;                     o1a[0] = a0[0] * c0[0] - b0[0] * c0[1]; o2a[0] = a0[0] * c0[1] + b0[0] * c0[0];
;                     o1a[1] = a0[1] * c0[2] - b0[1] * c0[3]; o2a[1] = a0[1] * c0[3] + b0[1] * c0[2];
;                     o1a[2] = a0[2] * c1[0] - b0[2] * c1[1]; o2a[2] = a0[2] * c1[1] + b0[2] * c1[0];
;                     o1a[3] = a0[3] * c1[2] - b0[3] * c1[3]; o2a[3] = a0[3] * c1[3] + b0[3] * c1[2];
.LBB0_1013:
	s_mov_b32 s99, 1
	s_lshl_b32 s4, s10, 8
	v_mov_b32_e32 v184, v232
	v_mov_b32_e32 v185, v201
	s_add_i32 s4, s4, s45
	s_cmp_gt_i32 s28, 3
	v_add_u32_e32 v188, s4, v185
	v_ashrrev_i32_e32 v189, 31, v188
	v_lshl_add_u64 v[128:129], v[188:189], 2, s[90:91]
	v_mov_b32_e32 v179, v245
	v_mov_b32_e32 v192, v246
	v_mov_b32_e32 v206, v247
	v_mov_b32_e32 v205, v248
	v_mov_b32_e32 v204, v249
	v_mov_b32_e32 v203, v250
	v_mov_b32_e32 v202, v251
	v_mov_b32_e32 v199, v252
	v_lshlrev_b32_e32 v128, 4, v184
	v_add_u32_e32 v190, 16, v188
	v_ashrrev_i32_e32 v129, 31, v128
	v_ashrrev_i32_e32 v191, 31, v190
	s_cselect_b64 s[10:11], -1, 0
	s_cmp_lt_i32 s28, 4
	v_lshl_add_u64 v[186:187], v[128:129], 2, s[24:25]
	s_cbranch_scc1 .LBB0_1015
	v_lshlrev_b64 v[128:129], 8, v[188:189]
	v_lshl_add_u64 v[128:129], v[186:187], 0, v[128:129]
	global_load_dwordx4 v[144:147], v[128:129], off offset:48
	global_load_dwordx4 v[148:151], v[128:129], off offset:32
	global_load_dwordx4 v[152:155], v[128:129], off offset:16
	global_load_dwordx4 v[156:159], v[128:129], off
	v_lshlrev_b64 v[128:129], 8, v[190:191]
	v_lshl_add_u64 v[140:141], v[186:187], 0, v[128:129]
	global_load_dwordx4 v[128:131], v[140:141], off offset:48
	global_load_dwordx4 v[132:135], v[140:141], off offset:32
	global_load_dwordx4 v[136:139], v[140:141], off offset:16
	s_nop 0
	global_load_dwordx4 v[140:143], v[140:141], off
.LBB0_1015:
	v_lshl_add_u32 v253, s55, 8, v201
	v_add_lshl_u32 v253, v253, s45, 2
	global_load_dword v245, v253, s[90:91]
	global_load_dword v246, v253, s[90:91] offset:64
	global_load_dword v247, v253, s[90:91] offset:128
	global_load_dword v248, v253, s[90:91] offset:192
	global_load_dword v249, v253, s[90:91] offset:512
	global_load_dword v250, v253, s[90:91] offset:576
	global_load_dword v251, v253, s[90:91] offset:640
	global_load_dword v252, v253, s[90:91] offset:704
	s_waitcnt vmcnt(8)
	v_fmamk_f32 v179, v179, 0x3b2aaaab, v198
	v_rsq_f32_e32 v189, v179
	v_lshlrev_b32_e32 v168, 9, v184
	v_lshlrev_b32_e32 v178, 8, v184
	v_and_b32_e32 v168, 0x200, v168
	v_lshl_add_u64 v[182:183], s[8:9], 0, v[168:169]
	v_and_b32_e32 v168, 0xfffffe00, v178
	s_cmp_gt_i32 s28, 3
	v_add_u32_e32 v178, 0x1000, v168
	v_add_u32_e32 v180, 0x1400, v168
	v_mul_f32_e32 v168, 0x3dd53b94, v189
	s_cselect_b64 s[6:7], -1, 0
	s_lshl_b32 s4, s28, 8
	v_and_b32_e32 v191, 0x7ff, v188
	v_pk_mul_f32 v[126:127], v[126:127], v[168:169] op_sel_hi:[1,0]
	v_pk_mul_f32 v[124:125], v[124:125], v[168:169] op_sel_hi:[1,0]
	v_pk_mul_f32 v[122:123], v[122:123], v[168:169] op_sel_hi:[1,0]
	v_pk_mul_f32 v[120:121], v[120:121], v[168:169] op_sel_hi:[1,0]
	v_pk_mul_f32 v[118:119], v[118:119], v[168:169] op_sel_hi:[1,0]
	v_pk_mul_f32 v[116:117], v[116:117], v[168:169] op_sel_hi:[1,0]
	v_pk_mul_f32 v[114:115], v[114:115], v[168:169] op_sel_hi:[1,0]
	v_pk_mul_f32 v[112:113], v[112:113], v[168:169] op_sel_hi:[1,0]
	v_lshlrev_b32_e32 v168, 4, v185
	s_add_i32 s56, s47, s4
	v_ashrrev_i32_e32 v179, 31, v178
	v_ashrrev_i32_e32 v181, 31, v180
	v_ashrrev_i32_e32 v189, 11, v188
	s_mov_b64 s[4:5], -1
	s_and_b64 vcc, exec, s[6:7]
	v_lshrrev_b32_e32 v191, 5, v191
	v_and_b32_e32 v168, 0x1f0, v168
	s_cbranch_vccz .LBB0_1017
	v_mov_b32_e32 v210, v157
	v_mov_b32_e32 v211, v159
	v_mov_b32_e32 v208, v156
	v_mov_b32_e32 v209, v158
	v_pk_mul_f32 v[212:213], v[116:117], v[210:211]
	v_lshl_add_u32 v185, v189, 9, s56
	v_pk_fma_f32 v[212:213], v[124:125], v[208:209], v[212:213] neg_lo:[0,0,1] neg_hi:[0,0,1]
	v_pk_mul_f32 v[208:209], v[116:117], v[208:209]
	v_or_b32_e32 v185, v185, v191
	v_pk_fma_f32 v[214:215], v[124:125], v[210:211], v[208:209]
	v_mov_b32_e32 v210, v153
	v_mov_b32_e32 v211, v155
	v_mov_b32_e32 v208, v152
	v_mov_b32_e32 v209, v154
	v_pk_mul_f32 v[216:217], v[118:119], v[210:211]
	s_nop 0
	v_pk_fma_f32 v[216:217], v[126:127], v[208:209], v[216:217] neg_lo:[0,0,1] neg_hi:[0,0,1]
	v_pk_mul_f32 v[208:209], v[118:119], v[208:209]
	s_nop 0
	v_pk_fma_f32 v[218:219], v[126:127], v[210:211], v[208:209]
	v_mov_b32_e32 v210, v149
	v_mov_b32_e32 v211, v151
	v_mov_b32_e32 v208, v148
	v_mov_b32_e32 v209, v150
	v_pk_mul_f32 v[220:221], v[112:113], v[210:211]
	s_nop 0
	v_pk_fma_f32 v[220:221], v[120:121], v[208:209], v[220:221] neg_lo:[0,0,1] neg_hi:[0,0,1]
	v_pk_mul_f32 v[208:209], v[112:113], v[208:209]
	s_nop 0
	v_pk_fma_f32 v[222:223], v[120:121], v[210:211], v[208:209]
	v_mov_b32_e32 v210, v145
	v_mov_b32_e32 v211, v147
	v_mov_b32_e32 v208, v144
	v_mov_b32_e32 v209, v146
	v_pk_mul_f32 v[224:225], v[114:115], v[210:211]
	s_nop 0
	v_pk_fma_f32 v[224:225], v[122:123], v[208:209], v[224:225] neg_lo:[0,0,1] neg_hi:[0,0,1]
	v_pk_mul_f32 v[208:209], v[114:115], v[208:209]
	s_nop 0
	v_pk_fma_f32 v[226:227], v[122:123], v[210:211], v[208:209]
	v_mad_i64_i32 v[208:209], s[4:5], v185, s54, v[182:183]
	v_lshl_add_u64 v[228:229], v[208:209], 0, v[168:169]
	v_lshl_add_u64 v[230:231], v[178:179], 1, v[228:229]
	v_cvt_pk_bf16_f32 v208, v212, v213
	v_cvt_pk_bf16_f32 v209, v216, v217
	v_cvt_pk_bf16_f32 v210, v220, v221
	v_cvt_pk_bf16_f32 v211, v224, v225
	global_store_dwordx4 v[230:231], v[208:211], off nt
	v_lshl_add_u64 v[212:213], v[180:181], 1, v[228:229]
	s_mov_b64 s[4:5], 0
	v_cvt_pk_bf16_f32 v208, v214, v215
	v_cvt_pk_bf16_f32 v209, v218, v219
	v_cvt_pk_bf16_f32 v210, v222, v223
	v_cvt_pk_bf16_f32 v211, v226, v227
	global_store_dwordx4 v[212:213], v[208:211], off nt

; #define LAS __attribute__((address_space(3)))
; __device__ __forceinline__ void attn_phase(const Ptrs& P, LAS unsigned char* lds, int vcu) {
;     ...
;         { const bf16_t* zsrc = A2 + (size_t)(b * SEQ + qw) * 2048 + 1024 + head * 128;
;           int lp = lane; asm volatile("" : "+v"(lp));
; #pragma unroll
;           for (int c = 0; c < 8; ++c) { const int r = c * 4 + (lp >> 4), k = (lp & 15) ^ (r & 15);
;               __builtin_amdgcn_global_load_lds((const unsigned*)(zsrc + (size_t)r * 2048 + k * 8), (LAS unsigned*)(wz + c * 1024), 16, 0, 0); } }
;     ...
;         for (int t = 0; t < NT; ++t) {
;             asm volatile("s_waitcnt vmcnt(0)" ::: "memory");
;             __syncthreads();
.LBB0_1170:
	s_lshl_b32 s6, s72, 8
	v_readlane_b32 s0, v255, 7
	s_add_i32 s92, s6, s0
	v_readlane_b32 s0, v254, 59
	s_add_i32 s0, s92, s0
	s_ashr_i32 s1, s0, 31
	v_readlane_b32 s12, v254, 44
	s_lshl_b32 s78, s72, 2
	s_lshl_b64 s[0:1], s[0:1], 12
	v_readlane_b32 s14, v254, 46
	v_readlane_b32 s15, v254, 47
	s_add_u32 s0, s14, s0
	s_addc_u32 s1, s15, s1
	v_readlane_b32 s7, v255, 8
	s_add_u32 s0, s0, s7
	s_addc_u32 s1, s1, 0
	s_add_u32 s86, s0, 0xd000800
	s_addc_u32 s87, s1, 0
	s_add_i32 s78, s78, 4
	s_cmp_lg_u32 s85, 3
	v_mov_b32_e32 v14, v1
	v_mov_b32_e32 v15, v1
	s_cselect_b64 s[94:95], -1, 0
	s_lshl_b64 s[0:1], s[72:73], 15
	v_mov_b32_e32 v0, v1
	v_mov_b32_e32 v2, v1
	v_mov_b32_e32 v3, v1
	v_mov_b32_e32 v4, v1
	v_mov_b32_e32 v5, v1
	v_mov_b32_e32 v6, v1
	v_mov_b32_e32 v7, v1
	v_mov_b32_e32 v8, v1
	v_mov_b32_e32 v9, v1
	v_mov_b32_e32 v10, v1
	v_mov_b32_e32 v11, v1
	v_mov_b32_e32 v12, v1
	v_mov_b32_e32 v13, v1
	v_mov_b32_e32 v224, 0
	v_mov_b64_e32 v[30:31], v[14:15]
	v_mov_b64_e32 v[46:47], v[14:15]
	v_mov_b64_e32 v[62:63], v[14:15]
	v_mov_b64_e32 v[78:79], v[14:15]
	v_add_u32_e32 v223, s6, v222
	s_add_u32 s79, s0, 0x8000
	s_mov_b32 s8, 0
	s_mov_b64 s[82:83], 0
	s_mov_b32 s90, 63
	v_mov_b64_e32 v[28:29], v[12:13]
	v_mov_b64_e32 v[26:27], v[10:11]
	v_mov_b64_e32 v[24:25], v[8:9]
	v_mov_b64_e32 v[22:23], v[6:7]
	v_mov_b64_e32 v[20:21], v[4:5]
	v_mov_b64_e32 v[18:19], v[2:3]
	v_mov_b64_e32 v[16:17], v[0:1]
	v_mov_b64_e32 v[44:45], v[12:13]
	v_mov_b64_e32 v[42:43], v[10:11]
	v_mov_b64_e32 v[40:41], v[8:9]
	v_mov_b64_e32 v[38:39], v[6:7]
	v_mov_b64_e32 v[36:37], v[4:5]
	v_mov_b64_e32 v[34:35], v[2:3]
	v_mov_b64_e32 v[32:33], v[0:1]
	v_mov_b64_e32 v[60:61], v[12:13]
	v_mov_b64_e32 v[58:59], v[10:11]
	v_mov_b64_e32 v[56:57], v[8:9]
	v_mov_b64_e32 v[54:55], v[6:7]
	v_mov_b64_e32 v[52:53], v[4:5]
	v_mov_b64_e32 v[50:51], v[2:3]
	v_mov_b64_e32 v[48:49], v[0:1]
	v_mov_b64_e32 v[76:77], v[12:13]
	v_mov_b64_e32 v[74:75], v[10:11]
	v_mov_b64_e32 v[72:73], v[8:9]
	v_mov_b64_e32 v[70:71], v[6:7]
	v_mov_b64_e32 v[68:69], v[4:5]
	v_mov_b64_e32 v[66:67], v[2:3]
	v_mov_b64_e32 v[64:65], v[0:1]
	v_mov_b32_e32 v10, 0
	v_mov_b32_e32 v80, 0
	v_mov_b32_e32 v81, v224
	v_mov_b32_e32 v82, v224
	v_mov_b32_e32 v83, v224
	v_mov_b32_e32 v84, v224
	v_mov_b32_e32 v85, v224
	v_mov_b32_e32 v86, v224
	v_mov_b32_e32 v87, v224
	v_mov_b32_e32 v88, v224
	v_mov_b32_e32 v89, v224
	v_mov_b32_e32 v90, v224
	v_mov_b32_e32 v91, v224
	v_mov_b32_e32 v92, v224
	v_mov_b32_e32 v93, v224
	v_mov_b32_e32 v94, v224
	v_mov_b32_e32 v95, v224
	v_readlane_b32 s13, v254, 45
	s_waitcnt vmcnt(0)
.LBB0_1171:
	s_waitcnt vmcnt(0)
	s_bitcmp1_b32 s8, 0
	s_cselect_b32 s70, 0xa000, 0
	v_add_u32_e32 v0, s70, v176
	s_add_i32 s72, s8, 1
	s_cmp_ge_u32 s72, s78
	s_mov_b64 s[0:1], -1
	s_waitcnt lgkmcnt(0)
	s_barrier
	s_cmp_lg_u32 s8, 0
	s_cbranch_scc1 .Lz_skip
	v_mov_b32_e32 v8, v201
	v_ashrrev_i32_e32 v2, 4, v8
	v_xor_b32_e32 v0, v2, v8
	v_ashrrev_i32_e32 v3, 31, v2
	v_lshlrev_b64 v[4:5], 12, v[2:3]
	v_lshlrev_b32_e32 v0, 4, v0
	v_lshl_add_u64 v[4:5], s[86:87], 0, v[4:5]
	v_and_b32_e32 v0, 0xf0, v0
	v_add_u32_e32 v6, 4, v2
	v_lshl_add_u64 v[4:5], v[4:5], 0, v[0:1]
	v_xor_b32_e32 v0, v6, v8
	v_ashrrev_i32_e32 v7, 31, v6
	v_lshlrev_b64 v[6:7], 12, v[6:7]
	v_lshlrev_b32_e32 v0, 4, v0
	s_mov_b32 m0, s23
	v_lshl_add_u64 v[6:7], s[86:87], 0, v[6:7]
	v_and_b32_e32 v0, 0xf0, v0
	v_readlane_b32 s0, v255, 9
	global_load_lds_dwordx4 v[4:5], off
	v_lshl_add_u64 v[6:7], v[6:7], 0, v[0:1]
	s_mov_b32 m0, s0
	v_readlane_b32 s0, v255, 10
	global_load_lds_dwordx4 v[6:7], off
	v_add_u32_e32 v6, 8, v2
	v_xor_b32_e32 v0, v6, v8
	v_ashrrev_i32_e32 v7, 31, v6
	v_lshlrev_b64 v[6:7], 12, v[6:7]
	v_lshlrev_b32_e32 v0, 4, v0
	v_lshl_add_u64 v[6:7], s[86:87], 0, v[6:7]
	v_and_b32_e32 v0, 0xf0, v0
	v_lshl_add_u64 v[6:7], v[6:7], 0, v[0:1]
	s_mov_b32 m0, s0
	v_readlane_b32 s0, v255, 11
	global_load_lds_dwordx4 v[6:7], off
	v_add_u32_e32 v6, 12, v2
	v_xor_b32_e32 v0, v6, v8
	v_ashrrev_i32_e32 v7, 31, v6
	v_lshlrev_b64 v[6:7], 12, v[6:7]
	v_lshlrev_b32_e32 v0, 4, v0
	v_lshl_add_u64 v[6:7], s[86:87], 0, v[6:7]
	v_and_b32_e32 v0, 0xf0, v0
	v_lshl_add_u64 v[6:7], v[6:7], 0, v[0:1]
	s_mov_b32 m0, s0
	s_mov_b64 s[0:1], 0x10000
	global_load_lds_dwordx4 v[6:7], off
	v_lshl_add_u64 v[4:5], v[4:5], 0, s[0:1]
	s_add_i32 m0, s23, 0x1000
	v_readlane_b32 s0, v255, 12
	global_load_lds_dwordx4 v[4:5], off
	v_add_u32_e32 v4, 20, v2
	v_xor_b32_e32 v0, v4, v8
	v_ashrrev_i32_e32 v5, 31, v4
	v_lshlrev_b64 v[4:5], 12, v[4:5]
	v_lshlrev_b32_e32 v0, 4, v0
	v_lshl_add_u64 v[4:5], s[86:87], 0, v[4:5]
	v_and_b32_e32 v0, 0xf0, v0
	v_lshl_add_u64 v[4:5], v[4:5], 0, v[0:1]
	s_add_i32 m0, s23, 0x1400
	global_load_lds_dwordx4 v[4:5], off
	v_add_u32_e32 v4, 24, v2
	v_xor_b32_e32 v0, v4, v8
	v_ashrrev_i32_e32 v5, 31, v4
	v_lshlrev_b64 v[4:5], 12, v[4:5]
	v_lshlrev_b32_e32 v0, 4, v0
	v_lshl_add_u64 v[4:5], s[86:87], 0, v[4:5]
	v_and_b32_e32 v0, 0xf0, v0
	v_add_u32_e32 v2, 28, v2
	v_lshl_add_u64 v[4:5], v[4:5], 0, v[0:1]
	v_xor_b32_e32 v0, v2, v8
	v_ashrrev_i32_e32 v3, 31, v2
	v_lshlrev_b64 v[2:3], 12, v[2:3]
	v_lshlrev_b32_e32 v0, 4, v0
	s_mov_b32 m0, s0
	v_lshl_add_u64 v[2:3], s[86:87], 0, v[2:3]
	v_and_b32_e32 v0, 0xf0, v0
	v_readlane_b32 s0, v255, 13
	global_load_lds_dwordx4 v[4:5], off
	v_lshl_add_u64 v[2:3], v[2:3], 0, v[0:1]
	s_mov_b32 m0, s0
	global_load_lds_dwordx4 v[2:3], off
	v_add_u32_e32 v0, s70, v176
	s_mov_b64 s[0:1], -1
.Lz_skip:
	s_cmp_ge_u32 s72, s78
	ds_read_b128 v[2:5], v0
	ds_read_b128 v[6:9], v0 offset:1024
	ds_read_b128 v[12:15], v0 offset:8192
	ds_read_b128 v[226:229], v0 offset:9216
	ds_read_b128 v[230:233], v0 offset:2048
	ds_read_b128 v[234:237], v0 offset:3072
	ds_read_b128 v[238:241], v0 offset:10240
	ds_read_b128 v[242:245], v0 offset:11264
	s_cbranch_scc1 .LBB0_1174
	s_andn2_b64 vcc, exec, s[0:1]
	s_cbranch_vccz .LBB0_1177

; #define PG8_STAGE(bufoff, gbase, voff) do { _Pragma("unroll") for (int _i = 0; _i < 2; ++_i) \
;         __builtin_amdgcn_global_load_lds((const unsigned*)((const char*)(gbase) + (voff)[_i]), (PG8_LAS unsigned*)(lds + (bufoff) + ldsw + _i * 8192), 16, 0, 0); } while (0)
; #define PG8_WAIT_V(n) asm volatile("s_waitcnt vmcnt(" #n ")" ::: "memory")
; #define PG8_BAR __builtin_amdgcn_s_barrier()
; template <class Epi, class Sched, bool ALIGN_EPI = false, bool SP2 = false>
; __device__ __forceinline__ void gemm_phase(PG8_LAS unsigned char* lds, const Gemm g, const Sched& S, const Epi& E) {
;     ...
;     if constexpr (SP2) {
;         PG8_STAGE(PG8_SB(0, 0), cB, voffB); PG8_STAGE(PG8_SB(0, 1), cB + hstep, voffB); PG8_STAGE(PG8_SA(0, 0), cA, voffA); PG8_STAGE(PG8_SA(0, 1), cA + hstep, voffA);
;         if (wr == 1) PG8_BAR;
;         PG8_WAIT_V(2); PG8_BAR;
;         PG8_STAGE(PG8_SB(1, 0), cB + kstep, voffB); PG8_STAGE(PG8_SA(1, 0), cA + kstep, voffA); PG8_STAGE(PG8_SB(1, 1), cB + hstep + kstep, voffB);
;         PG8_WAIT_V(6); PG8_BAR;
.LBB0_1382:
	s_mov_b64 s[12:13], 0x80
	s_add_i32 m0, s30, 0x18000
	v_lshl_add_u64 v[8:9], v[8:9], 0, s[12:13]
	s_waitcnt vmcnt(2)
	s_barrier
	global_load_lds_dwordx4 v[8:9], off
	v_lshl_add_u64 v[4:5], v[4:5], 0, s[12:13]
	s_add_i32 m0, s30, 0x1a000
	s_add_i32 s36, s30, 0x8000
	global_load_lds_dwordx4 v[4:5], off
	v_lshl_add_u64 v[4:5], v[6:7], 0, s[12:13]
	s_mov_b32 m0, s36
	s_add_i32 s37, s30, 0xa000
	global_load_lds_dwordx4 v[4:5], off
	v_lshl_add_u64 v[4:5], v[10:11], 0, s[12:13]
	s_mov_b32 m0, s37
	v_lshl_add_u64 v[2:3], v[2:3], 0, s[12:13]
	global_load_lds_dwordx4 v[4:5], off
	s_add_i32 m0, s30, 0x1c000
	v_lshl_add_u64 v[0:1], v[0:1], 0, s[12:13]
	global_load_lds_dwordx4 v[2:3], off
	s_add_i32 m0, s30, 0x1e000
	v_bfe_u32 v145, v200, 4, 2
	global_load_lds_dwordx4 v[0:1], off
	s_lshr_b32 s1, s1, 26
	v_and_b32_e32 v144, 15, v200
	s_add_i32 s1, s0, s1
	v_lshlrev_b32_e32 v0, 4, v145
	v_lshlrev_b32_e32 v2, 2, v200
	s_ashr_i32 s38, s1, 6
	v_lshl_or_b32 v1, v144, 6, v0
	s_lshl_b32 s1, s3, 13
	v_and_b32_e32 v2, 32, v2
	v_bitop3_b32 v3, v1, s1, v2 bitop3:0xde
	s_lshl_b32 s1, s14, 5
	s_sext_i32_i8 s49, s2
	s_and_b32 s1, s1, 0x60
	v_lshlrev_b32_e32 v1, 6, v200
	s_movk_i32 s2, 0x3c0
	s_lshl_b32 s39, s3, 6
	v_and_or_b32 v0, v1, s2, v0
	s_lshl_b32 s2, s1, 7
	v_bitop3_b32 v146, s2, v0, v2 bitop3:0xf6
	s_cmp_gt_i32 s0, 63
	v_add_u32_e32 v0, v15, v14
	s_cselect_b64 s[14:15], -1, 0
	s_add_i32 s40, s38, -2
	v_mul_lo_u32 v0, s0, v0
	s_cmpk_lt_u32 s16, 0x100
	v_lshlrev_b32_e32 v0, 1, v0
	s_cselect_b64 s[16:17], -1, 0
	s_lshl_b32 s1, s1, 1
	v_add3_u32 v0, v12, v0, v13
	v_mov_b32_e32 v1, v131
	s_add_u32 s1, s90, s1
	v_lshl_add_u64 v[136:137], s[6:7], 0, v[0:1]
	v_add_u32_e32 v0, v16, v14
	s_addc_u32 s2, s91, 0
	v_mul_lo_u32 v0, s0, v0
	s_waitcnt vmcnt(6)
	s_add_u32 s41, s1, 0x9000000
	v_lshlrev_b32_e32 v0, 1, v0
	s_addc_u32 s42, s2, 0
	v_add3_u32 v0, v12, v0, v13
	s_add_i32 s44, 0, 0x10000
	s_add_i32 s45, 0, 0x14000
	s_ashr_i32 s43, s83, 31
	v_lshl_add_u64 v[138:139], s[6:7], 0, v[0:1]
	v_mov_b64_e32 v[140:141], 0x200
	v_mov_b64_e32 v[142:143], 0x1ff
	v_add_u32_e32 v147, s44, v146
	v_add_u32_e32 v148, s45, v146
	v_add_u32_e32 v149, 0, v3
	s_barrier
	s_mov_b32 s99, 0
	s_branch .LBB0_1385

; #define PG8_STAGE(bufoff, gbase, voff) do { _Pragma("unroll") for (int _i = 0; _i < 2; ++_i) \
;         __builtin_amdgcn_global_load_lds((const unsigned*)((const char*)(gbase) + (voff)[_i]), (PG8_LAS unsigned*)(lds + (bufoff) + ldsw + _i * 8192), 16, 0, 0); } while (0)
; #define PG8_LDA(dst, b, h) do { _Pragma("unroll") for (int m = 0; m < 4; ++m) _Pragma("unroll") for (int k = 0; k < 2; ++k) dst[m][k] = *(const PG8_LAS bf16x8*)(lds + PG8_SA(b, h) + aoff + m * 2048 + k * 1024); } while (0)
; #define PG8_LDB(dst, b, h) do { _Pragma("unroll") for (int n = 0; n < 2; ++n) _Pragma("unroll") for (int k = 0; k < 2; ++k) dst[n][k] = *(const PG8_LAS bf16x8*)(lds + PG8_SB(b, h) + boff + n * 2048 + k * 1024); } while (0)
; #define PG8_MMA(ai, bj, At, Bt) do { __builtin_amdgcn_s_setprio(1); _Pragma("unroll") for (int m = 0; m < 4; ++m) _Pragma("unroll") for (int n = 0; n < 2; ++n) _Pragma("unroll") for (int k = 0; k < 2; ++k) \
;         acc[ai][bj][m][n] = __builtin_amdgcn_mfma_f32_16x16x32_bf16(Bt[n][k], At[m][k], acc[ai][bj][m][n], 0, 0, 0); __builtin_amdgcn_s_setprio(0); } while (0)
; #define PG8_WAIT_V(n) asm volatile("s_waitcnt vmcnt(" #n ")" ::: "memory")
; #define PG8_WAIT_L(n) asm volatile("s_waitcnt lgkmcnt(" #n ")" ::: "memory")
; #define PG8_BAR __builtin_amdgcn_s_barrier()
; #define PG8_SCHED __builtin_amdgcn_sched_barrier(0)
; template <class Epi, class Sched, bool ALIGN_EPI = false, bool SP2 = false>
; __device__ __forceinline__ void gemm_phase(PG8_LAS unsigned char* lds, const Gemm g, const Sched& S, const Epi& E) {
;     ...
;         for (int t = 0; t < nt; t += 2) {
;             if constexpr (Epi::HAS_MID) { if (t == Epi::MID_T) E.mid(acc, cur, wr, wc, fr, fq); }
;             const bool last = (t == nt - 2);
;             const char* a1 = cA + (size_t)(t + 1) * kstep;
;             const char* a2 = last ? nA : cA + (size_t)(t + 2) * kstep; const char* b2 = last ? nB : cB + (size_t)(t + 2) * kstep;
;             const char* a3 = a2 + kstep; const char* b3 = b2 + kstep;
;             if (last && has_next) S.a_ready(nxt);
;             if constexpr (SP2) {
;             PG8_LDB(B0, 0, 0); PG8_LDB(B1, 0, 1); PG8_SCHED; PG8_LDA(At, 0, 0); PG8_STAGE(PG8_SA(1, 1), a1 + hstep, voffA);
;             PG8_WAIT_V(8); PG8_WAIT_L(0); PG8_BAR; PG8_MMA(0, 0, At, B0); PG8_MMA(0, 1, At, B1); PG8_BAR; PG8_SCHED;
.LBB0_1395:
	s_andn2_b64 vcc, exec, s[14:15]
	s_cbranch_vccnz .LBB0_1398
	s_add_u32 s20, s20, 0x80
	s_addc_u32 s21, s21, 0
	s_add_u32 s50, s22, 0x100
	s_addc_u32 s51, s23, 0
	s_mov_b32 s22, 0
	ds_read_b128 v[150:153], v147
	ds_read_b128 v[154:157], v147 offset:1024
	ds_read_b128 v[158:161], v147 offset:2048
	ds_read_b128 v[162:165], v147 offset:3072
	ds_read_b128 v[166:169], v148
	ds_read_b128 v[170:173], v148 offset:1024
	ds_read_b128 v[174:177], v148 offset:2048
	ds_read_b128 v[178:181], v148 offset:3072
	s_add_i32 s52, s22, 2
	s_add_u32 s53, s20, 0x80
	s_addc_u32 s23, s21, 0
	s_cmp_eq_u32 s40, s22
	s_cselect_b32 s22, s0, s53
	s_cselect_b32 s23, s1, s23
	s_cselect_b32 s55, s19, s51
	s_cselect_b32 s54, s18, s50
	v_lshl_add_u64 v[198:199], s[20:21], 0, v[136:137]
	s_add_i32 m0, s30, 0xc000
	ds_read_b128 v[182:185], v149
	ds_read_b128 v[186:189], v149 offset:1024
	ds_read_b128 v[190:193], v149 offset:2048
	ds_read_b128 v[194:197], v149 offset:3072
	ds_read_b128 v[202:205], v149 offset:4096
	ds_read_b128 v[206:209], v149 offset:5120
	ds_read_b128 v[210:213], v149 offset:6144
	ds_read_b128 v[214:217], v149 offset:7168
	global_load_lds_dwordx4 v[198:199], off
	v_lshl_add_u64 v[198:199], s[20:21], 0, v[138:139]
	s_add_i32 m0, s30, 0xe000
	s_nop 0
	global_load_lds_dwordx4 v[198:199], off
	s_cmp_eq_u32 s99, 0
	s_cbranch_scc1 .Lw8_6_0
	s_waitcnt vmcnt(16)
	s_branch .Lwj_6_0

; #define PG8_STAGE(bufoff, gbase, voff) do { _Pragma("unroll") for (int _i = 0; _i < 2; ++_i) \
;         __builtin_amdgcn_global_load_lds((const unsigned*)((const char*)(gbase) + (voff)[_i]), (PG8_LAS unsigned*)(lds + (bufoff) + ldsw + _i * 8192), 16, 0, 0); } while (0)
; #define PG8_LDA(dst, b, h) do { _Pragma("unroll") for (int m = 0; m < 4; ++m) _Pragma("unroll") for (int k = 0; k < 2; ++k) dst[m][k] = *(const PG8_LAS bf16x8*)(lds + PG8_SA(b, h) + aoff + m * 2048 + k * 1024); } while (0)
; #define PG8_MMA(ai, bj, At, Bt) do { __builtin_amdgcn_s_setprio(1); _Pragma("unroll") for (int m = 0; m < 4; ++m) _Pragma("unroll") for (int n = 0; n < 2; ++n) _Pragma("unroll") for (int k = 0; k < 2; ++k) \
;         acc[ai][bj][m][n] = __builtin_amdgcn_mfma_f32_16x16x32_bf16(Bt[n][k], At[m][k], acc[ai][bj][m][n], 0, 0, 0); __builtin_amdgcn_s_setprio(0); } while (0)
; #define PG8_WAIT_V(n) asm volatile("s_waitcnt vmcnt(" #n ")" ::: "memory")
; #define PG8_WAIT_L(n) asm volatile("s_waitcnt lgkmcnt(" #n ")" ::: "memory")
; #define PG8_BAR __builtin_amdgcn_s_barrier()
; #define PG8_SCHED __builtin_amdgcn_sched_barrier(0)
; template <class Epi, class Sched, bool ALIGN_EPI = false, bool SP2 = false>
; __device__ __forceinline__ void gemm_phase(PG8_LAS unsigned char* lds, const Gemm g, const Sched& S, const Epi& E) {
;     ...
;             PG8_WAIT_V(8); PG8_WAIT_L(0); PG8_BAR; PG8_MMA(0, 0, At, B0); PG8_MMA(0, 1, At, B1); PG8_BAR; PG8_SCHED;
;             PG8_LDA(At, 0, 1); PG8_STAGE(PG8_SB(0, 0), b2, voffB); PG8_STAGE(PG8_SB(0, 1), b2 + hstep, voffB); PG8_STAGE(PG8_SA(0, 0), a2, voffA);
.Lwj_6_0:
	s_waitcnt lgkmcnt(0)
	s_barrier
	s_setprio 1
	s_waitcnt lgkmcnt(0)
	v_mfma_f32_16x16x32_bf16 v[120:123], v[150:153], v[182:185], 0
	v_mfma_f32_16x16x32_bf16 v[124:127], v[158:161], v[182:185], 0
	v_mfma_f32_16x16x32_bf16 v[108:111], v[150:153], v[190:193], 0
	v_mfma_f32_16x16x32_bf16 v[104:107], v[158:161], v[190:193], 0
	v_mfma_f32_16x16x32_bf16 v[92:95], v[150:153], v[202:205], 0
	v_mfma_f32_16x16x32_bf16 v[88:91], v[158:161], v[202:205], 0
	v_mfma_f32_16x16x32_bf16 v[76:79], v[150:153], v[210:213], 0
	v_mfma_f32_16x16x32_bf16 v[72:75], v[158:161], v[210:213], 0
	v_mfma_f32_16x16x32_bf16 v[120:123], v[154:157], v[186:189], v[120:123]
	v_mfma_f32_16x16x32_bf16 v[124:127], v[162:165], v[186:189], v[124:127]
	v_mfma_f32_16x16x32_bf16 v[108:111], v[154:157], v[194:197], v[108:111]
	v_mfma_f32_16x16x32_bf16 v[104:107], v[162:165], v[194:197], v[104:107]
	v_mfma_f32_16x16x32_bf16 v[92:95], v[154:157], v[206:209], v[92:95]
	v_mfma_f32_16x16x32_bf16 v[88:91], v[162:165], v[206:209], v[88:91]
	v_mfma_f32_16x16x32_bf16 v[76:79], v[154:157], v[214:217], v[76:79]
	v_mfma_f32_16x16x32_bf16 v[72:75], v[162:165], v[214:217], v[72:75]
	s_setprio 0
	s_setprio 1
	v_mfma_f32_16x16x32_bf16 v[116:119], v[166:169], v[182:185], 0
	v_mfma_f32_16x16x32_bf16 v[112:115], v[174:177], v[182:185], 0
	v_mfma_f32_16x16x32_bf16 v[100:103], v[166:169], v[190:193], 0
	v_mfma_f32_16x16x32_bf16 v[96:99], v[174:177], v[190:193], 0
	v_mfma_f32_16x16x32_bf16 v[84:87], v[166:169], v[202:205], 0
	v_mfma_f32_16x16x32_bf16 v[80:83], v[174:177], v[202:205], 0
	v_mfma_f32_16x16x32_bf16 v[68:71], v[166:169], v[210:213], 0
	v_mfma_f32_16x16x32_bf16 v[64:67], v[174:177], v[210:213], 0
	v_mfma_f32_16x16x32_bf16 v[116:119], v[170:173], v[186:189], v[116:119]
	v_mfma_f32_16x16x32_bf16 v[112:115], v[178:181], v[186:189], v[112:115]
	v_mfma_f32_16x16x32_bf16 v[100:103], v[170:173], v[194:197], v[100:103]
	v_mfma_f32_16x16x32_bf16 v[96:99], v[178:181], v[194:197], v[96:99]
	v_mfma_f32_16x16x32_bf16 v[84:87], v[170:173], v[206:209], v[84:87]
	v_mfma_f32_16x16x32_bf16 v[80:83], v[178:181], v[206:209], v[80:83]
	v_mfma_f32_16x16x32_bf16 v[68:71], v[170:173], v[214:217], v[68:71]
	v_mfma_f32_16x16x32_bf16 v[64:67], v[178:181], v[214:217], v[64:67]
	s_setprio 0
	s_barrier
	s_add_i32 s53, s44, s29
	v_lshl_add_u64 v[198:199], s[54:55], 0, v[130:131]
	s_mov_b32 m0, s53
	ds_read_b128 v[182:185], v149 offset:16384
	ds_read_b128 v[186:189], v149 offset:17408
	ds_read_b128 v[190:193], v149 offset:18432
	ds_read_b128 v[194:197], v149 offset:19456
	ds_read_b128 v[202:205], v149 offset:20480
	ds_read_b128 v[206:209], v149 offset:21504
	ds_read_b128 v[210:213], v149 offset:22528
	ds_read_b128 v[214:217], v149 offset:23552
	global_load_lds_dwordx4 v[198:199], off
	s_add_i32 m0, s53, 0x2000
	v_lshl_add_u64 v[218:219], s[54:55], 0, v[134:135]
	s_add_u32 s54, s54, s6
	s_addc_u32 s55, s55, s7
	s_add_i32 s53, s45, s29
	global_load_lds_dwordx4 v[218:219], off
	v_lshl_add_u64 v[220:221], s[54:55], 0, v[130:131]
	s_mov_b32 m0, s53
	v_lshl_add_u64 v[222:223], s[54:55], 0, v[134:135]
	global_load_lds_dwordx4 v[220:221], off
	s_add_i32 m0, s53, 0x2000
	v_lshl_add_u64 v[224:225], s[22:23], 0, v[128:129]
	global_load_lds_dwordx4 v[222:223], off
	s_mov_b32 m0, s30
	v_lshl_add_u64 v[226:227], s[22:23], 0, v[132:133]
	global_load_lds_dwordx4 v[224:225], off
	s_mov_b32 m0, s31
	s_nop 0
	global_load_lds_dwordx4 v[226:227], off
	s_cmp_eq_u32 s99, 0
	s_cbranch_scc1 .Lw8_6_1
	s_waitcnt vmcnt(16)
	s_branch .Lwj_6_1

; #define PG8_STAGE(bufoff, gbase, voff) do { _Pragma("unroll") for (int _i = 0; _i < 2; ++_i) \
;         __builtin_amdgcn_global_load_lds((const unsigned*)((const char*)(gbase) + (voff)[_i]), (PG8_LAS unsigned*)(lds + (bufoff) + ldsw + _i * 8192), 16, 0, 0); } while (0)
; #define PG8_LDA(dst, b, h) do { _Pragma("unroll") for (int m = 0; m < 4; ++m) _Pragma("unroll") for (int k = 0; k < 2; ++k) dst[m][k] = *(const PG8_LAS bf16x8*)(lds + PG8_SA(b, h) + aoff + m * 2048 + k * 1024); } while (0)
; #define PG8_LDB(dst, b, h) do { _Pragma("unroll") for (int n = 0; n < 2; ++n) _Pragma("unroll") for (int k = 0; k < 2; ++k) dst[n][k] = *(const PG8_LAS bf16x8*)(lds + PG8_SB(b, h) + boff + n * 2048 + k * 1024); } while (0)
; #define PG8_MMA(ai, bj, At, Bt) do { __builtin_amdgcn_s_setprio(1); _Pragma("unroll") for (int m = 0; m < 4; ++m) _Pragma("unroll") for (int n = 0; n < 2; ++n) _Pragma("unroll") for (int k = 0; k < 2; ++k) \
;         acc[ai][bj][m][n] = __builtin_amdgcn_mfma_f32_16x16x32_bf16(Bt[n][k], At[m][k], acc[ai][bj][m][n], 0, 0, 0); __builtin_amdgcn_s_setprio(0); } while (0)
; #define PG8_WAIT_V(n) asm volatile("s_waitcnt vmcnt(" #n ")" ::: "memory")
; #define PG8_WAIT_L(n) asm volatile("s_waitcnt lgkmcnt(" #n ")" ::: "memory")
; #define PG8_BAR __builtin_amdgcn_s_barrier()
; #define PG8_SCHED __builtin_amdgcn_sched_barrier(0)
; template <class Epi, class Sched, bool ALIGN_EPI = false, bool SP2 = false>
; __device__ __forceinline__ void gemm_phase(PG8_LAS unsigned char* lds, const Gemm g, const Sched& S, const Epi& E) {
;     ...
;             PG8_WAIT_V(8); PG8_WAIT_L(0); PG8_BAR; PG8_MMA(1, 0, At, B0); PG8_MMA(1, 1, At, B1); PG8_BAR; PG8_SCHED;
;             PG8_LDB(B0, 1, 0); PG8_LDB(B1, 1, 1); PG8_SCHED; PG8_LDA(At, 1, 0); PG8_STAGE(PG8_SA(0, 1), a2 + hstep, voffA);
;             PG8_WAIT_V(8); PG8_WAIT_L(0); PG8_BAR; PG8_MMA(0, 0, At, B0); PG8_MMA(0, 1, At, B1); PG8_BAR; PG8_SCHED;
.Lwj_6_1:
	s_waitcnt lgkmcnt(0)
	s_barrier
	s_setprio 1
	s_waitcnt lgkmcnt(0)
	v_mfma_f32_16x16x32_bf16 v[60:63], v[150:153], v[182:185], 0
	v_mfma_f32_16x16x32_bf16 v[56:59], v[158:161], v[182:185], 0
	v_mfma_f32_16x16x32_bf16 v[44:47], v[150:153], v[190:193], 0
	v_mfma_f32_16x16x32_bf16 v[40:43], v[158:161], v[190:193], 0
	v_mfma_f32_16x16x32_bf16 v[28:31], v[150:153], v[202:205], 0
	v_mfma_f32_16x16x32_bf16 v[24:27], v[158:161], v[202:205], 0
	v_mfma_f32_16x16x32_bf16 v[12:15], v[150:153], v[210:213], 0
	v_mfma_f32_16x16x32_bf16 v[8:11], v[158:161], v[210:213], 0
	v_mfma_f32_16x16x32_bf16 v[60:63], v[154:157], v[186:189], v[60:63]
	v_mfma_f32_16x16x32_bf16 v[56:59], v[162:165], v[186:189], v[56:59]
	v_mfma_f32_16x16x32_bf16 v[44:47], v[154:157], v[194:197], v[44:47]
	v_mfma_f32_16x16x32_bf16 v[40:43], v[162:165], v[194:197], v[40:43]
	v_mfma_f32_16x16x32_bf16 v[28:31], v[154:157], v[206:209], v[28:31]
	v_mfma_f32_16x16x32_bf16 v[24:27], v[162:165], v[206:209], v[24:27]
	v_mfma_f32_16x16x32_bf16 v[12:15], v[154:157], v[214:217], v[12:15]
	v_mfma_f32_16x16x32_bf16 v[8:11], v[162:165], v[214:217], v[8:11]
	s_setprio 0
	s_setprio 1
	v_mfma_f32_16x16x32_bf16 v[52:55], v[166:169], v[182:185], 0
	v_mfma_f32_16x16x32_bf16 v[48:51], v[174:177], v[182:185], 0
	v_mfma_f32_16x16x32_bf16 v[36:39], v[166:169], v[190:193], 0
	v_mfma_f32_16x16x32_bf16 v[32:35], v[174:177], v[190:193], 0
	v_mfma_f32_16x16x32_bf16 v[20:23], v[166:169], v[202:205], 0
	v_mfma_f32_16x16x32_bf16 v[16:19], v[174:177], v[202:205], 0
	v_mfma_f32_16x16x32_bf16 v[4:7], v[166:169], v[210:213], 0
	v_mfma_f32_16x16x32_bf16 v[0:3], v[174:177], v[210:213], 0
	v_mfma_f32_16x16x32_bf16 v[52:55], v[170:173], v[186:189], v[52:55]
	v_mfma_f32_16x16x32_bf16 v[48:51], v[178:181], v[186:189], v[48:51]
	v_mfma_f32_16x16x32_bf16 v[36:39], v[170:173], v[194:197], v[36:39]
	v_mfma_f32_16x16x32_bf16 v[32:35], v[178:181], v[194:197], v[32:35]
	v_mfma_f32_16x16x32_bf16 v[20:23], v[170:173], v[206:209], v[20:23]
	v_mfma_f32_16x16x32_bf16 v[16:19], v[178:181], v[206:209], v[16:19]
	v_mfma_f32_16x16x32_bf16 v[4:7], v[170:173], v[214:217], v[4:7]
	v_mfma_f32_16x16x32_bf16 v[0:3], v[178:181], v[214:217], v[0:3]
	s_setprio 0
	s_barrier
	s_add_i32 s53, 0, 0x18000
	s_add_i32 s54, 0, 0x1c000
	v_add_u32_e32 v162, s53, v146
	v_add_u32_e32 v178, s54, v146
	ds_read_b128 v[150:153], v162
	ds_read_b128 v[154:157], v162 offset:1024
	ds_read_b128 v[158:161], v162 offset:2048
	ds_read_b128 v[162:165], v162 offset:3072
	ds_read_b128 v[166:169], v178
	ds_read_b128 v[170:173], v178 offset:1024
	ds_read_b128 v[174:177], v178 offset:2048
	ds_read_b128 v[178:181], v178 offset:3072
	s_add_u32 s22, s22, s6
	s_addc_u32 s23, s23, s7
	s_mov_b32 m0, s33
	v_lshl_add_u64 v[228:229], s[22:23], 0, v[128:129]
	ds_read_b128 v[182:185], v149 offset:32768
	ds_read_b128 v[186:189], v149 offset:33792
	ds_read_b128 v[190:193], v149 offset:34816
	ds_read_b128 v[194:197], v149 offset:35840
	ds_read_b128 v[202:205], v149 offset:36864
	ds_read_b128 v[206:209], v149 offset:37888
	ds_read_b128 v[210:213], v149 offset:38912
	ds_read_b128 v[214:217], v149 offset:39936
	global_load_lds_dwordx4 v[228:229], off
	v_lshl_add_u64 v[228:229], s[22:23], 0, v[132:133]
	s_mov_b32 m0, s34
	s_nop 0
	global_load_lds_dwordx4 v[228:229], off
	s_waitcnt vmcnt(8)
	s_waitcnt lgkmcnt(0)
	s_barrier
	s_setprio 1
	s_waitcnt lgkmcnt(0)
	v_mfma_f32_16x16x32_bf16 v[120:123], v[150:153], v[182:185], v[120:123]
	v_mfma_f32_16x16x32_bf16 v[124:127], v[158:161], v[182:185], v[124:127]
	v_mfma_f32_16x16x32_bf16 v[108:111], v[150:153], v[190:193], v[108:111]
	v_mfma_f32_16x16x32_bf16 v[104:107], v[158:161], v[190:193], v[104:107]
	v_mfma_f32_16x16x32_bf16 v[92:95], v[150:153], v[202:205], v[92:95]
	v_mfma_f32_16x16x32_bf16 v[88:91], v[158:161], v[202:205], v[88:91]
	v_mfma_f32_16x16x32_bf16 v[76:79], v[150:153], v[210:213], v[76:79]
	v_mfma_f32_16x16x32_bf16 v[72:75], v[158:161], v[210:213], v[72:75]
	v_mfma_f32_16x16x32_bf16 v[120:123], v[154:157], v[186:189], v[120:123]
	v_mfma_f32_16x16x32_bf16 v[124:127], v[162:165], v[186:189], v[124:127]
	v_mfma_f32_16x16x32_bf16 v[108:111], v[154:157], v[194:197], v[108:111]
	v_mfma_f32_16x16x32_bf16 v[104:107], v[162:165], v[194:197], v[104:107]
	v_mfma_f32_16x16x32_bf16 v[92:95], v[154:157], v[206:209], v[92:95]
	v_mfma_f32_16x16x32_bf16 v[88:91], v[162:165], v[206:209], v[88:91]
	v_mfma_f32_16x16x32_bf16 v[76:79], v[154:157], v[214:217], v[76:79]
	v_mfma_f32_16x16x32_bf16 v[72:75], v[162:165], v[214:217], v[72:75]
	s_setprio 0
	s_setprio 1
	v_mfma_f32_16x16x32_bf16 v[116:119], v[166:169], v[182:185], v[116:119]
	v_mfma_f32_16x16x32_bf16 v[112:115], v[174:177], v[182:185], v[112:115]
	v_mfma_f32_16x16x32_bf16 v[100:103], v[166:169], v[190:193], v[100:103]
	v_mfma_f32_16x16x32_bf16 v[96:99], v[174:177], v[190:193], v[96:99]
	v_mfma_f32_16x16x32_bf16 v[84:87], v[166:169], v[202:205], v[84:87]
	v_mfma_f32_16x16x32_bf16 v[80:83], v[174:177], v[202:205], v[80:83]
	v_mfma_f32_16x16x32_bf16 v[68:71], v[166:169], v[210:213], v[68:71]
	v_mfma_f32_16x16x32_bf16 v[64:67], v[174:177], v[210:213], v[64:67]
	v_mfma_f32_16x16x32_bf16 v[116:119], v[170:173], v[186:189], v[116:119]
	v_mfma_f32_16x16x32_bf16 v[112:115], v[178:181], v[186:189], v[112:115]
	v_mfma_f32_16x16x32_bf16 v[100:103], v[170:173], v[194:197], v[100:103]
	v_mfma_f32_16x16x32_bf16 v[96:99], v[178:181], v[194:197], v[96:99]
	v_mfma_f32_16x16x32_bf16 v[84:87], v[170:173], v[206:209], v[84:87]
	v_mfma_f32_16x16x32_bf16 v[80:83], v[178:181], v[206:209], v[80:83]
	v_mfma_f32_16x16x32_bf16 v[68:71], v[170:173], v[214:217], v[68:71]
	v_mfma_f32_16x16x32_bf16 v[64:67], v[178:181], v[214:217], v[64:67]
	s_setprio 0
	s_barrier
; #define PG8_STAGE(bufoff, gbase, voff) do { _Pragma("unroll") for (int _i = 0; _i < 2; ++_i) \
;         __builtin_amdgcn_global_load_lds((const unsigned*)((const char*)(gbase) + (voff)[_i]), (PG8_LAS unsigned*)(lds + (bufoff) + ldsw + _i * 8192), 16, 0, 0); } while (0)
; #define PG8_LDA(dst, b, h) do { _Pragma("unroll") for (int m = 0; m < 4; ++m) _Pragma("unroll") for (int k = 0; k < 2; ++k) dst[m][k] = *(const PG8_LAS bf16x8*)(lds + PG8_SA(b, h) + aoff + m * 2048 + k * 1024); } while (0)
; #define PG8_MMA(ai, bj, At, Bt) do { __builtin_amdgcn_s_setprio(1); _Pragma("unroll") for (int m = 0; m < 4; ++m) _Pragma("unroll") for (int n = 0; n < 2; ++n) _Pragma("unroll") for (int k = 0; k < 2; ++k) \
;         acc[ai][bj][m][n] = __builtin_amdgcn_mfma_f32_16x16x32_bf16(Bt[n][k], At[m][k], acc[ai][bj][m][n], 0, 0, 0); __builtin_amdgcn_s_setprio(0); } while (0)
; #define PG8_WAIT_V(n) asm volatile("s_waitcnt vmcnt(" #n ")" ::: "memory")
; #define PG8_WAIT_L(n) asm volatile("s_waitcnt lgkmcnt(" #n ")" ::: "memory")
; #define PG8_BAR __builtin_amdgcn_s_barrier()
; #define PG8_SCHED __builtin_amdgcn_sched_barrier(0)
; template <class Epi, class Sched, bool ALIGN_EPI = false, bool SP2 = false>
; __device__ __forceinline__ void gemm_phase(PG8_LAS unsigned char* lds, const Gemm g, const Sched& S, const Epi& E) {
;     ...
;         for (int t = 0; t < nt; t += 2) {
;     ...
;             PG8_LDA(At, 1, 1); PG8_STAGE(PG8_SB(1, 0), b3, voffB); PG8_STAGE(PG8_SB(1, 1), b3 + hstep, voffB); PG8_STAGE(PG8_SA(1, 0), a3, voffA);
;             PG8_WAIT_V(8); PG8_WAIT_L(0); PG8_BAR; PG8_MMA(1, 0, At, B0); PG8_MMA(1, 1, At, B1); PG8_BAR; PG8_SCHED;
	s_add_i32 s22, s53, s29
	v_lshl_add_u64 v[198:199], v[198:199], 0, s[12:13]
	s_mov_b32 m0, s22
	ds_read_b128 v[182:185], v149 offset:49152
	ds_read_b128 v[186:189], v149 offset:50176
	ds_read_b128 v[190:193], v149 offset:51200
	ds_read_b128 v[194:197], v149 offset:52224
	ds_read_b128 v[202:205], v149 offset:53248
	ds_read_b128 v[206:209], v149 offset:54272
	ds_read_b128 v[210:213], v149 offset:55296
	ds_read_b128 v[214:217], v149 offset:56320
	global_load_lds_dwordx4 v[198:199], off
	v_lshl_add_u64 v[198:199], v[218:219], 0, s[12:13]
	s_add_i32 m0, s22, 0x2000
	s_add_i32 s22, s54, s29
	global_load_lds_dwordx4 v[198:199], off
	v_lshl_add_u64 v[198:199], v[220:221], 0, s[12:13]
	s_mov_b32 m0, s22
	s_nop 0
	global_load_lds_dwordx4 v[198:199], off
	v_lshl_add_u64 v[198:199], v[222:223], 0, s[12:13]
	s_add_i32 m0, s22, 0x2000
	s_nop 0
	global_load_lds_dwordx4 v[198:199], off
	v_lshl_add_u64 v[198:199], v[224:225], 0, s[12:13]
	s_mov_b32 m0, s36
	s_nop 0
	global_load_lds_dwordx4 v[198:199], off
	v_lshl_add_u64 v[198:199], v[226:227], 0, s[12:13]
	s_mov_b32 m0, s37
	s_nop 0
	global_load_lds_dwordx4 v[198:199], off
	s_waitcnt vmcnt(8)
	s_waitcnt lgkmcnt(0)
	s_barrier
	s_setprio 1
	s_waitcnt lgkmcnt(0)
	v_mfma_f32_16x16x32_bf16 v[60:63], v[150:153], v[182:185], v[60:63]
	v_mfma_f32_16x16x32_bf16 v[56:59], v[158:161], v[182:185], v[56:59]
	v_mfma_f32_16x16x32_bf16 v[44:47], v[150:153], v[190:193], v[44:47]
	v_mfma_f32_16x16x32_bf16 v[40:43], v[158:161], v[190:193], v[40:43]
	v_mfma_f32_16x16x32_bf16 v[28:31], v[150:153], v[202:205], v[28:31]
	v_mfma_f32_16x16x32_bf16 v[24:27], v[158:161], v[202:205], v[24:27]
	v_mfma_f32_16x16x32_bf16 v[12:15], v[150:153], v[210:213], v[12:15]
	v_mfma_f32_16x16x32_bf16 v[8:11], v[158:161], v[210:213], v[8:11]
	v_mfma_f32_16x16x32_bf16 v[60:63], v[154:157], v[186:189], v[60:63]
	v_mfma_f32_16x16x32_bf16 v[56:59], v[162:165], v[186:189], v[56:59]
	v_mfma_f32_16x16x32_bf16 v[44:47], v[154:157], v[194:197], v[44:47]
	v_mfma_f32_16x16x32_bf16 v[40:43], v[162:165], v[194:197], v[40:43]
	v_mfma_f32_16x16x32_bf16 v[28:31], v[154:157], v[206:209], v[28:31]
	v_mfma_f32_16x16x32_bf16 v[24:27], v[162:165], v[206:209], v[24:27]
	v_mfma_f32_16x16x32_bf16 v[12:15], v[154:157], v[214:217], v[12:15]
	v_mfma_f32_16x16x32_bf16 v[8:11], v[162:165], v[214:217], v[8:11]
	s_setprio 0
	s_setprio 1
	v_mfma_f32_16x16x32_bf16 v[52:55], v[166:169], v[182:185], v[52:55]
	v_mfma_f32_16x16x32_bf16 v[48:51], v[174:177], v[182:185], v[48:51]
	v_mfma_f32_16x16x32_bf16 v[36:39], v[166:169], v[190:193], v[36:39]
	v_mfma_f32_16x16x32_bf16 v[32:35], v[174:177], v[190:193], v[32:35]
	v_mfma_f32_16x16x32_bf16 v[20:23], v[166:169], v[202:205], v[20:23]
	v_mfma_f32_16x16x32_bf16 v[16:19], v[174:177], v[202:205], v[16:19]
	v_mfma_f32_16x16x32_bf16 v[4:7], v[166:169], v[210:213], v[4:7]
	v_mfma_f32_16x16x32_bf16 v[0:3], v[174:177], v[210:213], v[0:3]
	v_mfma_f32_16x16x32_bf16 v[52:55], v[170:173], v[186:189], v[52:55]
	v_mfma_f32_16x16x32_bf16 v[48:51], v[178:181], v[186:189], v[48:51]
	v_mfma_f32_16x16x32_bf16 v[36:39], v[170:173], v[194:197], v[36:39]
	v_mfma_f32_16x16x32_bf16 v[32:35], v[178:181], v[194:197], v[32:35]
	v_mfma_f32_16x16x32_bf16 v[20:23], v[170:173], v[206:209], v[20:23]
	v_mfma_f32_16x16x32_bf16 v[16:19], v[178:181], v[206:209], v[16:19]
	v_mfma_f32_16x16x32_bf16 v[4:7], v[170:173], v[214:217], v[4:7]
	v_mfma_f32_16x16x32_bf16 v[0:3], v[178:181], v[214:217], v[0:3]
	s_setprio 0
	s_barrier
	s_add_u32 s20, s20, 0x100
	s_addc_u32 s21, s21, 0
	s_add_u32 s50, s50, 0x100
	s_addc_u32 s51, s51, 0
	s_cmp_ge_i32 s52, s38
	s_mov_b32 s22, s52
	s_cbranch_scc1 .LBB0_1398

; __device__ __forceinline__ u32x4 pk8(f32x4 a, f32x4 b) { u32x4 w; w.x = pk2(a[0], a[1]); w.y = pk2(a[2], a[3]); w.z = pk2(b[0], b[1]); w.w = pk2(b[2], b[3]); return w; }
;     __device__ __forceinline__ void operator()(const AccT& acc, const Unit& u, int wr, int wc, int fr_, int fq_) const {
;         int fr = fr_, fq = fq_; asm volatile("" : "+v"(fr), "+v"(fq));
;         bf16_t* const O = (bf16_t*)(ws + WS_RB);
; #pragma unroll
;         for (int ai = 0; ai < 2; ++ai)
; #pragma unroll
;             for (int m = 0; m < 4; ++m) {
;                 const size_t row = (size_t)ROW_OF(ai, m);
; #pragma unroll
;                 for (int bj = 0; bj < 2; ++bj)
;                     st16c(O + row * 1024 + u.pn * 256 + bj * 128 + wc * 32 + 8 * fq, pk8(acc[ai][bj][m][0], acc[ai][bj][m][1]));
;             }
;     }
.LBB0_1400:
	s_mov_b32 s99, 1
	v_mov_b32_e32 v150, v144
	v_mov_b32_e32 v151, v145
	s_lshl_b32 s20, s46, 8
	s_add_i32 s20, s20, s39
	v_add_u32_e32 v150, s20, v150
	s_lshl_b32 s20, s49, 8
	s_ashr_i32 s21, s20, 31
	s_lshl_b64 s[20:21], s[20:21], 1
	s_add_u32 s20, s41, s20
	v_lshlrev_b32_e32 v152, 3, v151
	v_cvt_pk_bf16_f32 v116, v116, v117
	v_cvt_pk_bf16_f32 v117, v118, v119
	v_cvt_pk_bf16_f32 v118, v112, v113
	v_add_u32_e32 v112, 16, v150
	v_cvt_pk_bf16_f32 v100, v100, v101
	v_cvt_pk_bf16_f32 v101, v102, v103
	v_cvt_pk_bf16_f32 v102, v96, v97
	v_add_u32_e32 v96, 32, v150
	v_cvt_pk_bf16_f32 v84, v84, v85
	v_cvt_pk_bf16_f32 v85, v86, v87
	v_cvt_pk_bf16_f32 v86, v80, v81
	v_add_u32_e32 v80, 48, v150
	v_cvt_pk_bf16_f32 v68, v68, v69
	v_cvt_pk_bf16_f32 v69, v70, v71
	v_cvt_pk_bf16_f32 v70, v64, v65
	v_add_u32_e32 v64, 0x80, v150
	v_cvt_pk_bf16_f32 v52, v52, v53
	v_cvt_pk_bf16_f32 v53, v54, v55
	v_cvt_pk_bf16_f32 v54, v48, v49
	v_add_u32_e32 v48, 0x90, v150
	v_cvt_pk_bf16_f32 v36, v36, v37
	v_cvt_pk_bf16_f32 v37, v38, v39
	v_cvt_pk_bf16_f32 v38, v32, v33
	v_add_u32_e32 v32, 0xa0, v150
	v_cvt_pk_bf16_f32 v20, v20, v21
	v_cvt_pk_bf16_f32 v21, v22, v23
	v_cvt_pk_bf16_f32 v22, v16, v17
	v_add_u32_e32 v16, 0xb0, v150
	s_addc_u32 s21, s42, s21
	v_ashrrev_i32_e32 v153, 31, v152
	v_ashrrev_i32_e32 v151, 31, v150
	v_ashrrev_i32_e32 v113, 31, v112
	v_ashrrev_i32_e32 v97, 31, v96
	v_ashrrev_i32_e32 v81, 31, v80
	v_ashrrev_i32_e32 v65, 31, v64
	v_ashrrev_i32_e32 v49, 31, v48
	v_ashrrev_i32_e32 v33, 31, v32
	v_ashrrev_i32_e32 v17, 31, v16
	v_lshl_add_u64 v[152:153], v[152:153], 1, s[20:21]
	v_lshlrev_b64 v[154:155], 11, v[150:151]
	v_lshlrev_b64 v[112:113], 11, v[112:113]
	v_lshlrev_b64 v[96:97], 11, v[96:97]
	v_lshlrev_b64 v[80:81], 11, v[80:81]
	v_lshlrev_b64 v[64:65], 11, v[64:65]
	v_lshlrev_b64 v[48:49], 11, v[48:49]
	v_lshlrev_b64 v[32:33], 11, v[32:33]
	v_lshlrev_b64 v[16:17], 11, v[16:17]
	v_lshl_add_u64 v[154:155], v[152:153], 0, v[154:155]
	v_cvt_pk_bf16_f32 v120, v120, v121
	v_cvt_pk_bf16_f32 v121, v122, v123
	v_cvt_pk_bf16_f32 v122, v124, v125
	v_cvt_pk_bf16_f32 v123, v126, v127
	v_cvt_pk_bf16_f32 v119, v114, v115
	v_lshl_add_u64 v[112:113], v[152:153], 0, v[112:113]
	v_cvt_pk_bf16_f32 v108, v108, v109
	v_cvt_pk_bf16_f32 v109, v110, v111
	v_cvt_pk_bf16_f32 v110, v104, v105
	v_cvt_pk_bf16_f32 v111, v106, v107
	v_cvt_pk_bf16_f32 v103, v98, v99
	v_lshl_add_u64 v[96:97], v[152:153], 0, v[96:97]
	v_cvt_pk_bf16_f32 v92, v92, v93
	v_cvt_pk_bf16_f32 v93, v94, v95
	v_cvt_pk_bf16_f32 v94, v88, v89
	v_cvt_pk_bf16_f32 v95, v90, v91
	v_cvt_pk_bf16_f32 v87, v82, v83
	v_lshl_add_u64 v[80:81], v[152:153], 0, v[80:81]
	v_cvt_pk_bf16_f32 v76, v76, v77
	v_cvt_pk_bf16_f32 v77, v78, v79
	v_cvt_pk_bf16_f32 v78, v72, v73
	v_cvt_pk_bf16_f32 v79, v74, v75
	v_cvt_pk_bf16_f32 v71, v66, v67
	v_lshl_add_u64 v[64:65], v[152:153], 0, v[64:65]
	v_cvt_pk_bf16_f32 v60, v60, v61
	v_cvt_pk_bf16_f32 v61, v62, v63
	v_cvt_pk_bf16_f32 v62, v56, v57
	v_cvt_pk_bf16_f32 v63, v58, v59
	v_cvt_pk_bf16_f32 v55, v50, v51
	v_lshl_add_u64 v[48:49], v[152:153], 0, v[48:49]
	v_cvt_pk_bf16_f32 v44, v44, v45
	v_cvt_pk_bf16_f32 v45, v46, v47
	v_cvt_pk_bf16_f32 v46, v40, v41
	v_cvt_pk_bf16_f32 v47, v42, v43
	v_cvt_pk_bf16_f32 v39, v34, v35
	v_lshl_add_u64 v[32:33], v[152:153], 0, v[32:33]
	v_cvt_pk_bf16_f32 v28, v28, v29
	v_cvt_pk_bf16_f32 v29, v30, v31
	v_cvt_pk_bf16_f32 v30, v24, v25
	v_cvt_pk_bf16_f32 v31, v26, v27
	v_cvt_pk_bf16_f32 v23, v18, v19
	v_lshl_add_u64 v[16:17], v[152:153], 0, v[16:17]
	v_cvt_pk_bf16_f32 v12, v12, v13
	v_cvt_pk_bf16_f32 v13, v14, v15
	v_cvt_pk_bf16_f32 v14, v8, v9
	v_cvt_pk_bf16_f32 v15, v10, v11
	v_cvt_pk_bf16_f32 v4, v4, v5
	v_cvt_pk_bf16_f32 v5, v6, v7
	v_cvt_pk_bf16_f32 v6, v0, v1
	v_cvt_pk_bf16_f32 v7, v2, v3
	s_and_b64 vcc, exec, s[2:3]
	s_mov_b64 s[2:3], -1
	global_store_dwordx4 v[154:155], v[120:123], off
	global_store_dwordx4 v[154:155], v[116:119], off offset:256
	global_store_dwordx4 v[112:113], v[108:111], off
	global_store_dwordx4 v[112:113], v[100:103], off offset:256
	global_store_dwordx4 v[96:97], v[92:95], off
	global_store_dwordx4 v[96:97], v[84:87], off offset:256
	global_store_dwordx4 v[80:81], v[76:79], off
	global_store_dwordx4 v[80:81], v[68:71], off offset:256
	global_store_dwordx4 v[64:65], v[60:63], off
	global_store_dwordx4 v[64:65], v[52:55], off offset:256
	global_store_dwordx4 v[48:49], v[44:47], off
	global_store_dwordx4 v[48:49], v[36:39], off offset:256
	global_store_dwordx4 v[32:33], v[28:31], off
	global_store_dwordx4 v[32:33], v[20:23], off offset:256
	global_store_dwordx4 v[16:17], v[12:15], off
	global_store_dwordx4 v[16:17], v[4:7], off offset:256
	s_cbranch_vccnz .LBB0_1384
	s_andn2_b64 vcc, exec, s[10:11]
	s_cbranch_vccnz .LBB0_1383
	s_barrier
	s_branch .LBB0_1383

; __global__ void __launch_bounds__(512, 2) fwd_kernel(Args a) {
	.amdhsa_kernel _Z10fwd_kernel4Args
		.amdhsa_group_segment_fixed_size 0
		.amdhsa_private_segment_fixed_size 0
		.amdhsa_kernarg_size 408
		.amdhsa_user_sgpr_count 2
		.amdhsa_user_sgpr_dispatch_ptr 0
		.amdhsa_user_sgpr_queue_ptr 0
		.amdhsa_user_sgpr_kernarg_segment_ptr 1
		.amdhsa_user_sgpr_dispatch_id 0
		.amdhsa_user_sgpr_kernarg_preload_length 0
		.amdhsa_user_sgpr_kernarg_preload_offset 0
		.amdhsa_user_sgpr_private_segment_size 0
		.amdhsa_uses_dynamic_stack 0
		.amdhsa_enable_private_segment 0
		.amdhsa_system_sgpr_workgroup_id_x 1
		.amdhsa_system_sgpr_workgroup_id_y 0
		.amdhsa_system_sgpr_workgroup_id_z 0
		.amdhsa_system_sgpr_workgroup_info 0
		.amdhsa_system_vgpr_workitem_id 2
		.amdhsa_next_free_vgpr 256
		.amdhsa_next_free_sgpr 100
		.amdhsa_accum_offset 256
		.amdhsa_reserve_vcc 1
		.amdhsa_float_round_mode_32 0
		.amdhsa_float_round_mode_16_64 0
		.amdhsa_float_denorm_mode_32 3
		.amdhsa_float_denorm_mode_16_64 3
		.amdhsa_dx10_clamp 1
		.amdhsa_ieee_mode 1
		.amdhsa_fp16_overflow 0
		.amdhsa_tg_split 0
		.amdhsa_exception_fp_ieee_invalid_op 0
		.amdhsa_exception_fp_denorm_src 0
		.amdhsa_exception_fp_ieee_div_zero 0
		.amdhsa_exception_fp_ieee_overflow 0
		.amdhsa_exception_fp_ieee_underflow 0
		.amdhsa_exception_fp_ieee_inexact 0
		.amdhsa_exception_int_div_zero 0
	.end_amdhsa_kernel

; __global__ void __launch_bounds__(512, 2) fwd_kernel(Args a) {
.Lfunc_end0:
	.size	_Z10fwd_kernel4Args, .Lfunc_end0-_Z10fwd_kernel4Args
	.set _Z10fwd_kernel4Args.num_vgpr, 256
	.set _Z10fwd_kernel4Args.num_agpr, 0
	.set _Z10fwd_kernel4Args.numbered_sgpr, 100
	.set _Z10fwd_kernel4Args.num_named_barrier, 0
	.set _Z10fwd_kernel4Args.private_seg_size, 0
	.set _Z10fwd_kernel4Args.uses_vcc, 1
	.set _Z10fwd_kernel4Args.uses_flat_scratch, 0
	.set _Z10fwd_kernel4Args.has_dyn_sized_stack, 0
	.set _Z10fwd_kernel4Args.has_recursion, 0
	.set _Z10fwd_kernel4Args.has_indirect_call, 0

; __global__ void __launch_bounds__(512, 2) fwd_kernel(Args a) {
amdhsa.kernels:
  - .agpr_count:     0
    .args:
      - .offset:         0
        .size:           152
        .value_kind:     by_value
      - .offset:         152
        .size:           4
        .value_kind:     hidden_block_count_x
      - .offset:         156
        .size:           4
        .value_kind:     hidden_block_count_y
      - .offset:         160
        .size:           4
        .value_kind:     hidden_block_count_z
      - .offset:         164
        .size:           2
        .value_kind:     hidden_group_size_x
      - .offset:         166
        .size:           2
        .value_kind:     hidden_group_size_y
      - .offset:         168
        .size:           2
        .value_kind:     hidden_group_size_z
      - .offset:         170
        .size:           2
        .value_kind:     hidden_remainder_x
      - .offset:         172
        .size:           2
        .value_kind:     hidden_remainder_y
      - .offset:         174
        .size:           2
        .value_kind:     hidden_remainder_z
      - .offset:         192
        .size:           8
        .value_kind:     hidden_global_offset_x
      - .offset:         200
        .size:           8
        .value_kind:     hidden_global_offset_y
      - .offset:         208
        .size:           8
        .value_kind:     hidden_global_offset_z
      - .offset:         216
        .size:           2
        .value_kind:     hidden_grid_dims
      - .offset:         240
        .size:           8
        .value_kind:     hidden_multigrid_sync_arg
      - .offset:         272
        .size:           4
        .value_kind:     hidden_dynamic_lds_size
    .group_segment_fixed_size: 0
    .kernarg_segment_align: 8
    .kernarg_segment_size: 408
    .language:       OpenCL C
    .language_version:
      - 2
      - 0
    .max_flat_workgroup_size: 512
    .name:           _Z10fwd_kernel4Args
    .private_segment_fixed_size: 0
    .sgpr_count:     106
    .sgpr_spill_count: 83
    .symbol:         _Z10fwd_kernel4Args.kd
    .uniform_work_group_size: 1
    .uses_dynamic_stack: false
    .vgpr_count:     256
    .vgpr_spill_count: 0
    .wavefront_size: 64
